# hand-scheduled RWKV MODE-1 (U/P) 16-step chunk body in P6: LDS operand prefetch one step ahead, 4 interleaved dot chains, no hazard nops
# speedup vs baseline: 1.0227x; 1.0076x over previous
; #define LAS __attribute__((address_space(3)))
; template <int CTRL> __device__ __forceinline__ float dpp_f(float x) { return __builtin_bit_cast(float, __builtin_amdgcn_mov_dpp(__builtin_bit_cast(int, x), CTRL, 0xf, 0xf, true)); }
; __device__ __forceinline__ float red8(float d) { d += dpp_f<0xB1>(d); d += dpp_f<0x4E>(d); d += dpp_f<0x141>(d); return d; }
; __device__ __forceinline__ void upd8(V8& S, const V8& w, const V8& b, const V8& k, float sa, float vv) {
;     const f32x2 sa2 = {sa, sa}, vv2 = {vv, vv};
; #pragma unroll
;     for (int i = 0; i < 4; ++i) { f32x2 t = vv2 * k.p[i]; t = sa2 * b.p[i] + t; S.p[i] = S.p[i] * w.p[i] + t; }
; }
; __device__ __forceinline__ void updp8(V8& S, const V8& w, const V8& b, float sa) {
;     const f32x2 sa2 = {sa, sa};
; #pragma unroll
;     for (int i = 0; i < 4; ++i) { const f32x2 t = sa2 * b.p[i]; S.p[i] = S.p[i] * w.p[i] + t; }
; }
; template <int MODE>
; __device__ __forceinline__ void scan_pair(LAS unsigned char* lds, CArgsP a, const ScanUnit u, int nch) {
;     ...
;         for (int t = 0; t < 16; ++t) {
;             const LAS float* p = cb + t * 64 + 8 * ks;
;             const V8 w = ld8(p), kk = ld8(p + 1024), bb = ld8(p + 2048), kv = ld8(p + 3072);
;             const float va = cb[(5 * 16 + t) * 64 + vr0], vb = cb[(5 * 16 + t) * 64 + vr1];
;             float da = dot8(Sa, kk), db = dot8(Sb, kk);
;             da = red8(da); db = red8(db);
;             upd8(Sa, w, bb, kv, -da, va); upd8(Sb, w, bb, kv, -db, vb);
;             if (MODE == 1) {
;                 float pa = dot8(Pa, kk), pb = dot8(Pb, kk);
;                 pa = red8(pa); pb = red8(pb);
;                 updp8(Pa, w, bb, -pa); updp8(Pb, w, bb, -pb);
.LBB0_821:
	v_cndmask_b32_e64 v161, 0, 1, s[26:27]
	v_mul_lo_u32 v161, v161, s4
	v_add_u32_e32 v33, v93, v161
	v_add_u32_e32 v151, v92, v161
	ds_read_b128 v[224:227], v33 offset:0
	ds_read_b128 v[228:231], v33 offset:16
	ds_read_b128 v[232:235], v33 offset:4096
	ds_read_b128 v[236:239], v33 offset:4112
	ds_read_b128 v[240:243], v33 offset:8192
	ds_read_b128 v[244:247], v33 offset:8208
	ds_read_b128 v[166:169], v33 offset:12288
	ds_read_b128 v[170:173], v33 offset:12304
	ds_read2_b32 v[248:249], v151 offset0:0 offset1:8
	ds_read_b128 v[174:177], v33 offset:256
	ds_read_b128 v[178:181], v33 offset:272
	ds_read_b128 v[182:185], v33 offset:4352
	ds_read_b128 v[186:189], v33 offset:4368
	ds_read_b128 v[190:193], v33 offset:8448
	ds_read_b128 v[130:133], v33 offset:8464
	ds_read_b128 v[134:137], v33 offset:12544
	ds_read_b128 v[138:141], v33 offset:12560
	ds_read2_b32 v[142:143], v151 offset0:64 offset1:72
	s_waitcnt lgkmcnt(9)
	v_pk_mul_f32 v[112:113], v[28:29], v[232:233]
	v_pk_mul_f32 v[114:115], v[24:25], v[232:233]
	v_pk_mul_f32 v[116:117], v[16:17], v[232:233]
	v_pk_mul_f32 v[118:119], v[8:9], v[232:233]
	v_pk_fma_f32 v[112:113], v[30:31], v[234:235], v[112:113]
	v_pk_fma_f32 v[114:115], v[26:27], v[234:235], v[114:115]
	v_pk_fma_f32 v[116:117], v[18:19], v[234:235], v[116:117]
	v_pk_fma_f32 v[118:119], v[10:11], v[234:235], v[118:119]
	v_pk_fma_f32 v[112:113], v[20:21], v[236:237], v[112:113]
	v_pk_fma_f32 v[114:115], v[12:13], v[236:237], v[114:115]
	v_pk_fma_f32 v[116:117], v[4:5], v[236:237], v[116:117]
	v_pk_fma_f32 v[118:119], v[0:1], v[236:237], v[118:119]
	v_pk_fma_f32 v[112:113], v[22:23], v[238:239], v[112:113]
	v_pk_fma_f32 v[114:115], v[14:15], v[238:239], v[114:115]
	v_pk_fma_f32 v[116:117], v[6:7], v[238:239], v[116:117]
	v_pk_fma_f32 v[118:119], v[2:3], v[238:239], v[118:119]
	v_add_f32_e32 v112, v112, v113
	v_add_f32_e32 v114, v114, v115
	v_add_f32_e32 v116, v116, v117
	v_add_f32_e32 v118, v118, v119
	v_pk_mul_f32 v[252:253], v[166:167], v[248:249] op_sel_hi:[1,0]
	v_pk_mul_f32 v[254:255], v[166:167], v[248:249] op_sel:[0,1] op_sel_hi:[1,1]
	v_pk_mul_f32 v[194:195], v[168:169], v[248:249] op_sel_hi:[1,0]
	v_pk_mul_f32 v[162:163], v[168:169], v[248:249] op_sel:[0,1] op_sel_hi:[1,1]
	v_add_f32_dpp v112, v112, v112 quad_perm:[1,0,3,2] row_mask:0xf bank_mask:0xf bound_ctrl:1
	v_add_f32_dpp v114, v114, v114 quad_perm:[1,0,3,2] row_mask:0xf bank_mask:0xf bound_ctrl:1
	v_add_f32_dpp v116, v116, v116 quad_perm:[1,0,3,2] row_mask:0xf bank_mask:0xf bound_ctrl:1
	v_add_f32_dpp v118, v118, v118 quad_perm:[1,0,3,2] row_mask:0xf bank_mask:0xf bound_ctrl:1
	v_pk_fma_f32 v[28:29], v[28:29], v[224:225], v[252:253]
	v_pk_fma_f32 v[24:25], v[24:25], v[224:225], v[254:255]
	v_pk_fma_f32 v[30:31], v[30:31], v[226:227], v[194:195]
	v_pk_fma_f32 v[26:27], v[26:27], v[226:227], v[162:163]
	v_add_f32_dpp v112, v112, v112 quad_perm:[2,3,0,1] row_mask:0xf bank_mask:0xf bound_ctrl:1
	v_add_f32_dpp v114, v114, v114 quad_perm:[2,3,0,1] row_mask:0xf bank_mask:0xf bound_ctrl:1
	v_add_f32_dpp v116, v116, v116 quad_perm:[2,3,0,1] row_mask:0xf bank_mask:0xf bound_ctrl:1
	v_add_f32_dpp v118, v118, v118 quad_perm:[2,3,0,1] row_mask:0xf bank_mask:0xf bound_ctrl:1
	v_pk_mul_f32 v[252:253], v[170:171], v[248:249] op_sel_hi:[1,0]
	v_pk_mul_f32 v[254:255], v[170:171], v[248:249] op_sel:[0,1] op_sel_hi:[1,1]
	v_pk_mul_f32 v[194:195], v[172:173], v[248:249] op_sel_hi:[1,0]
	v_pk_mul_f32 v[162:163], v[172:173], v[248:249] op_sel:[0,1] op_sel_hi:[1,1]
	v_add_f32_dpp v112, v112, v112 row_half_mirror row_mask:0xf bank_mask:0xf bound_ctrl:1
	v_add_f32_dpp v114, v114, v114 row_half_mirror row_mask:0xf bank_mask:0xf bound_ctrl:1
	v_add_f32_dpp v116, v116, v116 row_half_mirror row_mask:0xf bank_mask:0xf bound_ctrl:1
	v_add_f32_dpp v118, v118, v118 row_half_mirror row_mask:0xf bank_mask:0xf bound_ctrl:1
	v_pk_fma_f32 v[20:21], v[20:21], v[228:229], v[252:253]
	v_pk_fma_f32 v[12:13], v[12:13], v[228:229], v[254:255]
	v_pk_fma_f32 v[22:23], v[22:23], v[230:231], v[194:195]
	v_pk_fma_f32 v[14:15], v[14:15], v[230:231], v[162:163]
	v_pk_mul_f32 v[16:17], v[16:17], v[224:225]
	v_pk_mul_f32 v[8:9], v[8:9], v[224:225]
	v_pk_mul_f32 v[18:19], v[18:19], v[226:227]
	v_pk_mul_f32 v[10:11], v[10:11], v[226:227]
	v_pk_mul_f32 v[4:5], v[4:5], v[228:229]
	v_pk_mul_f32 v[0:1], v[0:1], v[228:229]
	v_pk_mul_f32 v[6:7], v[6:7], v[230:231]
	v_pk_mul_f32 v[2:3], v[2:3], v[230:231]
	v_pk_fma_f32 v[28:29], v[240:241], v[112:113], v[28:29] op_sel_hi:[1,0,1] neg_lo:[0,1,0] neg_hi:[0,1,0]
	v_pk_fma_f32 v[24:25], v[240:241], v[114:115], v[24:25] op_sel_hi:[1,0,1] neg_lo:[0,1,0] neg_hi:[0,1,0]
	v_pk_fma_f32 v[30:31], v[242:243], v[112:113], v[30:31] op_sel_hi:[1,0,1] neg_lo:[0,1,0] neg_hi:[0,1,0]
	v_pk_fma_f32 v[26:27], v[242:243], v[114:115], v[26:27] op_sel_hi:[1,0,1] neg_lo:[0,1,0] neg_hi:[0,1,0]
	v_pk_fma_f32 v[20:21], v[244:245], v[112:113], v[20:21] op_sel_hi:[1,0,1] neg_lo:[0,1,0] neg_hi:[0,1,0]
	v_pk_fma_f32 v[12:13], v[244:245], v[114:115], v[12:13] op_sel_hi:[1,0,1] neg_lo:[0,1,0] neg_hi:[0,1,0]
	v_pk_fma_f32 v[22:23], v[246:247], v[112:113], v[22:23] op_sel_hi:[1,0,1] neg_lo:[0,1,0] neg_hi:[0,1,0]
	v_pk_fma_f32 v[14:15], v[246:247], v[114:115], v[14:15] op_sel_hi:[1,0,1] neg_lo:[0,1,0] neg_hi:[0,1,0]
	v_pk_fma_f32 v[16:17], v[240:241], v[116:117], v[16:17] op_sel_hi:[1,0,1] neg_lo:[0,1,0] neg_hi:[0,1,0]
	v_pk_fma_f32 v[8:9], v[240:241], v[118:119], v[8:9] op_sel_hi:[1,0,1] neg_lo:[0,1,0] neg_hi:[0,1,0]
	v_pk_fma_f32 v[18:19], v[242:243], v[116:117], v[18:19] op_sel_hi:[1,0,1] neg_lo:[0,1,0] neg_hi:[0,1,0]
	v_pk_fma_f32 v[10:11], v[242:243], v[118:119], v[10:11] op_sel_hi:[1,0,1] neg_lo:[0,1,0] neg_hi:[0,1,0]
	v_pk_fma_f32 v[4:5], v[244:245], v[116:117], v[4:5] op_sel_hi:[1,0,1] neg_lo:[0,1,0] neg_hi:[0,1,0]
	v_pk_fma_f32 v[0:1], v[244:245], v[118:119], v[0:1] op_sel_hi:[1,0,1] neg_lo:[0,1,0] neg_hi:[0,1,0]
	v_pk_fma_f32 v[6:7], v[246:247], v[116:117], v[6:7] op_sel_hi:[1,0,1] neg_lo:[0,1,0] neg_hi:[0,1,0]
	v_pk_fma_f32 v[2:3], v[246:247], v[118:119], v[2:3] op_sel_hi:[1,0,1] neg_lo:[0,1,0] neg_hi:[0,1,0]
	ds_read_b128 v[224:227], v33 offset:512
	ds_read_b128 v[228:231], v33 offset:528
	ds_read_b128 v[232:235], v33 offset:4608
	ds_read_b128 v[236:239], v33 offset:4624
	ds_read_b128 v[240:243], v33 offset:8704
	ds_read_b128 v[244:247], v33 offset:8720
	ds_read_b128 v[166:169], v33 offset:12800
	ds_read_b128 v[170:173], v33 offset:12816
	ds_read2_b32 v[248:249], v151 offset0:128 offset1:136
	s_waitcnt lgkmcnt(9)
; #define LAS __attribute__((address_space(3)))
; template <int CTRL> __device__ __forceinline__ float dpp_f(float x) { return __builtin_bit_cast(float, __builtin_amdgcn_mov_dpp(__builtin_bit_cast(int, x), CTRL, 0xf, 0xf, true)); }
; __device__ __forceinline__ float red8(float d) { d += dpp_f<0xB1>(d); d += dpp_f<0x4E>(d); d += dpp_f<0x141>(d); return d; }
; __device__ __forceinline__ void upd8(V8& S, const V8& w, const V8& b, const V8& k, float sa, float vv) {
;     const f32x2 sa2 = {sa, sa}, vv2 = {vv, vv};
; #pragma unroll
;     for (int i = 0; i < 4; ++i) { f32x2 t = vv2 * k.p[i]; t = sa2 * b.p[i] + t; S.p[i] = S.p[i] * w.p[i] + t; }
; }
; __device__ __forceinline__ void updp8(V8& S, const V8& w, const V8& b, float sa) {
;     const f32x2 sa2 = {sa, sa};
; #pragma unroll
;     for (int i = 0; i < 4; ++i) { const f32x2 t = sa2 * b.p[i]; S.p[i] = S.p[i] * w.p[i] + t; }
; }
; template <int MODE>
; __device__ __forceinline__ void scan_pair(LAS unsigned char* lds, CArgsP a, const ScanUnit u, int nch) {
;     ...
;         for (int t = 0; t < 16; ++t) {
;             const LAS float* p = cb + t * 64 + 8 * ks;
;             const V8 w = ld8(p), kk = ld8(p + 1024), bb = ld8(p + 2048), kv = ld8(p + 3072);
;             const float va = cb[(5 * 16 + t) * 64 + vr0], vb = cb[(5 * 16 + t) * 64 + vr1];
;             float da = dot8(Sa, kk), db = dot8(Sb, kk);
;             da = red8(da); db = red8(db);
;             upd8(Sa, w, bb, kv, -da, va); upd8(Sb, w, bb, kv, -db, vb);
;             if (MODE == 1) {
;                 float pa = dot8(Pa, kk), pb = dot8(Pb, kk);
;                 pa = red8(pa); pb = red8(pb);
;                 updp8(Pa, w, bb, -pa); updp8(Pb, w, bb, -pb);
	v_pk_mul_f32 v[112:113], v[28:29], v[182:183]
	v_pk_mul_f32 v[114:115], v[24:25], v[182:183]
	v_pk_mul_f32 v[116:117], v[16:17], v[182:183]
	v_pk_mul_f32 v[118:119], v[8:9], v[182:183]
	v_pk_fma_f32 v[112:113], v[30:31], v[184:185], v[112:113]
	v_pk_fma_f32 v[114:115], v[26:27], v[184:185], v[114:115]
	v_pk_fma_f32 v[116:117], v[18:19], v[184:185], v[116:117]
	v_pk_fma_f32 v[118:119], v[10:11], v[184:185], v[118:119]
	v_pk_fma_f32 v[112:113], v[20:21], v[186:187], v[112:113]
	v_pk_fma_f32 v[114:115], v[12:13], v[186:187], v[114:115]
	v_pk_fma_f32 v[116:117], v[4:5], v[186:187], v[116:117]
	v_pk_fma_f32 v[118:119], v[0:1], v[186:187], v[118:119]
	v_pk_fma_f32 v[112:113], v[22:23], v[188:189], v[112:113]
	v_pk_fma_f32 v[114:115], v[14:15], v[188:189], v[114:115]
	v_pk_fma_f32 v[116:117], v[6:7], v[188:189], v[116:117]
	v_pk_fma_f32 v[118:119], v[2:3], v[188:189], v[118:119]
	v_add_f32_e32 v112, v112, v113
	v_add_f32_e32 v114, v114, v115
	v_add_f32_e32 v116, v116, v117
	v_add_f32_e32 v118, v118, v119
	v_pk_mul_f32 v[252:253], v[134:135], v[142:143] op_sel_hi:[1,0]
	v_pk_mul_f32 v[254:255], v[134:135], v[142:143] op_sel:[0,1] op_sel_hi:[1,1]
	v_pk_mul_f32 v[194:195], v[136:137], v[142:143] op_sel_hi:[1,0]
	v_pk_mul_f32 v[162:163], v[136:137], v[142:143] op_sel:[0,1] op_sel_hi:[1,1]
	v_add_f32_dpp v112, v112, v112 quad_perm:[1,0,3,2] row_mask:0xf bank_mask:0xf bound_ctrl:1
	v_add_f32_dpp v114, v114, v114 quad_perm:[1,0,3,2] row_mask:0xf bank_mask:0xf bound_ctrl:1
	v_add_f32_dpp v116, v116, v116 quad_perm:[1,0,3,2] row_mask:0xf bank_mask:0xf bound_ctrl:1
	v_add_f32_dpp v118, v118, v118 quad_perm:[1,0,3,2] row_mask:0xf bank_mask:0xf bound_ctrl:1
	v_pk_fma_f32 v[28:29], v[28:29], v[174:175], v[252:253]
	v_pk_fma_f32 v[24:25], v[24:25], v[174:175], v[254:255]
	v_pk_fma_f32 v[30:31], v[30:31], v[176:177], v[194:195]
	v_pk_fma_f32 v[26:27], v[26:27], v[176:177], v[162:163]
	v_add_f32_dpp v112, v112, v112 quad_perm:[2,3,0,1] row_mask:0xf bank_mask:0xf bound_ctrl:1
	v_add_f32_dpp v114, v114, v114 quad_perm:[2,3,0,1] row_mask:0xf bank_mask:0xf bound_ctrl:1
	v_add_f32_dpp v116, v116, v116 quad_perm:[2,3,0,1] row_mask:0xf bank_mask:0xf bound_ctrl:1
	v_add_f32_dpp v118, v118, v118 quad_perm:[2,3,0,1] row_mask:0xf bank_mask:0xf bound_ctrl:1
	v_pk_mul_f32 v[252:253], v[138:139], v[142:143] op_sel_hi:[1,0]
	v_pk_mul_f32 v[254:255], v[138:139], v[142:143] op_sel:[0,1] op_sel_hi:[1,1]
	v_pk_mul_f32 v[194:195], v[140:141], v[142:143] op_sel_hi:[1,0]
	v_pk_mul_f32 v[162:163], v[140:141], v[142:143] op_sel:[0,1] op_sel_hi:[1,1]
	v_add_f32_dpp v112, v112, v112 row_half_mirror row_mask:0xf bank_mask:0xf bound_ctrl:1
	v_add_f32_dpp v114, v114, v114 row_half_mirror row_mask:0xf bank_mask:0xf bound_ctrl:1
	v_add_f32_dpp v116, v116, v116 row_half_mirror row_mask:0xf bank_mask:0xf bound_ctrl:1
	v_add_f32_dpp v118, v118, v118 row_half_mirror row_mask:0xf bank_mask:0xf bound_ctrl:1
	v_pk_fma_f32 v[20:21], v[20:21], v[178:179], v[252:253]
	v_pk_fma_f32 v[12:13], v[12:13], v[178:179], v[254:255]
	v_pk_fma_f32 v[22:23], v[22:23], v[180:181], v[194:195]
	v_pk_fma_f32 v[14:15], v[14:15], v[180:181], v[162:163]
	v_pk_mul_f32 v[16:17], v[16:17], v[174:175]
	v_pk_mul_f32 v[8:9], v[8:9], v[174:175]
	v_pk_mul_f32 v[18:19], v[18:19], v[176:177]
	v_pk_mul_f32 v[10:11], v[10:11], v[176:177]
	v_pk_mul_f32 v[4:5], v[4:5], v[178:179]
	v_pk_mul_f32 v[0:1], v[0:1], v[178:179]
	v_pk_mul_f32 v[6:7], v[6:7], v[180:181]
	v_pk_mul_f32 v[2:3], v[2:3], v[180:181]
	v_pk_fma_f32 v[28:29], v[190:191], v[112:113], v[28:29] op_sel_hi:[1,0,1] neg_lo:[0,1,0] neg_hi:[0,1,0]
	v_pk_fma_f32 v[24:25], v[190:191], v[114:115], v[24:25] op_sel_hi:[1,0,1] neg_lo:[0,1,0] neg_hi:[0,1,0]
	v_pk_fma_f32 v[30:31], v[192:193], v[112:113], v[30:31] op_sel_hi:[1,0,1] neg_lo:[0,1,0] neg_hi:[0,1,0]
	v_pk_fma_f32 v[26:27], v[192:193], v[114:115], v[26:27] op_sel_hi:[1,0,1] neg_lo:[0,1,0] neg_hi:[0,1,0]
	v_pk_fma_f32 v[20:21], v[130:131], v[112:113], v[20:21] op_sel_hi:[1,0,1] neg_lo:[0,1,0] neg_hi:[0,1,0]
	v_pk_fma_f32 v[12:13], v[130:131], v[114:115], v[12:13] op_sel_hi:[1,0,1] neg_lo:[0,1,0] neg_hi:[0,1,0]
	v_pk_fma_f32 v[22:23], v[132:133], v[112:113], v[22:23] op_sel_hi:[1,0,1] neg_lo:[0,1,0] neg_hi:[0,1,0]
	v_pk_fma_f32 v[14:15], v[132:133], v[114:115], v[14:15] op_sel_hi:[1,0,1] neg_lo:[0,1,0] neg_hi:[0,1,0]
	v_pk_fma_f32 v[16:17], v[190:191], v[116:117], v[16:17] op_sel_hi:[1,0,1] neg_lo:[0,1,0] neg_hi:[0,1,0]
	v_pk_fma_f32 v[8:9], v[190:191], v[118:119], v[8:9] op_sel_hi:[1,0,1] neg_lo:[0,1,0] neg_hi:[0,1,0]
	v_pk_fma_f32 v[18:19], v[192:193], v[116:117], v[18:19] op_sel_hi:[1,0,1] neg_lo:[0,1,0] neg_hi:[0,1,0]
	v_pk_fma_f32 v[10:11], v[192:193], v[118:119], v[10:11] op_sel_hi:[1,0,1] neg_lo:[0,1,0] neg_hi:[0,1,0]
	v_pk_fma_f32 v[4:5], v[130:131], v[116:117], v[4:5] op_sel_hi:[1,0,1] neg_lo:[0,1,0] neg_hi:[0,1,0]
	v_pk_fma_f32 v[0:1], v[130:131], v[118:119], v[0:1] op_sel_hi:[1,0,1] neg_lo:[0,1,0] neg_hi:[0,1,0]
	v_pk_fma_f32 v[6:7], v[132:133], v[116:117], v[6:7] op_sel_hi:[1,0,1] neg_lo:[0,1,0] neg_hi:[0,1,0]
	v_pk_fma_f32 v[2:3], v[132:133], v[118:119], v[2:3] op_sel_hi:[1,0,1] neg_lo:[0,1,0] neg_hi:[0,1,0]
	ds_read_b128 v[174:177], v33 offset:768
	ds_read_b128 v[178:181], v33 offset:784
	ds_read_b128 v[182:185], v33 offset:4864
	ds_read_b128 v[186:189], v33 offset:4880
	ds_read_b128 v[190:193], v33 offset:8960
	ds_read_b128 v[130:133], v33 offset:8976
	ds_read_b128 v[134:137], v33 offset:13056
	ds_read_b128 v[138:141], v33 offset:13072
	ds_read2_b32 v[142:143], v151 offset0:192 offset1:200
	s_waitcnt lgkmcnt(9)
; #define LAS __attribute__((address_space(3)))
; template <int CTRL> __device__ __forceinline__ float dpp_f(float x) { return __builtin_bit_cast(float, __builtin_amdgcn_mov_dpp(__builtin_bit_cast(int, x), CTRL, 0xf, 0xf, true)); }
; __device__ __forceinline__ float red8(float d) { d += dpp_f<0xB1>(d); d += dpp_f<0x4E>(d); d += dpp_f<0x141>(d); return d; }
; __device__ __forceinline__ void upd8(V8& S, const V8& w, const V8& b, const V8& k, float sa, float vv) {
;     const f32x2 sa2 = {sa, sa}, vv2 = {vv, vv};
; #pragma unroll
;     for (int i = 0; i < 4; ++i) { f32x2 t = vv2 * k.p[i]; t = sa2 * b.p[i] + t; S.p[i] = S.p[i] * w.p[i] + t; }
; }
; __device__ __forceinline__ void updp8(V8& S, const V8& w, const V8& b, float sa) {
;     const f32x2 sa2 = {sa, sa};
; #pragma unroll
;     for (int i = 0; i < 4; ++i) { const f32x2 t = sa2 * b.p[i]; S.p[i] = S.p[i] * w.p[i] + t; }
; }
; template <int MODE>
; __device__ __forceinline__ void scan_pair(LAS unsigned char* lds, CArgsP a, const ScanUnit u, int nch) {
;     ...
;         for (int t = 0; t < 16; ++t) {
;             const LAS float* p = cb + t * 64 + 8 * ks;
;             const V8 w = ld8(p), kk = ld8(p + 1024), bb = ld8(p + 2048), kv = ld8(p + 3072);
;             const float va = cb[(5 * 16 + t) * 64 + vr0], vb = cb[(5 * 16 + t) * 64 + vr1];
;             float da = dot8(Sa, kk), db = dot8(Sb, kk);
;             da = red8(da); db = red8(db);
;             upd8(Sa, w, bb, kv, -da, va); upd8(Sb, w, bb, kv, -db, vb);
;             if (MODE == 1) {
;                 float pa = dot8(Pa, kk), pb = dot8(Pb, kk);
;                 pa = red8(pa); pb = red8(pb);
;                 updp8(Pa, w, bb, -pa); updp8(Pb, w, bb, -pb);
	v_pk_mul_f32 v[112:113], v[28:29], v[232:233]
	v_pk_mul_f32 v[114:115], v[24:25], v[232:233]
	v_pk_mul_f32 v[116:117], v[16:17], v[232:233]
	v_pk_mul_f32 v[118:119], v[8:9], v[232:233]
	v_pk_fma_f32 v[112:113], v[30:31], v[234:235], v[112:113]
	v_pk_fma_f32 v[114:115], v[26:27], v[234:235], v[114:115]
	v_pk_fma_f32 v[116:117], v[18:19], v[234:235], v[116:117]
	v_pk_fma_f32 v[118:119], v[10:11], v[234:235], v[118:119]
	v_pk_fma_f32 v[112:113], v[20:21], v[236:237], v[112:113]
	v_pk_fma_f32 v[114:115], v[12:13], v[236:237], v[114:115]
	v_pk_fma_f32 v[116:117], v[4:5], v[236:237], v[116:117]
	v_pk_fma_f32 v[118:119], v[0:1], v[236:237], v[118:119]
	v_pk_fma_f32 v[112:113], v[22:23], v[238:239], v[112:113]
	v_pk_fma_f32 v[114:115], v[14:15], v[238:239], v[114:115]
	v_pk_fma_f32 v[116:117], v[6:7], v[238:239], v[116:117]
	v_pk_fma_f32 v[118:119], v[2:3], v[238:239], v[118:119]
	v_add_f32_e32 v112, v112, v113
	v_add_f32_e32 v114, v114, v115
	v_add_f32_e32 v116, v116, v117
	v_add_f32_e32 v118, v118, v119
	v_pk_mul_f32 v[252:253], v[166:167], v[248:249] op_sel_hi:[1,0]
	v_pk_mul_f32 v[254:255], v[166:167], v[248:249] op_sel:[0,1] op_sel_hi:[1,1]
	v_pk_mul_f32 v[194:195], v[168:169], v[248:249] op_sel_hi:[1,0]
	v_pk_mul_f32 v[162:163], v[168:169], v[248:249] op_sel:[0,1] op_sel_hi:[1,1]
	v_add_f32_dpp v112, v112, v112 quad_perm:[1,0,3,2] row_mask:0xf bank_mask:0xf bound_ctrl:1
	v_add_f32_dpp v114, v114, v114 quad_perm:[1,0,3,2] row_mask:0xf bank_mask:0xf bound_ctrl:1
	v_add_f32_dpp v116, v116, v116 quad_perm:[1,0,3,2] row_mask:0xf bank_mask:0xf bound_ctrl:1
	v_add_f32_dpp v118, v118, v118 quad_perm:[1,0,3,2] row_mask:0xf bank_mask:0xf bound_ctrl:1
	v_pk_fma_f32 v[28:29], v[28:29], v[224:225], v[252:253]
	v_pk_fma_f32 v[24:25], v[24:25], v[224:225], v[254:255]
	v_pk_fma_f32 v[30:31], v[30:31], v[226:227], v[194:195]
	v_pk_fma_f32 v[26:27], v[26:27], v[226:227], v[162:163]
	v_add_f32_dpp v112, v112, v112 quad_perm:[2,3,0,1] row_mask:0xf bank_mask:0xf bound_ctrl:1
	v_add_f32_dpp v114, v114, v114 quad_perm:[2,3,0,1] row_mask:0xf bank_mask:0xf bound_ctrl:1
	v_add_f32_dpp v116, v116, v116 quad_perm:[2,3,0,1] row_mask:0xf bank_mask:0xf bound_ctrl:1
	v_add_f32_dpp v118, v118, v118 quad_perm:[2,3,0,1] row_mask:0xf bank_mask:0xf bound_ctrl:1
	v_pk_mul_f32 v[252:253], v[170:171], v[248:249] op_sel_hi:[1,0]
	v_pk_mul_f32 v[254:255], v[170:171], v[248:249] op_sel:[0,1] op_sel_hi:[1,1]
	v_pk_mul_f32 v[194:195], v[172:173], v[248:249] op_sel_hi:[1,0]
	v_pk_mul_f32 v[162:163], v[172:173], v[248:249] op_sel:[0,1] op_sel_hi:[1,1]
	v_add_f32_dpp v112, v112, v112 row_half_mirror row_mask:0xf bank_mask:0xf bound_ctrl:1
	v_add_f32_dpp v114, v114, v114 row_half_mirror row_mask:0xf bank_mask:0xf bound_ctrl:1
	v_add_f32_dpp v116, v116, v116 row_half_mirror row_mask:0xf bank_mask:0xf bound_ctrl:1
	v_add_f32_dpp v118, v118, v118 row_half_mirror row_mask:0xf bank_mask:0xf bound_ctrl:1
	v_pk_fma_f32 v[20:21], v[20:21], v[228:229], v[252:253]
	v_pk_fma_f32 v[12:13], v[12:13], v[228:229], v[254:255]
	v_pk_fma_f32 v[22:23], v[22:23], v[230:231], v[194:195]
	v_pk_fma_f32 v[14:15], v[14:15], v[230:231], v[162:163]
	v_pk_mul_f32 v[16:17], v[16:17], v[224:225]
	v_pk_mul_f32 v[8:9], v[8:9], v[224:225]
	v_pk_mul_f32 v[18:19], v[18:19], v[226:227]
	v_pk_mul_f32 v[10:11], v[10:11], v[226:227]
	v_pk_mul_f32 v[4:5], v[4:5], v[228:229]
	v_pk_mul_f32 v[0:1], v[0:1], v[228:229]
	v_pk_mul_f32 v[6:7], v[6:7], v[230:231]
	v_pk_mul_f32 v[2:3], v[2:3], v[230:231]
	v_pk_fma_f32 v[28:29], v[240:241], v[112:113], v[28:29] op_sel_hi:[1,0,1] neg_lo:[0,1,0] neg_hi:[0,1,0]
	v_pk_fma_f32 v[24:25], v[240:241], v[114:115], v[24:25] op_sel_hi:[1,0,1] neg_lo:[0,1,0] neg_hi:[0,1,0]
	v_pk_fma_f32 v[30:31], v[242:243], v[112:113], v[30:31] op_sel_hi:[1,0,1] neg_lo:[0,1,0] neg_hi:[0,1,0]
	v_pk_fma_f32 v[26:27], v[242:243], v[114:115], v[26:27] op_sel_hi:[1,0,1] neg_lo:[0,1,0] neg_hi:[0,1,0]
	v_pk_fma_f32 v[20:21], v[244:245], v[112:113], v[20:21] op_sel_hi:[1,0,1] neg_lo:[0,1,0] neg_hi:[0,1,0]
	v_pk_fma_f32 v[12:13], v[244:245], v[114:115], v[12:13] op_sel_hi:[1,0,1] neg_lo:[0,1,0] neg_hi:[0,1,0]
	v_pk_fma_f32 v[22:23], v[246:247], v[112:113], v[22:23] op_sel_hi:[1,0,1] neg_lo:[0,1,0] neg_hi:[0,1,0]
	v_pk_fma_f32 v[14:15], v[246:247], v[114:115], v[14:15] op_sel_hi:[1,0,1] neg_lo:[0,1,0] neg_hi:[0,1,0]
	v_pk_fma_f32 v[16:17], v[240:241], v[116:117], v[16:17] op_sel_hi:[1,0,1] neg_lo:[0,1,0] neg_hi:[0,1,0]
	v_pk_fma_f32 v[8:9], v[240:241], v[118:119], v[8:9] op_sel_hi:[1,0,1] neg_lo:[0,1,0] neg_hi:[0,1,0]
	v_pk_fma_f32 v[18:19], v[242:243], v[116:117], v[18:19] op_sel_hi:[1,0,1] neg_lo:[0,1,0] neg_hi:[0,1,0]
	v_pk_fma_f32 v[10:11], v[242:243], v[118:119], v[10:11] op_sel_hi:[1,0,1] neg_lo:[0,1,0] neg_hi:[0,1,0]
	v_pk_fma_f32 v[4:5], v[244:245], v[116:117], v[4:5] op_sel_hi:[1,0,1] neg_lo:[0,1,0] neg_hi:[0,1,0]
	v_pk_fma_f32 v[0:1], v[244:245], v[118:119], v[0:1] op_sel_hi:[1,0,1] neg_lo:[0,1,0] neg_hi:[0,1,0]
	v_pk_fma_f32 v[6:7], v[246:247], v[116:117], v[6:7] op_sel_hi:[1,0,1] neg_lo:[0,1,0] neg_hi:[0,1,0]
	v_pk_fma_f32 v[2:3], v[246:247], v[118:119], v[2:3] op_sel_hi:[1,0,1] neg_lo:[0,1,0] neg_hi:[0,1,0]
	ds_read_b128 v[224:227], v33 offset:1024
	ds_read_b128 v[228:231], v33 offset:1040
	ds_read_b128 v[232:235], v33 offset:5120
	ds_read_b128 v[236:239], v33 offset:5136
	ds_read_b128 v[240:243], v33 offset:9216
	ds_read_b128 v[244:247], v33 offset:9232
	ds_read_b128 v[166:169], v33 offset:13312
	ds_read_b128 v[170:173], v33 offset:13328
	v_add_u32_e32 v151, 0x400, v151
	ds_read2_b32 v[248:249], v151 offset0:0 offset1:8
	s_waitcnt lgkmcnt(9)
; #define LAS __attribute__((address_space(3)))
; template <int CTRL> __device__ __forceinline__ float dpp_f(float x) { return __builtin_bit_cast(float, __builtin_amdgcn_mov_dpp(__builtin_bit_cast(int, x), CTRL, 0xf, 0xf, true)); }
; __device__ __forceinline__ float red8(float d) { d += dpp_f<0xB1>(d); d += dpp_f<0x4E>(d); d += dpp_f<0x141>(d); return d; }
; __device__ __forceinline__ void upd8(V8& S, const V8& w, const V8& b, const V8& k, float sa, float vv) {
;     const f32x2 sa2 = {sa, sa}, vv2 = {vv, vv};
; #pragma unroll
;     for (int i = 0; i < 4; ++i) { f32x2 t = vv2 * k.p[i]; t = sa2 * b.p[i] + t; S.p[i] = S.p[i] * w.p[i] + t; }
; }
; __device__ __forceinline__ void updp8(V8& S, const V8& w, const V8& b, float sa) {
;     const f32x2 sa2 = {sa, sa};
; #pragma unroll
;     for (int i = 0; i < 4; ++i) { const f32x2 t = sa2 * b.p[i]; S.p[i] = S.p[i] * w.p[i] + t; }
; }
; template <int MODE>
; __device__ __forceinline__ void scan_pair(LAS unsigned char* lds, CArgsP a, const ScanUnit u, int nch) {
;     ...
;         for (int t = 0; t < 16; ++t) {
;             const LAS float* p = cb + t * 64 + 8 * ks;
;             const V8 w = ld8(p), kk = ld8(p + 1024), bb = ld8(p + 2048), kv = ld8(p + 3072);
;             const float va = cb[(5 * 16 + t) * 64 + vr0], vb = cb[(5 * 16 + t) * 64 + vr1];
;             float da = dot8(Sa, kk), db = dot8(Sb, kk);
;             da = red8(da); db = red8(db);
;             upd8(Sa, w, bb, kv, -da, va); upd8(Sb, w, bb, kv, -db, vb);
;             if (MODE == 1) {
;                 float pa = dot8(Pa, kk), pb = dot8(Pb, kk);
;                 pa = red8(pa); pb = red8(pb);
;                 updp8(Pa, w, bb, -pa); updp8(Pb, w, bb, -pb);
	v_pk_mul_f32 v[112:113], v[28:29], v[182:183]
	v_pk_mul_f32 v[114:115], v[24:25], v[182:183]
	v_pk_mul_f32 v[116:117], v[16:17], v[182:183]
	v_pk_mul_f32 v[118:119], v[8:9], v[182:183]
	v_pk_fma_f32 v[112:113], v[30:31], v[184:185], v[112:113]
	v_pk_fma_f32 v[114:115], v[26:27], v[184:185], v[114:115]
	v_pk_fma_f32 v[116:117], v[18:19], v[184:185], v[116:117]
	v_pk_fma_f32 v[118:119], v[10:11], v[184:185], v[118:119]
	v_pk_fma_f32 v[112:113], v[20:21], v[186:187], v[112:113]
	v_pk_fma_f32 v[114:115], v[12:13], v[186:187], v[114:115]
	v_pk_fma_f32 v[116:117], v[4:5], v[186:187], v[116:117]
	v_pk_fma_f32 v[118:119], v[0:1], v[186:187], v[118:119]
	v_pk_fma_f32 v[112:113], v[22:23], v[188:189], v[112:113]
	v_pk_fma_f32 v[114:115], v[14:15], v[188:189], v[114:115]
	v_pk_fma_f32 v[116:117], v[6:7], v[188:189], v[116:117]
	v_pk_fma_f32 v[118:119], v[2:3], v[188:189], v[118:119]
	v_add_f32_e32 v112, v112, v113
	v_add_f32_e32 v114, v114, v115
	v_add_f32_e32 v116, v116, v117
	v_add_f32_e32 v118, v118, v119
	v_pk_mul_f32 v[252:253], v[134:135], v[142:143] op_sel_hi:[1,0]
	v_pk_mul_f32 v[254:255], v[134:135], v[142:143] op_sel:[0,1] op_sel_hi:[1,1]
	v_pk_mul_f32 v[194:195], v[136:137], v[142:143] op_sel_hi:[1,0]
	v_pk_mul_f32 v[162:163], v[136:137], v[142:143] op_sel:[0,1] op_sel_hi:[1,1]
	v_add_f32_dpp v112, v112, v112 quad_perm:[1,0,3,2] row_mask:0xf bank_mask:0xf bound_ctrl:1
	v_add_f32_dpp v114, v114, v114 quad_perm:[1,0,3,2] row_mask:0xf bank_mask:0xf bound_ctrl:1
	v_add_f32_dpp v116, v116, v116 quad_perm:[1,0,3,2] row_mask:0xf bank_mask:0xf bound_ctrl:1
	v_add_f32_dpp v118, v118, v118 quad_perm:[1,0,3,2] row_mask:0xf bank_mask:0xf bound_ctrl:1
	v_pk_fma_f32 v[28:29], v[28:29], v[174:175], v[252:253]
	v_pk_fma_f32 v[24:25], v[24:25], v[174:175], v[254:255]
	v_pk_fma_f32 v[30:31], v[30:31], v[176:177], v[194:195]
	v_pk_fma_f32 v[26:27], v[26:27], v[176:177], v[162:163]
	v_add_f32_dpp v112, v112, v112 quad_perm:[2,3,0,1] row_mask:0xf bank_mask:0xf bound_ctrl:1
	v_add_f32_dpp v114, v114, v114 quad_perm:[2,3,0,1] row_mask:0xf bank_mask:0xf bound_ctrl:1
	v_add_f32_dpp v116, v116, v116 quad_perm:[2,3,0,1] row_mask:0xf bank_mask:0xf bound_ctrl:1
	v_add_f32_dpp v118, v118, v118 quad_perm:[2,3,0,1] row_mask:0xf bank_mask:0xf bound_ctrl:1
	v_pk_mul_f32 v[252:253], v[138:139], v[142:143] op_sel_hi:[1,0]
	v_pk_mul_f32 v[254:255], v[138:139], v[142:143] op_sel:[0,1] op_sel_hi:[1,1]
	v_pk_mul_f32 v[194:195], v[140:141], v[142:143] op_sel_hi:[1,0]
	v_pk_mul_f32 v[162:163], v[140:141], v[142:143] op_sel:[0,1] op_sel_hi:[1,1]
	v_add_f32_dpp v112, v112, v112 row_half_mirror row_mask:0xf bank_mask:0xf bound_ctrl:1
	v_add_f32_dpp v114, v114, v114 row_half_mirror row_mask:0xf bank_mask:0xf bound_ctrl:1
	v_add_f32_dpp v116, v116, v116 row_half_mirror row_mask:0xf bank_mask:0xf bound_ctrl:1
	v_add_f32_dpp v118, v118, v118 row_half_mirror row_mask:0xf bank_mask:0xf bound_ctrl:1
	v_pk_fma_f32 v[20:21], v[20:21], v[178:179], v[252:253]
	v_pk_fma_f32 v[12:13], v[12:13], v[178:179], v[254:255]
	v_pk_fma_f32 v[22:23], v[22:23], v[180:181], v[194:195]
	v_pk_fma_f32 v[14:15], v[14:15], v[180:181], v[162:163]
	v_pk_mul_f32 v[16:17], v[16:17], v[174:175]
	v_pk_mul_f32 v[8:9], v[8:9], v[174:175]
	v_pk_mul_f32 v[18:19], v[18:19], v[176:177]
	v_pk_mul_f32 v[10:11], v[10:11], v[176:177]
	v_pk_mul_f32 v[4:5], v[4:5], v[178:179]
	v_pk_mul_f32 v[0:1], v[0:1], v[178:179]
	v_pk_mul_f32 v[6:7], v[6:7], v[180:181]
	v_pk_mul_f32 v[2:3], v[2:3], v[180:181]
	v_pk_fma_f32 v[28:29], v[190:191], v[112:113], v[28:29] op_sel_hi:[1,0,1] neg_lo:[0,1,0] neg_hi:[0,1,0]
	v_pk_fma_f32 v[24:25], v[190:191], v[114:115], v[24:25] op_sel_hi:[1,0,1] neg_lo:[0,1,0] neg_hi:[0,1,0]
	v_pk_fma_f32 v[30:31], v[192:193], v[112:113], v[30:31] op_sel_hi:[1,0,1] neg_lo:[0,1,0] neg_hi:[0,1,0]
	v_pk_fma_f32 v[26:27], v[192:193], v[114:115], v[26:27] op_sel_hi:[1,0,1] neg_lo:[0,1,0] neg_hi:[0,1,0]
	v_pk_fma_f32 v[20:21], v[130:131], v[112:113], v[20:21] op_sel_hi:[1,0,1] neg_lo:[0,1,0] neg_hi:[0,1,0]
	v_pk_fma_f32 v[12:13], v[130:131], v[114:115], v[12:13] op_sel_hi:[1,0,1] neg_lo:[0,1,0] neg_hi:[0,1,0]
	v_pk_fma_f32 v[22:23], v[132:133], v[112:113], v[22:23] op_sel_hi:[1,0,1] neg_lo:[0,1,0] neg_hi:[0,1,0]
	v_pk_fma_f32 v[14:15], v[132:133], v[114:115], v[14:15] op_sel_hi:[1,0,1] neg_lo:[0,1,0] neg_hi:[0,1,0]
	v_pk_fma_f32 v[16:17], v[190:191], v[116:117], v[16:17] op_sel_hi:[1,0,1] neg_lo:[0,1,0] neg_hi:[0,1,0]
	v_pk_fma_f32 v[8:9], v[190:191], v[118:119], v[8:9] op_sel_hi:[1,0,1] neg_lo:[0,1,0] neg_hi:[0,1,0]
	v_pk_fma_f32 v[18:19], v[192:193], v[116:117], v[18:19] op_sel_hi:[1,0,1] neg_lo:[0,1,0] neg_hi:[0,1,0]
	v_pk_fma_f32 v[10:11], v[192:193], v[118:119], v[10:11] op_sel_hi:[1,0,1] neg_lo:[0,1,0] neg_hi:[0,1,0]
	v_pk_fma_f32 v[4:5], v[130:131], v[116:117], v[4:5] op_sel_hi:[1,0,1] neg_lo:[0,1,0] neg_hi:[0,1,0]
	v_pk_fma_f32 v[0:1], v[130:131], v[118:119], v[0:1] op_sel_hi:[1,0,1] neg_lo:[0,1,0] neg_hi:[0,1,0]
	v_pk_fma_f32 v[6:7], v[132:133], v[116:117], v[6:7] op_sel_hi:[1,0,1] neg_lo:[0,1,0] neg_hi:[0,1,0]
	v_pk_fma_f32 v[2:3], v[132:133], v[118:119], v[2:3] op_sel_hi:[1,0,1] neg_lo:[0,1,0] neg_hi:[0,1,0]
	ds_read_b128 v[174:177], v33 offset:1280
	ds_read_b128 v[178:181], v33 offset:1296
	ds_read_b128 v[182:185], v33 offset:5376
	ds_read_b128 v[186:189], v33 offset:5392
	ds_read_b128 v[190:193], v33 offset:9472
	ds_read_b128 v[130:133], v33 offset:9488
	ds_read_b128 v[134:137], v33 offset:13568
	ds_read_b128 v[138:141], v33 offset:13584
	ds_read2_b32 v[142:143], v151 offset0:64 offset1:72
	s_waitcnt lgkmcnt(9)
; #define LAS __attribute__((address_space(3)))
; template <int CTRL> __device__ __forceinline__ float dpp_f(float x) { return __builtin_bit_cast(float, __builtin_amdgcn_mov_dpp(__builtin_bit_cast(int, x), CTRL, 0xf, 0xf, true)); }
; __device__ __forceinline__ float red8(float d) { d += dpp_f<0xB1>(d); d += dpp_f<0x4E>(d); d += dpp_f<0x141>(d); return d; }
; __device__ __forceinline__ void upd8(V8& S, const V8& w, const V8& b, const V8& k, float sa, float vv) {
;     const f32x2 sa2 = {sa, sa}, vv2 = {vv, vv};
; #pragma unroll
;     for (int i = 0; i < 4; ++i) { f32x2 t = vv2 * k.p[i]; t = sa2 * b.p[i] + t; S.p[i] = S.p[i] * w.p[i] + t; }
; }
; __device__ __forceinline__ void updp8(V8& S, const V8& w, const V8& b, float sa) {
;     const f32x2 sa2 = {sa, sa};
; #pragma unroll
;     for (int i = 0; i < 4; ++i) { const f32x2 t = sa2 * b.p[i]; S.p[i] = S.p[i] * w.p[i] + t; }
; }
; template <int MODE>
; __device__ __forceinline__ void scan_pair(LAS unsigned char* lds, CArgsP a, const ScanUnit u, int nch) {
;     ...
;         for (int t = 0; t < 16; ++t) {
;             const LAS float* p = cb + t * 64 + 8 * ks;
;             const V8 w = ld8(p), kk = ld8(p + 1024), bb = ld8(p + 2048), kv = ld8(p + 3072);
;             const float va = cb[(5 * 16 + t) * 64 + vr0], vb = cb[(5 * 16 + t) * 64 + vr1];
;             float da = dot8(Sa, kk), db = dot8(Sb, kk);
;             da = red8(da); db = red8(db);
;             upd8(Sa, w, bb, kv, -da, va); upd8(Sb, w, bb, kv, -db, vb);
;             if (MODE == 1) {
;                 float pa = dot8(Pa, kk), pb = dot8(Pb, kk);
;                 pa = red8(pa); pb = red8(pb);
;                 updp8(Pa, w, bb, -pa); updp8(Pb, w, bb, -pb);
	v_pk_mul_f32 v[112:113], v[28:29], v[232:233]
	v_pk_mul_f32 v[114:115], v[24:25], v[232:233]
	v_pk_mul_f32 v[116:117], v[16:17], v[232:233]
	v_pk_mul_f32 v[118:119], v[8:9], v[232:233]
	v_pk_fma_f32 v[112:113], v[30:31], v[234:235], v[112:113]
	v_pk_fma_f32 v[114:115], v[26:27], v[234:235], v[114:115]
	v_pk_fma_f32 v[116:117], v[18:19], v[234:235], v[116:117]
	v_pk_fma_f32 v[118:119], v[10:11], v[234:235], v[118:119]
	v_pk_fma_f32 v[112:113], v[20:21], v[236:237], v[112:113]
	v_pk_fma_f32 v[114:115], v[12:13], v[236:237], v[114:115]
	v_pk_fma_f32 v[116:117], v[4:5], v[236:237], v[116:117]
	v_pk_fma_f32 v[118:119], v[0:1], v[236:237], v[118:119]
	v_pk_fma_f32 v[112:113], v[22:23], v[238:239], v[112:113]
	v_pk_fma_f32 v[114:115], v[14:15], v[238:239], v[114:115]
	v_pk_fma_f32 v[116:117], v[6:7], v[238:239], v[116:117]
	v_pk_fma_f32 v[118:119], v[2:3], v[238:239], v[118:119]
	v_add_f32_e32 v112, v112, v113
	v_add_f32_e32 v114, v114, v115
	v_add_f32_e32 v116, v116, v117
	v_add_f32_e32 v118, v118, v119
	v_pk_mul_f32 v[252:253], v[166:167], v[248:249] op_sel_hi:[1,0]
	v_pk_mul_f32 v[254:255], v[166:167], v[248:249] op_sel:[0,1] op_sel_hi:[1,1]
	v_pk_mul_f32 v[194:195], v[168:169], v[248:249] op_sel_hi:[1,0]
	v_pk_mul_f32 v[162:163], v[168:169], v[248:249] op_sel:[0,1] op_sel_hi:[1,1]
	v_add_f32_dpp v112, v112, v112 quad_perm:[1,0,3,2] row_mask:0xf bank_mask:0xf bound_ctrl:1
	v_add_f32_dpp v114, v114, v114 quad_perm:[1,0,3,2] row_mask:0xf bank_mask:0xf bound_ctrl:1
	v_add_f32_dpp v116, v116, v116 quad_perm:[1,0,3,2] row_mask:0xf bank_mask:0xf bound_ctrl:1
	v_add_f32_dpp v118, v118, v118 quad_perm:[1,0,3,2] row_mask:0xf bank_mask:0xf bound_ctrl:1
	v_pk_fma_f32 v[28:29], v[28:29], v[224:225], v[252:253]
	v_pk_fma_f32 v[24:25], v[24:25], v[224:225], v[254:255]
	v_pk_fma_f32 v[30:31], v[30:31], v[226:227], v[194:195]
	v_pk_fma_f32 v[26:27], v[26:27], v[226:227], v[162:163]
	v_add_f32_dpp v112, v112, v112 quad_perm:[2,3,0,1] row_mask:0xf bank_mask:0xf bound_ctrl:1
	v_add_f32_dpp v114, v114, v114 quad_perm:[2,3,0,1] row_mask:0xf bank_mask:0xf bound_ctrl:1
	v_add_f32_dpp v116, v116, v116 quad_perm:[2,3,0,1] row_mask:0xf bank_mask:0xf bound_ctrl:1
	v_add_f32_dpp v118, v118, v118 quad_perm:[2,3,0,1] row_mask:0xf bank_mask:0xf bound_ctrl:1
	v_pk_mul_f32 v[252:253], v[170:171], v[248:249] op_sel_hi:[1,0]
	v_pk_mul_f32 v[254:255], v[170:171], v[248:249] op_sel:[0,1] op_sel_hi:[1,1]
	v_pk_mul_f32 v[194:195], v[172:173], v[248:249] op_sel_hi:[1,0]
	v_pk_mul_f32 v[162:163], v[172:173], v[248:249] op_sel:[0,1] op_sel_hi:[1,1]
	v_add_f32_dpp v112, v112, v112 row_half_mirror row_mask:0xf bank_mask:0xf bound_ctrl:1
	v_add_f32_dpp v114, v114, v114 row_half_mirror row_mask:0xf bank_mask:0xf bound_ctrl:1
	v_add_f32_dpp v116, v116, v116 row_half_mirror row_mask:0xf bank_mask:0xf bound_ctrl:1
	v_add_f32_dpp v118, v118, v118 row_half_mirror row_mask:0xf bank_mask:0xf bound_ctrl:1
	v_pk_fma_f32 v[20:21], v[20:21], v[228:229], v[252:253]
	v_pk_fma_f32 v[12:13], v[12:13], v[228:229], v[254:255]
	v_pk_fma_f32 v[22:23], v[22:23], v[230:231], v[194:195]
	v_pk_fma_f32 v[14:15], v[14:15], v[230:231], v[162:163]
	v_pk_mul_f32 v[16:17], v[16:17], v[224:225]
	v_pk_mul_f32 v[8:9], v[8:9], v[224:225]
	v_pk_mul_f32 v[18:19], v[18:19], v[226:227]
	v_pk_mul_f32 v[10:11], v[10:11], v[226:227]
	v_pk_mul_f32 v[4:5], v[4:5], v[228:229]
	v_pk_mul_f32 v[0:1], v[0:1], v[228:229]
	v_pk_mul_f32 v[6:7], v[6:7], v[230:231]
	v_pk_mul_f32 v[2:3], v[2:3], v[230:231]
	v_pk_fma_f32 v[28:29], v[240:241], v[112:113], v[28:29] op_sel_hi:[1,0,1] neg_lo:[0,1,0] neg_hi:[0,1,0]
	v_pk_fma_f32 v[24:25], v[240:241], v[114:115], v[24:25] op_sel_hi:[1,0,1] neg_lo:[0,1,0] neg_hi:[0,1,0]
	v_pk_fma_f32 v[30:31], v[242:243], v[112:113], v[30:31] op_sel_hi:[1,0,1] neg_lo:[0,1,0] neg_hi:[0,1,0]
	v_pk_fma_f32 v[26:27], v[242:243], v[114:115], v[26:27] op_sel_hi:[1,0,1] neg_lo:[0,1,0] neg_hi:[0,1,0]
	v_pk_fma_f32 v[20:21], v[244:245], v[112:113], v[20:21] op_sel_hi:[1,0,1] neg_lo:[0,1,0] neg_hi:[0,1,0]
	v_pk_fma_f32 v[12:13], v[244:245], v[114:115], v[12:13] op_sel_hi:[1,0,1] neg_lo:[0,1,0] neg_hi:[0,1,0]
	v_pk_fma_f32 v[22:23], v[246:247], v[112:113], v[22:23] op_sel_hi:[1,0,1] neg_lo:[0,1,0] neg_hi:[0,1,0]
	v_pk_fma_f32 v[14:15], v[246:247], v[114:115], v[14:15] op_sel_hi:[1,0,1] neg_lo:[0,1,0] neg_hi:[0,1,0]
	v_pk_fma_f32 v[16:17], v[240:241], v[116:117], v[16:17] op_sel_hi:[1,0,1] neg_lo:[0,1,0] neg_hi:[0,1,0]
	v_pk_fma_f32 v[8:9], v[240:241], v[118:119], v[8:9] op_sel_hi:[1,0,1] neg_lo:[0,1,0] neg_hi:[0,1,0]
	v_pk_fma_f32 v[18:19], v[242:243], v[116:117], v[18:19] op_sel_hi:[1,0,1] neg_lo:[0,1,0] neg_hi:[0,1,0]
	v_pk_fma_f32 v[10:11], v[242:243], v[118:119], v[10:11] op_sel_hi:[1,0,1] neg_lo:[0,1,0] neg_hi:[0,1,0]
	v_pk_fma_f32 v[4:5], v[244:245], v[116:117], v[4:5] op_sel_hi:[1,0,1] neg_lo:[0,1,0] neg_hi:[0,1,0]
	v_pk_fma_f32 v[0:1], v[244:245], v[118:119], v[0:1] op_sel_hi:[1,0,1] neg_lo:[0,1,0] neg_hi:[0,1,0]
	v_pk_fma_f32 v[6:7], v[246:247], v[116:117], v[6:7] op_sel_hi:[1,0,1] neg_lo:[0,1,0] neg_hi:[0,1,0]
	v_pk_fma_f32 v[2:3], v[246:247], v[118:119], v[2:3] op_sel_hi:[1,0,1] neg_lo:[0,1,0] neg_hi:[0,1,0]
	ds_read_b128 v[224:227], v33 offset:1536
	ds_read_b128 v[228:231], v33 offset:1552
	ds_read_b128 v[232:235], v33 offset:5632
	ds_read_b128 v[236:239], v33 offset:5648
	ds_read_b128 v[240:243], v33 offset:9728
	ds_read_b128 v[244:247], v33 offset:9744
	ds_read_b128 v[166:169], v33 offset:13824
	ds_read_b128 v[170:173], v33 offset:13840
	ds_read2_b32 v[248:249], v151 offset0:128 offset1:136
	s_waitcnt lgkmcnt(9)
; #define LAS __attribute__((address_space(3)))
; template <int CTRL> __device__ __forceinline__ float dpp_f(float x) { return __builtin_bit_cast(float, __builtin_amdgcn_mov_dpp(__builtin_bit_cast(int, x), CTRL, 0xf, 0xf, true)); }
; __device__ __forceinline__ float red8(float d) { d += dpp_f<0xB1>(d); d += dpp_f<0x4E>(d); d += dpp_f<0x141>(d); return d; }
; __device__ __forceinline__ void upd8(V8& S, const V8& w, const V8& b, const V8& k, float sa, float vv) {
;     const f32x2 sa2 = {sa, sa}, vv2 = {vv, vv};
; #pragma unroll
;     for (int i = 0; i < 4; ++i) { f32x2 t = vv2 * k.p[i]; t = sa2 * b.p[i] + t; S.p[i] = S.p[i] * w.p[i] + t; }
; }
; __device__ __forceinline__ void updp8(V8& S, const V8& w, const V8& b, float sa) {
;     const f32x2 sa2 = {sa, sa};
; #pragma unroll
;     for (int i = 0; i < 4; ++i) { const f32x2 t = sa2 * b.p[i]; S.p[i] = S.p[i] * w.p[i] + t; }
; }
; template <int MODE>
; __device__ __forceinline__ void scan_pair(LAS unsigned char* lds, CArgsP a, const ScanUnit u, int nch) {
;     ...
;             const LAS float* p = cb + t * 64 + 8 * ks;
;             const V8 w = ld8(p), kk = ld8(p + 1024), bb = ld8(p + 2048), kv = ld8(p + 3072);
;             const float va = cb[(5 * 16 + t) * 64 + vr0], vb = cb[(5 * 16 + t) * 64 + vr1];
;             float da = dot8(Sa, kk), db = dot8(Sb, kk);
;             da = red8(da); db = red8(db);
;             upd8(Sa, w, bb, kv, -da, va); upd8(Sb, w, bb, kv, -db, vb);
;             if (MODE == 1) {
;                 float pa = dot8(Pa, kk), pb = dot8(Pb, kk);
;                 pa = red8(pa); pb = red8(pb);
;                 updp8(Pa, w, bb, -pa); updp8(Pb, w, bb, -pb);
	v_pk_mul_f32 v[112:113], v[28:29], v[182:183]
	v_pk_mul_f32 v[114:115], v[24:25], v[182:183]
	v_pk_mul_f32 v[116:117], v[16:17], v[182:183]
	v_pk_mul_f32 v[118:119], v[8:9], v[182:183]
	v_pk_fma_f32 v[112:113], v[30:31], v[184:185], v[112:113]
	v_pk_fma_f32 v[114:115], v[26:27], v[184:185], v[114:115]
	v_pk_fma_f32 v[116:117], v[18:19], v[184:185], v[116:117]
	v_pk_fma_f32 v[118:119], v[10:11], v[184:185], v[118:119]
	v_pk_fma_f32 v[112:113], v[20:21], v[186:187], v[112:113]
	v_pk_fma_f32 v[114:115], v[12:13], v[186:187], v[114:115]
	v_pk_fma_f32 v[116:117], v[4:5], v[186:187], v[116:117]
	v_pk_fma_f32 v[118:119], v[0:1], v[186:187], v[118:119]
	v_pk_fma_f32 v[112:113], v[22:23], v[188:189], v[112:113]
	v_pk_fma_f32 v[114:115], v[14:15], v[188:189], v[114:115]
	v_pk_fma_f32 v[116:117], v[6:7], v[188:189], v[116:117]
	v_pk_fma_f32 v[118:119], v[2:3], v[188:189], v[118:119]
	v_add_f32_e32 v112, v112, v113
	v_add_f32_e32 v114, v114, v115
	v_add_f32_e32 v116, v116, v117
	v_add_f32_e32 v118, v118, v119
	v_pk_mul_f32 v[252:253], v[134:135], v[142:143] op_sel_hi:[1,0]
	v_pk_mul_f32 v[254:255], v[134:135], v[142:143] op_sel:[0,1] op_sel_hi:[1,1]
	v_pk_mul_f32 v[194:195], v[136:137], v[142:143] op_sel_hi:[1,0]
	v_pk_mul_f32 v[162:163], v[136:137], v[142:143] op_sel:[0,1] op_sel_hi:[1,1]
	v_add_f32_dpp v112, v112, v112 quad_perm:[1,0,3,2] row_mask:0xf bank_mask:0xf bound_ctrl:1
	v_add_f32_dpp v114, v114, v114 quad_perm:[1,0,3,2] row_mask:0xf bank_mask:0xf bound_ctrl:1
	v_add_f32_dpp v116, v116, v116 quad_perm:[1,0,3,2] row_mask:0xf bank_mask:0xf bound_ctrl:1
	v_add_f32_dpp v118, v118, v118 quad_perm:[1,0,3,2] row_mask:0xf bank_mask:0xf bound_ctrl:1
	v_pk_fma_f32 v[28:29], v[28:29], v[174:175], v[252:253]
	v_pk_fma_f32 v[24:25], v[24:25], v[174:175], v[254:255]
	v_pk_fma_f32 v[30:31], v[30:31], v[176:177], v[194:195]
	v_pk_fma_f32 v[26:27], v[26:27], v[176:177], v[162:163]
	v_add_f32_dpp v112, v112, v112 quad_perm:[2,3,0,1] row_mask:0xf bank_mask:0xf bound_ctrl:1
	v_add_f32_dpp v114, v114, v114 quad_perm:[2,3,0,1] row_mask:0xf bank_mask:0xf bound_ctrl:1
	v_add_f32_dpp v116, v116, v116 quad_perm:[2,3,0,1] row_mask:0xf bank_mask:0xf bound_ctrl:1
	v_add_f32_dpp v118, v118, v118 quad_perm:[2,3,0,1] row_mask:0xf bank_mask:0xf bound_ctrl:1
	v_pk_mul_f32 v[252:253], v[138:139], v[142:143] op_sel_hi:[1,0]
	v_pk_mul_f32 v[254:255], v[138:139], v[142:143] op_sel:[0,1] op_sel_hi:[1,1]
	v_pk_mul_f32 v[194:195], v[140:141], v[142:143] op_sel_hi:[1,0]
	v_pk_mul_f32 v[162:163], v[140:141], v[142:143] op_sel:[0,1] op_sel_hi:[1,1]
	v_add_f32_dpp v112, v112, v112 row_half_mirror row_mask:0xf bank_mask:0xf bound_ctrl:1
	v_add_f32_dpp v114, v114, v114 row_half_mirror row_mask:0xf bank_mask:0xf bound_ctrl:1
	v_add_f32_dpp v116, v116, v116 row_half_mirror row_mask:0xf bank_mask:0xf bound_ctrl:1
	v_add_f32_dpp v118, v118, v118 row_half_mirror row_mask:0xf bank_mask:0xf bound_ctrl:1
	v_pk_fma_f32 v[20:21], v[20:21], v[178:179], v[252:253]
	v_pk_fma_f32 v[12:13], v[12:13], v[178:179], v[254:255]
	v_pk_fma_f32 v[22:23], v[22:23], v[180:181], v[194:195]
	v_pk_fma_f32 v[14:15], v[14:15], v[180:181], v[162:163]
	v_pk_mul_f32 v[16:17], v[16:17], v[174:175]
	v_pk_mul_f32 v[8:9], v[8:9], v[174:175]
	v_pk_mul_f32 v[18:19], v[18:19], v[176:177]
	v_pk_mul_f32 v[10:11], v[10:11], v[176:177]
	v_pk_mul_f32 v[4:5], v[4:5], v[178:179]
	v_pk_mul_f32 v[0:1], v[0:1], v[178:179]
	v_pk_mul_f32 v[6:7], v[6:7], v[180:181]
	v_pk_mul_f32 v[2:3], v[2:3], v[180:181]
	v_pk_fma_f32 v[28:29], v[190:191], v[112:113], v[28:29] op_sel_hi:[1,0,1] neg_lo:[0,1,0] neg_hi:[0,1,0]
	v_pk_fma_f32 v[24:25], v[190:191], v[114:115], v[24:25] op_sel_hi:[1,0,1] neg_lo:[0,1,0] neg_hi:[0,1,0]
	v_pk_fma_f32 v[30:31], v[192:193], v[112:113], v[30:31] op_sel_hi:[1,0,1] neg_lo:[0,1,0] neg_hi:[0,1,0]
	v_pk_fma_f32 v[26:27], v[192:193], v[114:115], v[26:27] op_sel_hi:[1,0,1] neg_lo:[0,1,0] neg_hi:[0,1,0]
	v_pk_fma_f32 v[20:21], v[130:131], v[112:113], v[20:21] op_sel_hi:[1,0,1] neg_lo:[0,1,0] neg_hi:[0,1,0]
	v_pk_fma_f32 v[12:13], v[130:131], v[114:115], v[12:13] op_sel_hi:[1,0,1] neg_lo:[0,1,0] neg_hi:[0,1,0]
	v_pk_fma_f32 v[22:23], v[132:133], v[112:113], v[22:23] op_sel_hi:[1,0,1] neg_lo:[0,1,0] neg_hi:[0,1,0]
	v_pk_fma_f32 v[14:15], v[132:133], v[114:115], v[14:15] op_sel_hi:[1,0,1] neg_lo:[0,1,0] neg_hi:[0,1,0]
	v_pk_fma_f32 v[16:17], v[190:191], v[116:117], v[16:17] op_sel_hi:[1,0,1] neg_lo:[0,1,0] neg_hi:[0,1,0]
	v_pk_fma_f32 v[8:9], v[190:191], v[118:119], v[8:9] op_sel_hi:[1,0,1] neg_lo:[0,1,0] neg_hi:[0,1,0]
	v_pk_fma_f32 v[18:19], v[192:193], v[116:117], v[18:19] op_sel_hi:[1,0,1] neg_lo:[0,1,0] neg_hi:[0,1,0]
	v_pk_fma_f32 v[10:11], v[192:193], v[118:119], v[10:11] op_sel_hi:[1,0,1] neg_lo:[0,1,0] neg_hi:[0,1,0]
	v_pk_fma_f32 v[4:5], v[130:131], v[116:117], v[4:5] op_sel_hi:[1,0,1] neg_lo:[0,1,0] neg_hi:[0,1,0]
	v_pk_fma_f32 v[0:1], v[130:131], v[118:119], v[0:1] op_sel_hi:[1,0,1] neg_lo:[0,1,0] neg_hi:[0,1,0]
	v_pk_fma_f32 v[6:7], v[132:133], v[116:117], v[6:7] op_sel_hi:[1,0,1] neg_lo:[0,1,0] neg_hi:[0,1,0]
	v_pk_fma_f32 v[2:3], v[132:133], v[118:119], v[2:3] op_sel_hi:[1,0,1] neg_lo:[0,1,0] neg_hi:[0,1,0]
	ds_read_b128 v[174:177], v33 offset:1792
	ds_read_b128 v[178:181], v33 offset:1808
	ds_read_b128 v[182:185], v33 offset:5888
	ds_read_b128 v[186:189], v33 offset:5904
	ds_read_b128 v[190:193], v33 offset:9984
	ds_read_b128 v[130:133], v33 offset:10000
	ds_read_b128 v[134:137], v33 offset:14080
	ds_read_b128 v[138:141], v33 offset:14096
	ds_read2_b32 v[142:143], v151 offset0:192 offset1:200
	s_waitcnt lgkmcnt(9)
; #define LAS __attribute__((address_space(3)))
; template <int CTRL> __device__ __forceinline__ float dpp_f(float x) { return __builtin_bit_cast(float, __builtin_amdgcn_mov_dpp(__builtin_bit_cast(int, x), CTRL, 0xf, 0xf, true)); }
; __device__ __forceinline__ float red8(float d) { d += dpp_f<0xB1>(d); d += dpp_f<0x4E>(d); d += dpp_f<0x141>(d); return d; }
; __device__ __forceinline__ void upd8(V8& S, const V8& w, const V8& b, const V8& k, float sa, float vv) {
;     const f32x2 sa2 = {sa, sa}, vv2 = {vv, vv};
; #pragma unroll
;     for (int i = 0; i < 4; ++i) { f32x2 t = vv2 * k.p[i]; t = sa2 * b.p[i] + t; S.p[i] = S.p[i] * w.p[i] + t; }
; }
; __device__ __forceinline__ void updp8(V8& S, const V8& w, const V8& b, float sa) {
;     const f32x2 sa2 = {sa, sa};
; #pragma unroll
;     for (int i = 0; i < 4; ++i) { const f32x2 t = sa2 * b.p[i]; S.p[i] = S.p[i] * w.p[i] + t; }
; }
; template <int MODE>
; __device__ __forceinline__ void scan_pair(LAS unsigned char* lds, CArgsP a, const ScanUnit u, int nch) {
;     ...
;             const LAS float* p = cb + t * 64 + 8 * ks;
;             const V8 w = ld8(p), kk = ld8(p + 1024), bb = ld8(p + 2048), kv = ld8(p + 3072);
;             const float va = cb[(5 * 16 + t) * 64 + vr0], vb = cb[(5 * 16 + t) * 64 + vr1];
;             float da = dot8(Sa, kk), db = dot8(Sb, kk);
;             da = red8(da); db = red8(db);
;             upd8(Sa, w, bb, kv, -da, va); upd8(Sb, w, bb, kv, -db, vb);
;             if (MODE == 1) {
;                 float pa = dot8(Pa, kk), pb = dot8(Pb, kk);
;                 pa = red8(pa); pb = red8(pb);
;                 updp8(Pa, w, bb, -pa); updp8(Pb, w, bb, -pb);
	v_pk_mul_f32 v[112:113], v[28:29], v[232:233]
	v_pk_mul_f32 v[114:115], v[24:25], v[232:233]
	v_pk_mul_f32 v[116:117], v[16:17], v[232:233]
	v_pk_mul_f32 v[118:119], v[8:9], v[232:233]
	v_pk_fma_f32 v[112:113], v[30:31], v[234:235], v[112:113]
	v_pk_fma_f32 v[114:115], v[26:27], v[234:235], v[114:115]
	v_pk_fma_f32 v[116:117], v[18:19], v[234:235], v[116:117]
	v_pk_fma_f32 v[118:119], v[10:11], v[234:235], v[118:119]
	v_pk_fma_f32 v[112:113], v[20:21], v[236:237], v[112:113]
	v_pk_fma_f32 v[114:115], v[12:13], v[236:237], v[114:115]
	v_pk_fma_f32 v[116:117], v[4:5], v[236:237], v[116:117]
	v_pk_fma_f32 v[118:119], v[0:1], v[236:237], v[118:119]
	v_pk_fma_f32 v[112:113], v[22:23], v[238:239], v[112:113]
	v_pk_fma_f32 v[114:115], v[14:15], v[238:239], v[114:115]
	v_pk_fma_f32 v[116:117], v[6:7], v[238:239], v[116:117]
	v_pk_fma_f32 v[118:119], v[2:3], v[238:239], v[118:119]
	v_add_f32_e32 v112, v112, v113
	v_add_f32_e32 v114, v114, v115
	v_add_f32_e32 v116, v116, v117
	v_add_f32_e32 v118, v118, v119
	v_pk_mul_f32 v[252:253], v[166:167], v[248:249] op_sel_hi:[1,0]
	v_pk_mul_f32 v[254:255], v[166:167], v[248:249] op_sel:[0,1] op_sel_hi:[1,1]
	v_pk_mul_f32 v[194:195], v[168:169], v[248:249] op_sel_hi:[1,0]
	v_pk_mul_f32 v[162:163], v[168:169], v[248:249] op_sel:[0,1] op_sel_hi:[1,1]
	v_add_f32_dpp v112, v112, v112 quad_perm:[1,0,3,2] row_mask:0xf bank_mask:0xf bound_ctrl:1
	v_add_f32_dpp v114, v114, v114 quad_perm:[1,0,3,2] row_mask:0xf bank_mask:0xf bound_ctrl:1
	v_add_f32_dpp v116, v116, v116 quad_perm:[1,0,3,2] row_mask:0xf bank_mask:0xf bound_ctrl:1
	v_add_f32_dpp v118, v118, v118 quad_perm:[1,0,3,2] row_mask:0xf bank_mask:0xf bound_ctrl:1
	v_pk_fma_f32 v[28:29], v[28:29], v[224:225], v[252:253]
	v_pk_fma_f32 v[24:25], v[24:25], v[224:225], v[254:255]
	v_pk_fma_f32 v[30:31], v[30:31], v[226:227], v[194:195]
	v_pk_fma_f32 v[26:27], v[26:27], v[226:227], v[162:163]
	v_add_f32_dpp v112, v112, v112 quad_perm:[2,3,0,1] row_mask:0xf bank_mask:0xf bound_ctrl:1
	v_add_f32_dpp v114, v114, v114 quad_perm:[2,3,0,1] row_mask:0xf bank_mask:0xf bound_ctrl:1
	v_add_f32_dpp v116, v116, v116 quad_perm:[2,3,0,1] row_mask:0xf bank_mask:0xf bound_ctrl:1
	v_add_f32_dpp v118, v118, v118 quad_perm:[2,3,0,1] row_mask:0xf bank_mask:0xf bound_ctrl:1
	v_pk_mul_f32 v[252:253], v[170:171], v[248:249] op_sel_hi:[1,0]
	v_pk_mul_f32 v[254:255], v[170:171], v[248:249] op_sel:[0,1] op_sel_hi:[1,1]
	v_pk_mul_f32 v[194:195], v[172:173], v[248:249] op_sel_hi:[1,0]
	v_pk_mul_f32 v[162:163], v[172:173], v[248:249] op_sel:[0,1] op_sel_hi:[1,1]
	v_add_f32_dpp v112, v112, v112 row_half_mirror row_mask:0xf bank_mask:0xf bound_ctrl:1
	v_add_f32_dpp v114, v114, v114 row_half_mirror row_mask:0xf bank_mask:0xf bound_ctrl:1
	v_add_f32_dpp v116, v116, v116 row_half_mirror row_mask:0xf bank_mask:0xf bound_ctrl:1
	v_add_f32_dpp v118, v118, v118 row_half_mirror row_mask:0xf bank_mask:0xf bound_ctrl:1
	v_pk_fma_f32 v[20:21], v[20:21], v[228:229], v[252:253]
	v_pk_fma_f32 v[12:13], v[12:13], v[228:229], v[254:255]
	v_pk_fma_f32 v[22:23], v[22:23], v[230:231], v[194:195]
	v_pk_fma_f32 v[14:15], v[14:15], v[230:231], v[162:163]
	v_pk_mul_f32 v[16:17], v[16:17], v[224:225]
	v_pk_mul_f32 v[8:9], v[8:9], v[224:225]
	v_pk_mul_f32 v[18:19], v[18:19], v[226:227]
	v_pk_mul_f32 v[10:11], v[10:11], v[226:227]
	v_pk_mul_f32 v[4:5], v[4:5], v[228:229]
	v_pk_mul_f32 v[0:1], v[0:1], v[228:229]
	v_pk_mul_f32 v[6:7], v[6:7], v[230:231]
	v_pk_mul_f32 v[2:3], v[2:3], v[230:231]
	v_pk_fma_f32 v[28:29], v[240:241], v[112:113], v[28:29] op_sel_hi:[1,0,1] neg_lo:[0,1,0] neg_hi:[0,1,0]
	v_pk_fma_f32 v[24:25], v[240:241], v[114:115], v[24:25] op_sel_hi:[1,0,1] neg_lo:[0,1,0] neg_hi:[0,1,0]
	v_pk_fma_f32 v[30:31], v[242:243], v[112:113], v[30:31] op_sel_hi:[1,0,1] neg_lo:[0,1,0] neg_hi:[0,1,0]
	v_pk_fma_f32 v[26:27], v[242:243], v[114:115], v[26:27] op_sel_hi:[1,0,1] neg_lo:[0,1,0] neg_hi:[0,1,0]
	v_pk_fma_f32 v[20:21], v[244:245], v[112:113], v[20:21] op_sel_hi:[1,0,1] neg_lo:[0,1,0] neg_hi:[0,1,0]
	v_pk_fma_f32 v[12:13], v[244:245], v[114:115], v[12:13] op_sel_hi:[1,0,1] neg_lo:[0,1,0] neg_hi:[0,1,0]
	v_pk_fma_f32 v[22:23], v[246:247], v[112:113], v[22:23] op_sel_hi:[1,0,1] neg_lo:[0,1,0] neg_hi:[0,1,0]
	v_pk_fma_f32 v[14:15], v[246:247], v[114:115], v[14:15] op_sel_hi:[1,0,1] neg_lo:[0,1,0] neg_hi:[0,1,0]
	v_pk_fma_f32 v[16:17], v[240:241], v[116:117], v[16:17] op_sel_hi:[1,0,1] neg_lo:[0,1,0] neg_hi:[0,1,0]
	v_pk_fma_f32 v[8:9], v[240:241], v[118:119], v[8:9] op_sel_hi:[1,0,1] neg_lo:[0,1,0] neg_hi:[0,1,0]
	v_pk_fma_f32 v[18:19], v[242:243], v[116:117], v[18:19] op_sel_hi:[1,0,1] neg_lo:[0,1,0] neg_hi:[0,1,0]
	v_pk_fma_f32 v[10:11], v[242:243], v[118:119], v[10:11] op_sel_hi:[1,0,1] neg_lo:[0,1,0] neg_hi:[0,1,0]
	v_pk_fma_f32 v[4:5], v[244:245], v[116:117], v[4:5] op_sel_hi:[1,0,1] neg_lo:[0,1,0] neg_hi:[0,1,0]
	v_pk_fma_f32 v[0:1], v[244:245], v[118:119], v[0:1] op_sel_hi:[1,0,1] neg_lo:[0,1,0] neg_hi:[0,1,0]
	v_pk_fma_f32 v[6:7], v[246:247], v[116:117], v[6:7] op_sel_hi:[1,0,1] neg_lo:[0,1,0] neg_hi:[0,1,0]
	v_pk_fma_f32 v[2:3], v[246:247], v[118:119], v[2:3] op_sel_hi:[1,0,1] neg_lo:[0,1,0] neg_hi:[0,1,0]
	ds_read_b128 v[224:227], v33 offset:2048
	ds_read_b128 v[228:231], v33 offset:2064
	ds_read_b128 v[232:235], v33 offset:6144
	ds_read_b128 v[236:239], v33 offset:6160
	ds_read_b128 v[240:243], v33 offset:10240
	ds_read_b128 v[244:247], v33 offset:10256
	ds_read_b128 v[166:169], v33 offset:14336
	ds_read_b128 v[170:173], v33 offset:14352
	v_add_u32_e32 v151, 0x400, v151
	ds_read2_b32 v[248:249], v151 offset0:0 offset1:8
	s_waitcnt lgkmcnt(9)
; #define LAS __attribute__((address_space(3)))
; template <int CTRL> __device__ __forceinline__ float dpp_f(float x) { return __builtin_bit_cast(float, __builtin_amdgcn_mov_dpp(__builtin_bit_cast(int, x), CTRL, 0xf, 0xf, true)); }
; __device__ __forceinline__ float red8(float d) { d += dpp_f<0xB1>(d); d += dpp_f<0x4E>(d); d += dpp_f<0x141>(d); return d; }
; __device__ __forceinline__ void upd8(V8& S, const V8& w, const V8& b, const V8& k, float sa, float vv) {
;     const f32x2 sa2 = {sa, sa}, vv2 = {vv, vv};
; #pragma unroll
;     for (int i = 0; i < 4; ++i) { f32x2 t = vv2 * k.p[i]; t = sa2 * b.p[i] + t; S.p[i] = S.p[i] * w.p[i] + t; }
; }
; __device__ __forceinline__ void updp8(V8& S, const V8& w, const V8& b, float sa) {
;     const f32x2 sa2 = {sa, sa};
; #pragma unroll
;     for (int i = 0; i < 4; ++i) { const f32x2 t = sa2 * b.p[i]; S.p[i] = S.p[i] * w.p[i] + t; }
; }
; template <int MODE>
; __device__ __forceinline__ void scan_pair(LAS unsigned char* lds, CArgsP a, const ScanUnit u, int nch) {
;     ...
;             const LAS float* p = cb + t * 64 + 8 * ks;
;             const V8 w = ld8(p), kk = ld8(p + 1024), bb = ld8(p + 2048), kv = ld8(p + 3072);
;             const float va = cb[(5 * 16 + t) * 64 + vr0], vb = cb[(5 * 16 + t) * 64 + vr1];
;             float da = dot8(Sa, kk), db = dot8(Sb, kk);
;             da = red8(da); db = red8(db);
;             upd8(Sa, w, bb, kv, -da, va); upd8(Sb, w, bb, kv, -db, vb);
;             if (MODE == 1) {
;                 float pa = dot8(Pa, kk), pb = dot8(Pb, kk);
;                 pa = red8(pa); pb = red8(pb);
;                 updp8(Pa, w, bb, -pa); updp8(Pb, w, bb, -pb);
	v_pk_mul_f32 v[112:113], v[28:29], v[182:183]
	v_pk_mul_f32 v[114:115], v[24:25], v[182:183]
	v_pk_mul_f32 v[116:117], v[16:17], v[182:183]
	v_pk_mul_f32 v[118:119], v[8:9], v[182:183]
	v_pk_fma_f32 v[112:113], v[30:31], v[184:185], v[112:113]
	v_pk_fma_f32 v[114:115], v[26:27], v[184:185], v[114:115]
	v_pk_fma_f32 v[116:117], v[18:19], v[184:185], v[116:117]
	v_pk_fma_f32 v[118:119], v[10:11], v[184:185], v[118:119]
	v_pk_fma_f32 v[112:113], v[20:21], v[186:187], v[112:113]
	v_pk_fma_f32 v[114:115], v[12:13], v[186:187], v[114:115]
	v_pk_fma_f32 v[116:117], v[4:5], v[186:187], v[116:117]
	v_pk_fma_f32 v[118:119], v[0:1], v[186:187], v[118:119]
	v_pk_fma_f32 v[112:113], v[22:23], v[188:189], v[112:113]
	v_pk_fma_f32 v[114:115], v[14:15], v[188:189], v[114:115]
	v_pk_fma_f32 v[116:117], v[6:7], v[188:189], v[116:117]
	v_pk_fma_f32 v[118:119], v[2:3], v[188:189], v[118:119]
	v_add_f32_e32 v112, v112, v113
	v_add_f32_e32 v114, v114, v115
	v_add_f32_e32 v116, v116, v117
	v_add_f32_e32 v118, v118, v119
	v_pk_mul_f32 v[252:253], v[134:135], v[142:143] op_sel_hi:[1,0]
	v_pk_mul_f32 v[254:255], v[134:135], v[142:143] op_sel:[0,1] op_sel_hi:[1,1]
	v_pk_mul_f32 v[194:195], v[136:137], v[142:143] op_sel_hi:[1,0]
	v_pk_mul_f32 v[162:163], v[136:137], v[142:143] op_sel:[0,1] op_sel_hi:[1,1]
	v_add_f32_dpp v112, v112, v112 quad_perm:[1,0,3,2] row_mask:0xf bank_mask:0xf bound_ctrl:1
	v_add_f32_dpp v114, v114, v114 quad_perm:[1,0,3,2] row_mask:0xf bank_mask:0xf bound_ctrl:1
	v_add_f32_dpp v116, v116, v116 quad_perm:[1,0,3,2] row_mask:0xf bank_mask:0xf bound_ctrl:1
	v_add_f32_dpp v118, v118, v118 quad_perm:[1,0,3,2] row_mask:0xf bank_mask:0xf bound_ctrl:1
	v_pk_fma_f32 v[28:29], v[28:29], v[174:175], v[252:253]
	v_pk_fma_f32 v[24:25], v[24:25], v[174:175], v[254:255]
	v_pk_fma_f32 v[30:31], v[30:31], v[176:177], v[194:195]
	v_pk_fma_f32 v[26:27], v[26:27], v[176:177], v[162:163]
	v_add_f32_dpp v112, v112, v112 quad_perm:[2,3,0,1] row_mask:0xf bank_mask:0xf bound_ctrl:1
	v_add_f32_dpp v114, v114, v114 quad_perm:[2,3,0,1] row_mask:0xf bank_mask:0xf bound_ctrl:1
	v_add_f32_dpp v116, v116, v116 quad_perm:[2,3,0,1] row_mask:0xf bank_mask:0xf bound_ctrl:1
	v_add_f32_dpp v118, v118, v118 quad_perm:[2,3,0,1] row_mask:0xf bank_mask:0xf bound_ctrl:1
	v_pk_mul_f32 v[252:253], v[138:139], v[142:143] op_sel_hi:[1,0]
	v_pk_mul_f32 v[254:255], v[138:139], v[142:143] op_sel:[0,1] op_sel_hi:[1,1]
	v_pk_mul_f32 v[194:195], v[140:141], v[142:143] op_sel_hi:[1,0]
	v_pk_mul_f32 v[162:163], v[140:141], v[142:143] op_sel:[0,1] op_sel_hi:[1,1]
	v_add_f32_dpp v112, v112, v112 row_half_mirror row_mask:0xf bank_mask:0xf bound_ctrl:1
	v_add_f32_dpp v114, v114, v114 row_half_mirror row_mask:0xf bank_mask:0xf bound_ctrl:1
	v_add_f32_dpp v116, v116, v116 row_half_mirror row_mask:0xf bank_mask:0xf bound_ctrl:1
	v_add_f32_dpp v118, v118, v118 row_half_mirror row_mask:0xf bank_mask:0xf bound_ctrl:1
	v_pk_fma_f32 v[20:21], v[20:21], v[178:179], v[252:253]
	v_pk_fma_f32 v[12:13], v[12:13], v[178:179], v[254:255]
	v_pk_fma_f32 v[22:23], v[22:23], v[180:181], v[194:195]
	v_pk_fma_f32 v[14:15], v[14:15], v[180:181], v[162:163]
	v_pk_mul_f32 v[16:17], v[16:17], v[174:175]
	v_pk_mul_f32 v[8:9], v[8:9], v[174:175]
	v_pk_mul_f32 v[18:19], v[18:19], v[176:177]
	v_pk_mul_f32 v[10:11], v[10:11], v[176:177]
	v_pk_mul_f32 v[4:5], v[4:5], v[178:179]
	v_pk_mul_f32 v[0:1], v[0:1], v[178:179]
	v_pk_mul_f32 v[6:7], v[6:7], v[180:181]
	v_pk_mul_f32 v[2:3], v[2:3], v[180:181]
	v_pk_fma_f32 v[28:29], v[190:191], v[112:113], v[28:29] op_sel_hi:[1,0,1] neg_lo:[0,1,0] neg_hi:[0,1,0]
	v_pk_fma_f32 v[24:25], v[190:191], v[114:115], v[24:25] op_sel_hi:[1,0,1] neg_lo:[0,1,0] neg_hi:[0,1,0]
	v_pk_fma_f32 v[30:31], v[192:193], v[112:113], v[30:31] op_sel_hi:[1,0,1] neg_lo:[0,1,0] neg_hi:[0,1,0]
	v_pk_fma_f32 v[26:27], v[192:193], v[114:115], v[26:27] op_sel_hi:[1,0,1] neg_lo:[0,1,0] neg_hi:[0,1,0]
	v_pk_fma_f32 v[20:21], v[130:131], v[112:113], v[20:21] op_sel_hi:[1,0,1] neg_lo:[0,1,0] neg_hi:[0,1,0]
	v_pk_fma_f32 v[12:13], v[130:131], v[114:115], v[12:13] op_sel_hi:[1,0,1] neg_lo:[0,1,0] neg_hi:[0,1,0]
	v_pk_fma_f32 v[22:23], v[132:133], v[112:113], v[22:23] op_sel_hi:[1,0,1] neg_lo:[0,1,0] neg_hi:[0,1,0]
	v_pk_fma_f32 v[14:15], v[132:133], v[114:115], v[14:15] op_sel_hi:[1,0,1] neg_lo:[0,1,0] neg_hi:[0,1,0]
	v_pk_fma_f32 v[16:17], v[190:191], v[116:117], v[16:17] op_sel_hi:[1,0,1] neg_lo:[0,1,0] neg_hi:[0,1,0]
	v_pk_fma_f32 v[8:9], v[190:191], v[118:119], v[8:9] op_sel_hi:[1,0,1] neg_lo:[0,1,0] neg_hi:[0,1,0]
	v_pk_fma_f32 v[18:19], v[192:193], v[116:117], v[18:19] op_sel_hi:[1,0,1] neg_lo:[0,1,0] neg_hi:[0,1,0]
	v_pk_fma_f32 v[10:11], v[192:193], v[118:119], v[10:11] op_sel_hi:[1,0,1] neg_lo:[0,1,0] neg_hi:[0,1,0]
	v_pk_fma_f32 v[4:5], v[130:131], v[116:117], v[4:5] op_sel_hi:[1,0,1] neg_lo:[0,1,0] neg_hi:[0,1,0]
	v_pk_fma_f32 v[0:1], v[130:131], v[118:119], v[0:1] op_sel_hi:[1,0,1] neg_lo:[0,1,0] neg_hi:[0,1,0]
	v_pk_fma_f32 v[6:7], v[132:133], v[116:117], v[6:7] op_sel_hi:[1,0,1] neg_lo:[0,1,0] neg_hi:[0,1,0]
	v_pk_fma_f32 v[2:3], v[132:133], v[118:119], v[2:3] op_sel_hi:[1,0,1] neg_lo:[0,1,0] neg_hi:[0,1,0]
	ds_read_b128 v[174:177], v33 offset:2304
	ds_read_b128 v[178:181], v33 offset:2320
	ds_read_b128 v[182:185], v33 offset:6400
	ds_read_b128 v[186:189], v33 offset:6416
	ds_read_b128 v[190:193], v33 offset:10496
	ds_read_b128 v[130:133], v33 offset:10512
	ds_read_b128 v[134:137], v33 offset:14592
	ds_read_b128 v[138:141], v33 offset:14608
	ds_read2_b32 v[142:143], v151 offset0:64 offset1:72
	s_waitcnt lgkmcnt(9)
; #define LAS __attribute__((address_space(3)))
; template <int CTRL> __device__ __forceinline__ float dpp_f(float x) { return __builtin_bit_cast(float, __builtin_amdgcn_mov_dpp(__builtin_bit_cast(int, x), CTRL, 0xf, 0xf, true)); }
; __device__ __forceinline__ float red8(float d) { d += dpp_f<0xB1>(d); d += dpp_f<0x4E>(d); d += dpp_f<0x141>(d); return d; }
; __device__ __forceinline__ void upd8(V8& S, const V8& w, const V8& b, const V8& k, float sa, float vv) {
;     const f32x2 sa2 = {sa, sa}, vv2 = {vv, vv};
; #pragma unroll
;     for (int i = 0; i < 4; ++i) { f32x2 t = vv2 * k.p[i]; t = sa2 * b.p[i] + t; S.p[i] = S.p[i] * w.p[i] + t; }
; }
; __device__ __forceinline__ void updp8(V8& S, const V8& w, const V8& b, float sa) {
;     const f32x2 sa2 = {sa, sa};
; #pragma unroll
;     for (int i = 0; i < 4; ++i) { const f32x2 t = sa2 * b.p[i]; S.p[i] = S.p[i] * w.p[i] + t; }
; }
; template <int MODE>
; __device__ __forceinline__ void scan_pair(LAS unsigned char* lds, CArgsP a, const ScanUnit u, int nch) {
;     ...
;             const LAS float* p = cb + t * 64 + 8 * ks;
;             const V8 w = ld8(p), kk = ld8(p + 1024), bb = ld8(p + 2048), kv = ld8(p + 3072);
;             const float va = cb[(5 * 16 + t) * 64 + vr0], vb = cb[(5 * 16 + t) * 64 + vr1];
;             float da = dot8(Sa, kk), db = dot8(Sb, kk);
;             da = red8(da); db = red8(db);
;             upd8(Sa, w, bb, kv, -da, va); upd8(Sb, w, bb, kv, -db, vb);
;             if (MODE == 1) {
;                 float pa = dot8(Pa, kk), pb = dot8(Pb, kk);
;                 pa = red8(pa); pb = red8(pb);
;                 updp8(Pa, w, bb, -pa); updp8(Pb, w, bb, -pb);
	v_pk_mul_f32 v[112:113], v[28:29], v[232:233]
	v_pk_mul_f32 v[114:115], v[24:25], v[232:233]
	v_pk_mul_f32 v[116:117], v[16:17], v[232:233]
	v_pk_mul_f32 v[118:119], v[8:9], v[232:233]
	v_pk_fma_f32 v[112:113], v[30:31], v[234:235], v[112:113]
	v_pk_fma_f32 v[114:115], v[26:27], v[234:235], v[114:115]
	v_pk_fma_f32 v[116:117], v[18:19], v[234:235], v[116:117]
	v_pk_fma_f32 v[118:119], v[10:11], v[234:235], v[118:119]
	v_pk_fma_f32 v[112:113], v[20:21], v[236:237], v[112:113]
	v_pk_fma_f32 v[114:115], v[12:13], v[236:237], v[114:115]
	v_pk_fma_f32 v[116:117], v[4:5], v[236:237], v[116:117]
	v_pk_fma_f32 v[118:119], v[0:1], v[236:237], v[118:119]
	v_pk_fma_f32 v[112:113], v[22:23], v[238:239], v[112:113]
	v_pk_fma_f32 v[114:115], v[14:15], v[238:239], v[114:115]
	v_pk_fma_f32 v[116:117], v[6:7], v[238:239], v[116:117]
	v_pk_fma_f32 v[118:119], v[2:3], v[238:239], v[118:119]
	v_add_f32_e32 v112, v112, v113
	v_add_f32_e32 v114, v114, v115
	v_add_f32_e32 v116, v116, v117
	v_add_f32_e32 v118, v118, v119
	v_pk_mul_f32 v[252:253], v[166:167], v[248:249] op_sel_hi:[1,0]
	v_pk_mul_f32 v[254:255], v[166:167], v[248:249] op_sel:[0,1] op_sel_hi:[1,1]
	v_pk_mul_f32 v[194:195], v[168:169], v[248:249] op_sel_hi:[1,0]
	v_pk_mul_f32 v[162:163], v[168:169], v[248:249] op_sel:[0,1] op_sel_hi:[1,1]
	v_add_f32_dpp v112, v112, v112 quad_perm:[1,0,3,2] row_mask:0xf bank_mask:0xf bound_ctrl:1
	v_add_f32_dpp v114, v114, v114 quad_perm:[1,0,3,2] row_mask:0xf bank_mask:0xf bound_ctrl:1
	v_add_f32_dpp v116, v116, v116 quad_perm:[1,0,3,2] row_mask:0xf bank_mask:0xf bound_ctrl:1
	v_add_f32_dpp v118, v118, v118 quad_perm:[1,0,3,2] row_mask:0xf bank_mask:0xf bound_ctrl:1
	v_pk_fma_f32 v[28:29], v[28:29], v[224:225], v[252:253]
	v_pk_fma_f32 v[24:25], v[24:25], v[224:225], v[254:255]
	v_pk_fma_f32 v[30:31], v[30:31], v[226:227], v[194:195]
	v_pk_fma_f32 v[26:27], v[26:27], v[226:227], v[162:163]
	v_add_f32_dpp v112, v112, v112 quad_perm:[2,3,0,1] row_mask:0xf bank_mask:0xf bound_ctrl:1
	v_add_f32_dpp v114, v114, v114 quad_perm:[2,3,0,1] row_mask:0xf bank_mask:0xf bound_ctrl:1
	v_add_f32_dpp v116, v116, v116 quad_perm:[2,3,0,1] row_mask:0xf bank_mask:0xf bound_ctrl:1
	v_add_f32_dpp v118, v118, v118 quad_perm:[2,3,0,1] row_mask:0xf bank_mask:0xf bound_ctrl:1
	v_pk_mul_f32 v[252:253], v[170:171], v[248:249] op_sel_hi:[1,0]
	v_pk_mul_f32 v[254:255], v[170:171], v[248:249] op_sel:[0,1] op_sel_hi:[1,1]
	v_pk_mul_f32 v[194:195], v[172:173], v[248:249] op_sel_hi:[1,0]
	v_pk_mul_f32 v[162:163], v[172:173], v[248:249] op_sel:[0,1] op_sel_hi:[1,1]
	v_add_f32_dpp v112, v112, v112 row_half_mirror row_mask:0xf bank_mask:0xf bound_ctrl:1
	v_add_f32_dpp v114, v114, v114 row_half_mirror row_mask:0xf bank_mask:0xf bound_ctrl:1
	v_add_f32_dpp v116, v116, v116 row_half_mirror row_mask:0xf bank_mask:0xf bound_ctrl:1
	v_add_f32_dpp v118, v118, v118 row_half_mirror row_mask:0xf bank_mask:0xf bound_ctrl:1
	v_pk_fma_f32 v[20:21], v[20:21], v[228:229], v[252:253]
	v_pk_fma_f32 v[12:13], v[12:13], v[228:229], v[254:255]
	v_pk_fma_f32 v[22:23], v[22:23], v[230:231], v[194:195]
	v_pk_fma_f32 v[14:15], v[14:15], v[230:231], v[162:163]
	v_pk_mul_f32 v[16:17], v[16:17], v[224:225]
	v_pk_mul_f32 v[8:9], v[8:9], v[224:225]
	v_pk_mul_f32 v[18:19], v[18:19], v[226:227]
	v_pk_mul_f32 v[10:11], v[10:11], v[226:227]
	v_pk_mul_f32 v[4:5], v[4:5], v[228:229]
	v_pk_mul_f32 v[0:1], v[0:1], v[228:229]
	v_pk_mul_f32 v[6:7], v[6:7], v[230:231]
	v_pk_mul_f32 v[2:3], v[2:3], v[230:231]
	v_pk_fma_f32 v[28:29], v[240:241], v[112:113], v[28:29] op_sel_hi:[1,0,1] neg_lo:[0,1,0] neg_hi:[0,1,0]
	v_pk_fma_f32 v[24:25], v[240:241], v[114:115], v[24:25] op_sel_hi:[1,0,1] neg_lo:[0,1,0] neg_hi:[0,1,0]
	v_pk_fma_f32 v[30:31], v[242:243], v[112:113], v[30:31] op_sel_hi:[1,0,1] neg_lo:[0,1,0] neg_hi:[0,1,0]
	v_pk_fma_f32 v[26:27], v[242:243], v[114:115], v[26:27] op_sel_hi:[1,0,1] neg_lo:[0,1,0] neg_hi:[0,1,0]
	v_pk_fma_f32 v[20:21], v[244:245], v[112:113], v[20:21] op_sel_hi:[1,0,1] neg_lo:[0,1,0] neg_hi:[0,1,0]
	v_pk_fma_f32 v[12:13], v[244:245], v[114:115], v[12:13] op_sel_hi:[1,0,1] neg_lo:[0,1,0] neg_hi:[0,1,0]
	v_pk_fma_f32 v[22:23], v[246:247], v[112:113], v[22:23] op_sel_hi:[1,0,1] neg_lo:[0,1,0] neg_hi:[0,1,0]
	v_pk_fma_f32 v[14:15], v[246:247], v[114:115], v[14:15] op_sel_hi:[1,0,1] neg_lo:[0,1,0] neg_hi:[0,1,0]
	v_pk_fma_f32 v[16:17], v[240:241], v[116:117], v[16:17] op_sel_hi:[1,0,1] neg_lo:[0,1,0] neg_hi:[0,1,0]
	v_pk_fma_f32 v[8:9], v[240:241], v[118:119], v[8:9] op_sel_hi:[1,0,1] neg_lo:[0,1,0] neg_hi:[0,1,0]
	v_pk_fma_f32 v[18:19], v[242:243], v[116:117], v[18:19] op_sel_hi:[1,0,1] neg_lo:[0,1,0] neg_hi:[0,1,0]
	v_pk_fma_f32 v[10:11], v[242:243], v[118:119], v[10:11] op_sel_hi:[1,0,1] neg_lo:[0,1,0] neg_hi:[0,1,0]
	v_pk_fma_f32 v[4:5], v[244:245], v[116:117], v[4:5] op_sel_hi:[1,0,1] neg_lo:[0,1,0] neg_hi:[0,1,0]
	v_pk_fma_f32 v[0:1], v[244:245], v[118:119], v[0:1] op_sel_hi:[1,0,1] neg_lo:[0,1,0] neg_hi:[0,1,0]
	v_pk_fma_f32 v[6:7], v[246:247], v[116:117], v[6:7] op_sel_hi:[1,0,1] neg_lo:[0,1,0] neg_hi:[0,1,0]
	v_pk_fma_f32 v[2:3], v[246:247], v[118:119], v[2:3] op_sel_hi:[1,0,1] neg_lo:[0,1,0] neg_hi:[0,1,0]
	ds_read_b128 v[224:227], v33 offset:2560
	ds_read_b128 v[228:231], v33 offset:2576
	ds_read_b128 v[232:235], v33 offset:6656
	ds_read_b128 v[236:239], v33 offset:6672
	ds_read_b128 v[240:243], v33 offset:10752
	ds_read_b128 v[244:247], v33 offset:10768
	ds_read_b128 v[166:169], v33 offset:14848
	ds_read_b128 v[170:173], v33 offset:14864
	ds_read2_b32 v[248:249], v151 offset0:128 offset1:136
	s_waitcnt lgkmcnt(9)
; #define LAS __attribute__((address_space(3)))
; __device__ __forceinline__ float red8(float d) { d += dpp_f<0xB1>(d); d += dpp_f<0x4E>(d); d += dpp_f<0x141>(d); return d; }
; __device__ __forceinline__ void updp8(V8& S, const V8& w, const V8& b, float sa) {
;     const f32x2 sa2 = {sa, sa};
; #pragma unroll
;     for (int i = 0; i < 4; ++i) { const f32x2 t = sa2 * b.p[i]; S.p[i] = S.p[i] * w.p[i] + t; }
; }
; template <int MODE>
; __device__ __forceinline__ void scan_pair(LAS unsigned char* lds, CArgsP a, const ScanUnit u, int nch) {
;     ...
;             const LAS float* p = cb + t * 64 + 8 * ks;
;             const V8 w = ld8(p), kk = ld8(p + 1024), bb = ld8(p + 2048), kv = ld8(p + 3072);
;             const float va = cb[(5 * 16 + t) * 64 + vr0], vb = cb[(5 * 16 + t) * 64 + vr1];
;             float da = dot8(Sa, kk), db = dot8(Sb, kk);
;             da = red8(da); db = red8(db);
;             upd8(Sa, w, bb, kv, -da, va); upd8(Sb, w, bb, kv, -db, vb);
;             if (MODE == 1) {
;                 float pa = dot8(Pa, kk), pb = dot8(Pb, kk);
;                 pa = red8(pa); pb = red8(pb);
;                 updp8(Pa, w, bb, -pa); updp8(Pb, w, bb, -pb);
	v_pk_mul_f32 v[112:113], v[28:29], v[182:183]
	v_pk_mul_f32 v[114:115], v[24:25], v[182:183]
	v_pk_mul_f32 v[116:117], v[16:17], v[182:183]
	v_pk_mul_f32 v[118:119], v[8:9], v[182:183]
	v_pk_fma_f32 v[112:113], v[30:31], v[184:185], v[112:113]
	v_pk_fma_f32 v[114:115], v[26:27], v[184:185], v[114:115]
	v_pk_fma_f32 v[116:117], v[18:19], v[184:185], v[116:117]
	v_pk_fma_f32 v[118:119], v[10:11], v[184:185], v[118:119]
	v_pk_fma_f32 v[112:113], v[20:21], v[186:187], v[112:113]
	v_pk_fma_f32 v[114:115], v[12:13], v[186:187], v[114:115]
	v_pk_fma_f32 v[116:117], v[4:5], v[186:187], v[116:117]
	v_pk_fma_f32 v[118:119], v[0:1], v[186:187], v[118:119]
	v_pk_fma_f32 v[112:113], v[22:23], v[188:189], v[112:113]
	v_pk_fma_f32 v[114:115], v[14:15], v[188:189], v[114:115]
	v_pk_fma_f32 v[116:117], v[6:7], v[188:189], v[116:117]
	v_pk_fma_f32 v[118:119], v[2:3], v[188:189], v[118:119]
	v_add_f32_e32 v112, v112, v113
	v_add_f32_e32 v114, v114, v115
	v_add_f32_e32 v116, v116, v117
	v_add_f32_e32 v118, v118, v119
	v_pk_mul_f32 v[252:253], v[134:135], v[142:143] op_sel_hi:[1,0]
	v_pk_mul_f32 v[254:255], v[134:135], v[142:143] op_sel:[0,1] op_sel_hi:[1,1]
	v_pk_mul_f32 v[194:195], v[136:137], v[142:143] op_sel_hi:[1,0]
	v_pk_mul_f32 v[162:163], v[136:137], v[142:143] op_sel:[0,1] op_sel_hi:[1,1]
	v_add_f32_dpp v112, v112, v112 quad_perm:[1,0,3,2] row_mask:0xf bank_mask:0xf bound_ctrl:1
	v_add_f32_dpp v114, v114, v114 quad_perm:[1,0,3,2] row_mask:0xf bank_mask:0xf bound_ctrl:1
	v_add_f32_dpp v116, v116, v116 quad_perm:[1,0,3,2] row_mask:0xf bank_mask:0xf bound_ctrl:1
	v_add_f32_dpp v118, v118, v118 quad_perm:[1,0,3,2] row_mask:0xf bank_mask:0xf bound_ctrl:1
	v_pk_fma_f32 v[28:29], v[28:29], v[174:175], v[252:253]
	v_pk_fma_f32 v[24:25], v[24:25], v[174:175], v[254:255]
	v_pk_fma_f32 v[30:31], v[30:31], v[176:177], v[194:195]
	v_pk_fma_f32 v[26:27], v[26:27], v[176:177], v[162:163]
	v_add_f32_dpp v112, v112, v112 quad_perm:[2,3,0,1] row_mask:0xf bank_mask:0xf bound_ctrl:1
	v_add_f32_dpp v114, v114, v114 quad_perm:[2,3,0,1] row_mask:0xf bank_mask:0xf bound_ctrl:1
	v_add_f32_dpp v116, v116, v116 quad_perm:[2,3,0,1] row_mask:0xf bank_mask:0xf bound_ctrl:1
	v_add_f32_dpp v118, v118, v118 quad_perm:[2,3,0,1] row_mask:0xf bank_mask:0xf bound_ctrl:1
	v_pk_mul_f32 v[252:253], v[138:139], v[142:143] op_sel_hi:[1,0]
	v_pk_mul_f32 v[254:255], v[138:139], v[142:143] op_sel:[0,1] op_sel_hi:[1,1]
	v_pk_mul_f32 v[194:195], v[140:141], v[142:143] op_sel_hi:[1,0]
	v_pk_mul_f32 v[162:163], v[140:141], v[142:143] op_sel:[0,1] op_sel_hi:[1,1]
	v_add_f32_dpp v112, v112, v112 row_half_mirror row_mask:0xf bank_mask:0xf bound_ctrl:1
	v_add_f32_dpp v114, v114, v114 row_half_mirror row_mask:0xf bank_mask:0xf bound_ctrl:1
	v_add_f32_dpp v116, v116, v116 row_half_mirror row_mask:0xf bank_mask:0xf bound_ctrl:1
	v_add_f32_dpp v118, v118, v118 row_half_mirror row_mask:0xf bank_mask:0xf bound_ctrl:1
	v_pk_fma_f32 v[20:21], v[20:21], v[178:179], v[252:253]
	v_pk_fma_f32 v[12:13], v[12:13], v[178:179], v[254:255]
	v_pk_fma_f32 v[22:23], v[22:23], v[180:181], v[194:195]
	v_pk_fma_f32 v[14:15], v[14:15], v[180:181], v[162:163]
	v_pk_mul_f32 v[16:17], v[16:17], v[174:175]
	v_pk_mul_f32 v[8:9], v[8:9], v[174:175]
	v_pk_mul_f32 v[18:19], v[18:19], v[176:177]
	v_pk_mul_f32 v[10:11], v[10:11], v[176:177]
	v_pk_mul_f32 v[4:5], v[4:5], v[178:179]
	v_pk_mul_f32 v[0:1], v[0:1], v[178:179]
	v_pk_mul_f32 v[6:7], v[6:7], v[180:181]
	v_pk_mul_f32 v[2:3], v[2:3], v[180:181]
	v_pk_fma_f32 v[28:29], v[190:191], v[112:113], v[28:29] op_sel_hi:[1,0,1] neg_lo:[0,1,0] neg_hi:[0,1,0]
	v_pk_fma_f32 v[24:25], v[190:191], v[114:115], v[24:25] op_sel_hi:[1,0,1] neg_lo:[0,1,0] neg_hi:[0,1,0]
	v_pk_fma_f32 v[30:31], v[192:193], v[112:113], v[30:31] op_sel_hi:[1,0,1] neg_lo:[0,1,0] neg_hi:[0,1,0]
	v_pk_fma_f32 v[26:27], v[192:193], v[114:115], v[26:27] op_sel_hi:[1,0,1] neg_lo:[0,1,0] neg_hi:[0,1,0]
	v_pk_fma_f32 v[20:21], v[130:131], v[112:113], v[20:21] op_sel_hi:[1,0,1] neg_lo:[0,1,0] neg_hi:[0,1,0]
	v_pk_fma_f32 v[12:13], v[130:131], v[114:115], v[12:13] op_sel_hi:[1,0,1] neg_lo:[0,1,0] neg_hi:[0,1,0]
	v_pk_fma_f32 v[22:23], v[132:133], v[112:113], v[22:23] op_sel_hi:[1,0,1] neg_lo:[0,1,0] neg_hi:[0,1,0]
	v_pk_fma_f32 v[14:15], v[132:133], v[114:115], v[14:15] op_sel_hi:[1,0,1] neg_lo:[0,1,0] neg_hi:[0,1,0]
	v_pk_fma_f32 v[16:17], v[190:191], v[116:117], v[16:17] op_sel_hi:[1,0,1] neg_lo:[0,1,0] neg_hi:[0,1,0]
	v_pk_fma_f32 v[8:9], v[190:191], v[118:119], v[8:9] op_sel_hi:[1,0,1] neg_lo:[0,1,0] neg_hi:[0,1,0]
	v_pk_fma_f32 v[18:19], v[192:193], v[116:117], v[18:19] op_sel_hi:[1,0,1] neg_lo:[0,1,0] neg_hi:[0,1,0]
	v_pk_fma_f32 v[10:11], v[192:193], v[118:119], v[10:11] op_sel_hi:[1,0,1] neg_lo:[0,1,0] neg_hi:[0,1,0]
	v_pk_fma_f32 v[4:5], v[130:131], v[116:117], v[4:5] op_sel_hi:[1,0,1] neg_lo:[0,1,0] neg_hi:[0,1,0]
	v_pk_fma_f32 v[0:1], v[130:131], v[118:119], v[0:1] op_sel_hi:[1,0,1] neg_lo:[0,1,0] neg_hi:[0,1,0]
	v_pk_fma_f32 v[6:7], v[132:133], v[116:117], v[6:7] op_sel_hi:[1,0,1] neg_lo:[0,1,0] neg_hi:[0,1,0]
	v_pk_fma_f32 v[2:3], v[132:133], v[118:119], v[2:3] op_sel_hi:[1,0,1] neg_lo:[0,1,0] neg_hi:[0,1,0]
	ds_read_b128 v[174:177], v33 offset:2816
	ds_read_b128 v[178:181], v33 offset:2832
	ds_read_b128 v[182:185], v33 offset:6912
	ds_read_b128 v[186:189], v33 offset:6928
	ds_read_b128 v[190:193], v33 offset:11008
	ds_read_b128 v[130:133], v33 offset:11024
	ds_read_b128 v[134:137], v33 offset:15104
	ds_read_b128 v[138:141], v33 offset:15120
	ds_read2_b32 v[142:143], v151 offset0:192 offset1:200
	s_waitcnt lgkmcnt(9)
; #define LAS __attribute__((address_space(3)))
; template <int CTRL> __device__ __forceinline__ float dpp_f(float x) { return __builtin_bit_cast(float, __builtin_amdgcn_mov_dpp(__builtin_bit_cast(int, x), CTRL, 0xf, 0xf, true)); }
; __device__ __forceinline__ float red8(float d) { d += dpp_f<0xB1>(d); d += dpp_f<0x4E>(d); d += dpp_f<0x141>(d); return d; }
; __device__ __forceinline__ void upd8(V8& S, const V8& w, const V8& b, const V8& k, float sa, float vv) {
;     const f32x2 sa2 = {sa, sa}, vv2 = {vv, vv};
; #pragma unroll
;     for (int i = 0; i < 4; ++i) { f32x2 t = vv2 * k.p[i]; t = sa2 * b.p[i] + t; S.p[i] = S.p[i] * w.p[i] + t; }
; }
; __device__ __forceinline__ void updp8(V8& S, const V8& w, const V8& b, float sa) {
;     const f32x2 sa2 = {sa, sa};
; #pragma unroll
;     for (int i = 0; i < 4; ++i) { const f32x2 t = sa2 * b.p[i]; S.p[i] = S.p[i] * w.p[i] + t; }
; }
; template <int MODE>
; __device__ __forceinline__ void scan_pair(LAS unsigned char* lds, CArgsP a, const ScanUnit u, int nch) {
;     ...
;             const LAS float* p = cb + t * 64 + 8 * ks;
;             const V8 w = ld8(p), kk = ld8(p + 1024), bb = ld8(p + 2048), kv = ld8(p + 3072);
;             const float va = cb[(5 * 16 + t) * 64 + vr0], vb = cb[(5 * 16 + t) * 64 + vr1];
;             float da = dot8(Sa, kk), db = dot8(Sb, kk);
;             da = red8(da); db = red8(db);
;             upd8(Sa, w, bb, kv, -da, va); upd8(Sb, w, bb, kv, -db, vb);
;             if (MODE == 1) {
;                 float pa = dot8(Pa, kk), pb = dot8(Pb, kk);
;                 pa = red8(pa); pb = red8(pb);
;                 updp8(Pa, w, bb, -pa); updp8(Pb, w, bb, -pb);
	v_pk_mul_f32 v[112:113], v[28:29], v[232:233]
	v_pk_mul_f32 v[114:115], v[24:25], v[232:233]
	v_pk_mul_f32 v[116:117], v[16:17], v[232:233]
	v_pk_mul_f32 v[118:119], v[8:9], v[232:233]
	v_pk_fma_f32 v[112:113], v[30:31], v[234:235], v[112:113]
	v_pk_fma_f32 v[114:115], v[26:27], v[234:235], v[114:115]
	v_pk_fma_f32 v[116:117], v[18:19], v[234:235], v[116:117]
	v_pk_fma_f32 v[118:119], v[10:11], v[234:235], v[118:119]
	v_pk_fma_f32 v[112:113], v[20:21], v[236:237], v[112:113]
	v_pk_fma_f32 v[114:115], v[12:13], v[236:237], v[114:115]
	v_pk_fma_f32 v[116:117], v[4:5], v[236:237], v[116:117]
	v_pk_fma_f32 v[118:119], v[0:1], v[236:237], v[118:119]
	v_pk_fma_f32 v[112:113], v[22:23], v[238:239], v[112:113]
	v_pk_fma_f32 v[114:115], v[14:15], v[238:239], v[114:115]
	v_pk_fma_f32 v[116:117], v[6:7], v[238:239], v[116:117]
	v_pk_fma_f32 v[118:119], v[2:3], v[238:239], v[118:119]
	v_add_f32_e32 v112, v112, v113
	v_add_f32_e32 v114, v114, v115
	v_add_f32_e32 v116, v116, v117
	v_add_f32_e32 v118, v118, v119
	v_pk_mul_f32 v[252:253], v[166:167], v[248:249] op_sel_hi:[1,0]
	v_pk_mul_f32 v[254:255], v[166:167], v[248:249] op_sel:[0,1] op_sel_hi:[1,1]
	v_pk_mul_f32 v[194:195], v[168:169], v[248:249] op_sel_hi:[1,0]
	v_pk_mul_f32 v[162:163], v[168:169], v[248:249] op_sel:[0,1] op_sel_hi:[1,1]
	v_add_f32_dpp v112, v112, v112 quad_perm:[1,0,3,2] row_mask:0xf bank_mask:0xf bound_ctrl:1
	v_add_f32_dpp v114, v114, v114 quad_perm:[1,0,3,2] row_mask:0xf bank_mask:0xf bound_ctrl:1
	v_add_f32_dpp v116, v116, v116 quad_perm:[1,0,3,2] row_mask:0xf bank_mask:0xf bound_ctrl:1
	v_add_f32_dpp v118, v118, v118 quad_perm:[1,0,3,2] row_mask:0xf bank_mask:0xf bound_ctrl:1
	v_pk_fma_f32 v[28:29], v[28:29], v[224:225], v[252:253]
	v_pk_fma_f32 v[24:25], v[24:25], v[224:225], v[254:255]
	v_pk_fma_f32 v[30:31], v[30:31], v[226:227], v[194:195]
	v_pk_fma_f32 v[26:27], v[26:27], v[226:227], v[162:163]
	v_add_f32_dpp v112, v112, v112 quad_perm:[2,3,0,1] row_mask:0xf bank_mask:0xf bound_ctrl:1
	v_add_f32_dpp v114, v114, v114 quad_perm:[2,3,0,1] row_mask:0xf bank_mask:0xf bound_ctrl:1
	v_add_f32_dpp v116, v116, v116 quad_perm:[2,3,0,1] row_mask:0xf bank_mask:0xf bound_ctrl:1
	v_add_f32_dpp v118, v118, v118 quad_perm:[2,3,0,1] row_mask:0xf bank_mask:0xf bound_ctrl:1
	v_pk_mul_f32 v[252:253], v[170:171], v[248:249] op_sel_hi:[1,0]
	v_pk_mul_f32 v[254:255], v[170:171], v[248:249] op_sel:[0,1] op_sel_hi:[1,1]
	v_pk_mul_f32 v[194:195], v[172:173], v[248:249] op_sel_hi:[1,0]
	v_pk_mul_f32 v[162:163], v[172:173], v[248:249] op_sel:[0,1] op_sel_hi:[1,1]
	v_add_f32_dpp v112, v112, v112 row_half_mirror row_mask:0xf bank_mask:0xf bound_ctrl:1
	v_add_f32_dpp v114, v114, v114 row_half_mirror row_mask:0xf bank_mask:0xf bound_ctrl:1
	v_add_f32_dpp v116, v116, v116 row_half_mirror row_mask:0xf bank_mask:0xf bound_ctrl:1
	v_add_f32_dpp v118, v118, v118 row_half_mirror row_mask:0xf bank_mask:0xf bound_ctrl:1
	v_pk_fma_f32 v[20:21], v[20:21], v[228:229], v[252:253]
	v_pk_fma_f32 v[12:13], v[12:13], v[228:229], v[254:255]
	v_pk_fma_f32 v[22:23], v[22:23], v[230:231], v[194:195]
	v_pk_fma_f32 v[14:15], v[14:15], v[230:231], v[162:163]
	v_pk_mul_f32 v[16:17], v[16:17], v[224:225]
	v_pk_mul_f32 v[8:9], v[8:9], v[224:225]
	v_pk_mul_f32 v[18:19], v[18:19], v[226:227]
	v_pk_mul_f32 v[10:11], v[10:11], v[226:227]
	v_pk_mul_f32 v[4:5], v[4:5], v[228:229]
	v_pk_mul_f32 v[0:1], v[0:1], v[228:229]
	v_pk_mul_f32 v[6:7], v[6:7], v[230:231]
	v_pk_mul_f32 v[2:3], v[2:3], v[230:231]
	v_pk_fma_f32 v[28:29], v[240:241], v[112:113], v[28:29] op_sel_hi:[1,0,1] neg_lo:[0,1,0] neg_hi:[0,1,0]
	v_pk_fma_f32 v[24:25], v[240:241], v[114:115], v[24:25] op_sel_hi:[1,0,1] neg_lo:[0,1,0] neg_hi:[0,1,0]
	v_pk_fma_f32 v[30:31], v[242:243], v[112:113], v[30:31] op_sel_hi:[1,0,1] neg_lo:[0,1,0] neg_hi:[0,1,0]
	v_pk_fma_f32 v[26:27], v[242:243], v[114:115], v[26:27] op_sel_hi:[1,0,1] neg_lo:[0,1,0] neg_hi:[0,1,0]
	v_pk_fma_f32 v[20:21], v[244:245], v[112:113], v[20:21] op_sel_hi:[1,0,1] neg_lo:[0,1,0] neg_hi:[0,1,0]
	v_pk_fma_f32 v[12:13], v[244:245], v[114:115], v[12:13] op_sel_hi:[1,0,1] neg_lo:[0,1,0] neg_hi:[0,1,0]
	v_pk_fma_f32 v[22:23], v[246:247], v[112:113], v[22:23] op_sel_hi:[1,0,1] neg_lo:[0,1,0] neg_hi:[0,1,0]
	v_pk_fma_f32 v[14:15], v[246:247], v[114:115], v[14:15] op_sel_hi:[1,0,1] neg_lo:[0,1,0] neg_hi:[0,1,0]
	v_pk_fma_f32 v[16:17], v[240:241], v[116:117], v[16:17] op_sel_hi:[1,0,1] neg_lo:[0,1,0] neg_hi:[0,1,0]
	v_pk_fma_f32 v[8:9], v[240:241], v[118:119], v[8:9] op_sel_hi:[1,0,1] neg_lo:[0,1,0] neg_hi:[0,1,0]
	v_pk_fma_f32 v[18:19], v[242:243], v[116:117], v[18:19] op_sel_hi:[1,0,1] neg_lo:[0,1,0] neg_hi:[0,1,0]
	v_pk_fma_f32 v[10:11], v[242:243], v[118:119], v[10:11] op_sel_hi:[1,0,1] neg_lo:[0,1,0] neg_hi:[0,1,0]
	v_pk_fma_f32 v[4:5], v[244:245], v[116:117], v[4:5] op_sel_hi:[1,0,1] neg_lo:[0,1,0] neg_hi:[0,1,0]
	v_pk_fma_f32 v[0:1], v[244:245], v[118:119], v[0:1] op_sel_hi:[1,0,1] neg_lo:[0,1,0] neg_hi:[0,1,0]
	v_pk_fma_f32 v[6:7], v[246:247], v[116:117], v[6:7] op_sel_hi:[1,0,1] neg_lo:[0,1,0] neg_hi:[0,1,0]
	v_pk_fma_f32 v[2:3], v[246:247], v[118:119], v[2:3] op_sel_hi:[1,0,1] neg_lo:[0,1,0] neg_hi:[0,1,0]
	ds_read_b128 v[224:227], v33 offset:3072
	ds_read_b128 v[228:231], v33 offset:3088
	ds_read_b128 v[232:235], v33 offset:7168
	ds_read_b128 v[236:239], v33 offset:7184
	ds_read_b128 v[240:243], v33 offset:11264
	ds_read_b128 v[244:247], v33 offset:11280
	ds_read_b128 v[166:169], v33 offset:15360
	ds_read_b128 v[170:173], v33 offset:15376
	v_add_u32_e32 v151, 0x400, v151
	ds_read2_b32 v[248:249], v151 offset0:0 offset1:8
	s_waitcnt lgkmcnt(9)
; #define LAS __attribute__((address_space(3)))
; template <int CTRL> __device__ __forceinline__ float dpp_f(float x) { return __builtin_bit_cast(float, __builtin_amdgcn_mov_dpp(__builtin_bit_cast(int, x), CTRL, 0xf, 0xf, true)); }
; __device__ __forceinline__ float red8(float d) { d += dpp_f<0xB1>(d); d += dpp_f<0x4E>(d); d += dpp_f<0x141>(d); return d; }
; __device__ __forceinline__ void upd8(V8& S, const V8& w, const V8& b, const V8& k, float sa, float vv) {
;     const f32x2 sa2 = {sa, sa}, vv2 = {vv, vv};
; #pragma unroll
;     for (int i = 0; i < 4; ++i) { f32x2 t = vv2 * k.p[i]; t = sa2 * b.p[i] + t; S.p[i] = S.p[i] * w.p[i] + t; }
; }
; __device__ __forceinline__ void updp8(V8& S, const V8& w, const V8& b, float sa) {
;     const f32x2 sa2 = {sa, sa};
; #pragma unroll
;     for (int i = 0; i < 4; ++i) { const f32x2 t = sa2 * b.p[i]; S.p[i] = S.p[i] * w.p[i] + t; }
; }
; template <int MODE>
; __device__ __forceinline__ void scan_pair(LAS unsigned char* lds, CArgsP a, const ScanUnit u, int nch) {
;     ...
;             const LAS float* p = cb + t * 64 + 8 * ks;
;             const V8 w = ld8(p), kk = ld8(p + 1024), bb = ld8(p + 2048), kv = ld8(p + 3072);
;             const float va = cb[(5 * 16 + t) * 64 + vr0], vb = cb[(5 * 16 + t) * 64 + vr1];
;             float da = dot8(Sa, kk), db = dot8(Sb, kk);
;             da = red8(da); db = red8(db);
;             upd8(Sa, w, bb, kv, -da, va); upd8(Sb, w, bb, kv, -db, vb);
;             if (MODE == 1) {
;                 float pa = dot8(Pa, kk), pb = dot8(Pb, kk);
;                 pa = red8(pa); pb = red8(pb);
;                 updp8(Pa, w, bb, -pa); updp8(Pb, w, bb, -pb);
	v_pk_mul_f32 v[112:113], v[28:29], v[182:183]
	v_pk_mul_f32 v[114:115], v[24:25], v[182:183]
	v_pk_mul_f32 v[116:117], v[16:17], v[182:183]
	v_pk_mul_f32 v[118:119], v[8:9], v[182:183]
	v_pk_fma_f32 v[112:113], v[30:31], v[184:185], v[112:113]
	v_pk_fma_f32 v[114:115], v[26:27], v[184:185], v[114:115]
	v_pk_fma_f32 v[116:117], v[18:19], v[184:185], v[116:117]
	v_pk_fma_f32 v[118:119], v[10:11], v[184:185], v[118:119]
	v_pk_fma_f32 v[112:113], v[20:21], v[186:187], v[112:113]
	v_pk_fma_f32 v[114:115], v[12:13], v[186:187], v[114:115]
	v_pk_fma_f32 v[116:117], v[4:5], v[186:187], v[116:117]
	v_pk_fma_f32 v[118:119], v[0:1], v[186:187], v[118:119]
	v_pk_fma_f32 v[112:113], v[22:23], v[188:189], v[112:113]
	v_pk_fma_f32 v[114:115], v[14:15], v[188:189], v[114:115]
	v_pk_fma_f32 v[116:117], v[6:7], v[188:189], v[116:117]
	v_pk_fma_f32 v[118:119], v[2:3], v[188:189], v[118:119]
	v_add_f32_e32 v112, v112, v113
	v_add_f32_e32 v114, v114, v115
	v_add_f32_e32 v116, v116, v117
	v_add_f32_e32 v118, v118, v119
	v_pk_mul_f32 v[252:253], v[134:135], v[142:143] op_sel_hi:[1,0]
	v_pk_mul_f32 v[254:255], v[134:135], v[142:143] op_sel:[0,1] op_sel_hi:[1,1]
	v_pk_mul_f32 v[194:195], v[136:137], v[142:143] op_sel_hi:[1,0]
	v_pk_mul_f32 v[162:163], v[136:137], v[142:143] op_sel:[0,1] op_sel_hi:[1,1]
	v_add_f32_dpp v112, v112, v112 quad_perm:[1,0,3,2] row_mask:0xf bank_mask:0xf bound_ctrl:1
	v_add_f32_dpp v114, v114, v114 quad_perm:[1,0,3,2] row_mask:0xf bank_mask:0xf bound_ctrl:1
	v_add_f32_dpp v116, v116, v116 quad_perm:[1,0,3,2] row_mask:0xf bank_mask:0xf bound_ctrl:1
	v_add_f32_dpp v118, v118, v118 quad_perm:[1,0,3,2] row_mask:0xf bank_mask:0xf bound_ctrl:1
	v_pk_fma_f32 v[28:29], v[28:29], v[174:175], v[252:253]
	v_pk_fma_f32 v[24:25], v[24:25], v[174:175], v[254:255]
	v_pk_fma_f32 v[30:31], v[30:31], v[176:177], v[194:195]
	v_pk_fma_f32 v[26:27], v[26:27], v[176:177], v[162:163]
	v_add_f32_dpp v112, v112, v112 quad_perm:[2,3,0,1] row_mask:0xf bank_mask:0xf bound_ctrl:1
	v_add_f32_dpp v114, v114, v114 quad_perm:[2,3,0,1] row_mask:0xf bank_mask:0xf bound_ctrl:1
	v_add_f32_dpp v116, v116, v116 quad_perm:[2,3,0,1] row_mask:0xf bank_mask:0xf bound_ctrl:1
	v_add_f32_dpp v118, v118, v118 quad_perm:[2,3,0,1] row_mask:0xf bank_mask:0xf bound_ctrl:1
	v_pk_mul_f32 v[252:253], v[138:139], v[142:143] op_sel_hi:[1,0]
	v_pk_mul_f32 v[254:255], v[138:139], v[142:143] op_sel:[0,1] op_sel_hi:[1,1]
	v_pk_mul_f32 v[194:195], v[140:141], v[142:143] op_sel_hi:[1,0]
	v_pk_mul_f32 v[162:163], v[140:141], v[142:143] op_sel:[0,1] op_sel_hi:[1,1]
	v_add_f32_dpp v112, v112, v112 row_half_mirror row_mask:0xf bank_mask:0xf bound_ctrl:1
	v_add_f32_dpp v114, v114, v114 row_half_mirror row_mask:0xf bank_mask:0xf bound_ctrl:1
	v_add_f32_dpp v116, v116, v116 row_half_mirror row_mask:0xf bank_mask:0xf bound_ctrl:1
	v_add_f32_dpp v118, v118, v118 row_half_mirror row_mask:0xf bank_mask:0xf bound_ctrl:1
	v_pk_fma_f32 v[20:21], v[20:21], v[178:179], v[252:253]
	v_pk_fma_f32 v[12:13], v[12:13], v[178:179], v[254:255]
	v_pk_fma_f32 v[22:23], v[22:23], v[180:181], v[194:195]
	v_pk_fma_f32 v[14:15], v[14:15], v[180:181], v[162:163]
	v_pk_mul_f32 v[16:17], v[16:17], v[174:175]
	v_pk_mul_f32 v[8:9], v[8:9], v[174:175]
	v_pk_mul_f32 v[18:19], v[18:19], v[176:177]
	v_pk_mul_f32 v[10:11], v[10:11], v[176:177]
	v_pk_mul_f32 v[4:5], v[4:5], v[178:179]
	v_pk_mul_f32 v[0:1], v[0:1], v[178:179]
	v_pk_mul_f32 v[6:7], v[6:7], v[180:181]
	v_pk_mul_f32 v[2:3], v[2:3], v[180:181]
	v_pk_fma_f32 v[28:29], v[190:191], v[112:113], v[28:29] op_sel_hi:[1,0,1] neg_lo:[0,1,0] neg_hi:[0,1,0]
	v_pk_fma_f32 v[24:25], v[190:191], v[114:115], v[24:25] op_sel_hi:[1,0,1] neg_lo:[0,1,0] neg_hi:[0,1,0]
	v_pk_fma_f32 v[30:31], v[192:193], v[112:113], v[30:31] op_sel_hi:[1,0,1] neg_lo:[0,1,0] neg_hi:[0,1,0]
	v_pk_fma_f32 v[26:27], v[192:193], v[114:115], v[26:27] op_sel_hi:[1,0,1] neg_lo:[0,1,0] neg_hi:[0,1,0]
	v_pk_fma_f32 v[20:21], v[130:131], v[112:113], v[20:21] op_sel_hi:[1,0,1] neg_lo:[0,1,0] neg_hi:[0,1,0]
	v_pk_fma_f32 v[12:13], v[130:131], v[114:115], v[12:13] op_sel_hi:[1,0,1] neg_lo:[0,1,0] neg_hi:[0,1,0]
	v_pk_fma_f32 v[22:23], v[132:133], v[112:113], v[22:23] op_sel_hi:[1,0,1] neg_lo:[0,1,0] neg_hi:[0,1,0]
	v_pk_fma_f32 v[14:15], v[132:133], v[114:115], v[14:15] op_sel_hi:[1,0,1] neg_lo:[0,1,0] neg_hi:[0,1,0]
	v_pk_fma_f32 v[16:17], v[190:191], v[116:117], v[16:17] op_sel_hi:[1,0,1] neg_lo:[0,1,0] neg_hi:[0,1,0]
	v_pk_fma_f32 v[8:9], v[190:191], v[118:119], v[8:9] op_sel_hi:[1,0,1] neg_lo:[0,1,0] neg_hi:[0,1,0]
	v_pk_fma_f32 v[18:19], v[192:193], v[116:117], v[18:19] op_sel_hi:[1,0,1] neg_lo:[0,1,0] neg_hi:[0,1,0]
	v_pk_fma_f32 v[10:11], v[192:193], v[118:119], v[10:11] op_sel_hi:[1,0,1] neg_lo:[0,1,0] neg_hi:[0,1,0]
	v_pk_fma_f32 v[4:5], v[130:131], v[116:117], v[4:5] op_sel_hi:[1,0,1] neg_lo:[0,1,0] neg_hi:[0,1,0]
	v_pk_fma_f32 v[0:1], v[130:131], v[118:119], v[0:1] op_sel_hi:[1,0,1] neg_lo:[0,1,0] neg_hi:[0,1,0]
	v_pk_fma_f32 v[6:7], v[132:133], v[116:117], v[6:7] op_sel_hi:[1,0,1] neg_lo:[0,1,0] neg_hi:[0,1,0]
	v_pk_fma_f32 v[2:3], v[132:133], v[118:119], v[2:3] op_sel_hi:[1,0,1] neg_lo:[0,1,0] neg_hi:[0,1,0]
	ds_read_b128 v[174:177], v33 offset:3328
	ds_read_b128 v[178:181], v33 offset:3344
	ds_read_b128 v[182:185], v33 offset:7424
	ds_read_b128 v[186:189], v33 offset:7440
	ds_read_b128 v[190:193], v33 offset:11520
	ds_read_b128 v[130:133], v33 offset:11536
	ds_read_b128 v[134:137], v33 offset:15616
	ds_read_b128 v[138:141], v33 offset:15632
	ds_read2_b32 v[142:143], v151 offset0:64 offset1:72
	s_waitcnt lgkmcnt(9)
; #define LAS __attribute__((address_space(3)))
; __device__ __forceinline__ float red8(float d) { d += dpp_f<0xB1>(d); d += dpp_f<0x4E>(d); d += dpp_f<0x141>(d); return d; }
; template <int MODE>
; __device__ __forceinline__ void scan_pair(LAS unsigned char* lds, CArgsP a, const ScanUnit u, int nch) {
;     ...
;             const LAS float* p = cb + t * 64 + 8 * ks;
;             const V8 w = ld8(p), kk = ld8(p + 1024), bb = ld8(p + 2048), kv = ld8(p + 3072);
;             const float va = cb[(5 * 16 + t) * 64 + vr0], vb = cb[(5 * 16 + t) * 64 + vr1];
;             float da = dot8(Sa, kk), db = dot8(Sb, kk);
;             da = red8(da); db = red8(db);
;             upd8(Sa, w, bb, kv, -da, va); upd8(Sb, w, bb, kv, -db, vb);
;             if (MODE == 1) {
;                 float pa = dot8(Pa, kk), pb = dot8(Pb, kk);
;                 pa = red8(pa); pb = red8(pb);
;                 updp8(Pa, w, bb, -pa); updp8(Pb, w, bb, -pb);
	v_pk_mul_f32 v[112:113], v[28:29], v[232:233]
	v_pk_mul_f32 v[114:115], v[24:25], v[232:233]
	v_pk_mul_f32 v[116:117], v[16:17], v[232:233]
	v_pk_mul_f32 v[118:119], v[8:9], v[232:233]
	v_pk_fma_f32 v[112:113], v[30:31], v[234:235], v[112:113]
	v_pk_fma_f32 v[114:115], v[26:27], v[234:235], v[114:115]
	v_pk_fma_f32 v[116:117], v[18:19], v[234:235], v[116:117]
	v_pk_fma_f32 v[118:119], v[10:11], v[234:235], v[118:119]
	v_pk_fma_f32 v[112:113], v[20:21], v[236:237], v[112:113]
	v_pk_fma_f32 v[114:115], v[12:13], v[236:237], v[114:115]
	v_pk_fma_f32 v[116:117], v[4:5], v[236:237], v[116:117]
	v_pk_fma_f32 v[118:119], v[0:1], v[236:237], v[118:119]
	v_pk_fma_f32 v[112:113], v[22:23], v[238:239], v[112:113]
	v_pk_fma_f32 v[114:115], v[14:15], v[238:239], v[114:115]
	v_pk_fma_f32 v[116:117], v[6:7], v[238:239], v[116:117]
	v_pk_fma_f32 v[118:119], v[2:3], v[238:239], v[118:119]
	v_add_f32_e32 v112, v112, v113
	v_add_f32_e32 v114, v114, v115
	v_add_f32_e32 v116, v116, v117
	v_add_f32_e32 v118, v118, v119
	v_pk_mul_f32 v[252:253], v[166:167], v[248:249] op_sel_hi:[1,0]
	v_pk_mul_f32 v[254:255], v[166:167], v[248:249] op_sel:[0,1] op_sel_hi:[1,1]
	v_pk_mul_f32 v[194:195], v[168:169], v[248:249] op_sel_hi:[1,0]
	v_pk_mul_f32 v[162:163], v[168:169], v[248:249] op_sel:[0,1] op_sel_hi:[1,1]
	v_add_f32_dpp v112, v112, v112 quad_perm:[1,0,3,2] row_mask:0xf bank_mask:0xf bound_ctrl:1
	v_add_f32_dpp v114, v114, v114 quad_perm:[1,0,3,2] row_mask:0xf bank_mask:0xf bound_ctrl:1
	v_add_f32_dpp v116, v116, v116 quad_perm:[1,0,3,2] row_mask:0xf bank_mask:0xf bound_ctrl:1
	v_add_f32_dpp v118, v118, v118 quad_perm:[1,0,3,2] row_mask:0xf bank_mask:0xf bound_ctrl:1
	v_pk_fma_f32 v[28:29], v[28:29], v[224:225], v[252:253]
	v_pk_fma_f32 v[24:25], v[24:25], v[224:225], v[254:255]
	v_pk_fma_f32 v[30:31], v[30:31], v[226:227], v[194:195]
	v_pk_fma_f32 v[26:27], v[26:27], v[226:227], v[162:163]
	v_add_f32_dpp v112, v112, v112 quad_perm:[2,3,0,1] row_mask:0xf bank_mask:0xf bound_ctrl:1
	v_add_f32_dpp v114, v114, v114 quad_perm:[2,3,0,1] row_mask:0xf bank_mask:0xf bound_ctrl:1
	v_add_f32_dpp v116, v116, v116 quad_perm:[2,3,0,1] row_mask:0xf bank_mask:0xf bound_ctrl:1
	v_add_f32_dpp v118, v118, v118 quad_perm:[2,3,0,1] row_mask:0xf bank_mask:0xf bound_ctrl:1
	v_pk_mul_f32 v[252:253], v[170:171], v[248:249] op_sel_hi:[1,0]
	v_pk_mul_f32 v[254:255], v[170:171], v[248:249] op_sel:[0,1] op_sel_hi:[1,1]
	v_pk_mul_f32 v[194:195], v[172:173], v[248:249] op_sel_hi:[1,0]
	v_pk_mul_f32 v[162:163], v[172:173], v[248:249] op_sel:[0,1] op_sel_hi:[1,1]
	v_add_f32_dpp v112, v112, v112 row_half_mirror row_mask:0xf bank_mask:0xf bound_ctrl:1
	v_add_f32_dpp v114, v114, v114 row_half_mirror row_mask:0xf bank_mask:0xf bound_ctrl:1
	v_add_f32_dpp v116, v116, v116 row_half_mirror row_mask:0xf bank_mask:0xf bound_ctrl:1
	v_add_f32_dpp v118, v118, v118 row_half_mirror row_mask:0xf bank_mask:0xf bound_ctrl:1
	v_pk_fma_f32 v[20:21], v[20:21], v[228:229], v[252:253]
	v_pk_fma_f32 v[12:13], v[12:13], v[228:229], v[254:255]
	v_pk_fma_f32 v[22:23], v[22:23], v[230:231], v[194:195]
	v_pk_fma_f32 v[14:15], v[14:15], v[230:231], v[162:163]
	v_pk_mul_f32 v[16:17], v[16:17], v[224:225]
	v_pk_mul_f32 v[8:9], v[8:9], v[224:225]
	v_pk_mul_f32 v[18:19], v[18:19], v[226:227]
	v_pk_mul_f32 v[10:11], v[10:11], v[226:227]
	v_pk_mul_f32 v[4:5], v[4:5], v[228:229]
	v_pk_mul_f32 v[0:1], v[0:1], v[228:229]
	v_pk_mul_f32 v[6:7], v[6:7], v[230:231]
	v_pk_mul_f32 v[2:3], v[2:3], v[230:231]
	v_pk_fma_f32 v[28:29], v[240:241], v[112:113], v[28:29] op_sel_hi:[1,0,1] neg_lo:[0,1,0] neg_hi:[0,1,0]
	v_pk_fma_f32 v[24:25], v[240:241], v[114:115], v[24:25] op_sel_hi:[1,0,1] neg_lo:[0,1,0] neg_hi:[0,1,0]
	v_pk_fma_f32 v[30:31], v[242:243], v[112:113], v[30:31] op_sel_hi:[1,0,1] neg_lo:[0,1,0] neg_hi:[0,1,0]
	v_pk_fma_f32 v[26:27], v[242:243], v[114:115], v[26:27] op_sel_hi:[1,0,1] neg_lo:[0,1,0] neg_hi:[0,1,0]
	v_pk_fma_f32 v[20:21], v[244:245], v[112:113], v[20:21] op_sel_hi:[1,0,1] neg_lo:[0,1,0] neg_hi:[0,1,0]
	v_pk_fma_f32 v[12:13], v[244:245], v[114:115], v[12:13] op_sel_hi:[1,0,1] neg_lo:[0,1,0] neg_hi:[0,1,0]
	v_pk_fma_f32 v[22:23], v[246:247], v[112:113], v[22:23] op_sel_hi:[1,0,1] neg_lo:[0,1,0] neg_hi:[0,1,0]
	v_pk_fma_f32 v[14:15], v[246:247], v[114:115], v[14:15] op_sel_hi:[1,0,1] neg_lo:[0,1,0] neg_hi:[0,1,0]
	v_pk_fma_f32 v[16:17], v[240:241], v[116:117], v[16:17] op_sel_hi:[1,0,1] neg_lo:[0,1,0] neg_hi:[0,1,0]
	v_pk_fma_f32 v[8:9], v[240:241], v[118:119], v[8:9] op_sel_hi:[1,0,1] neg_lo:[0,1,0] neg_hi:[0,1,0]
	v_pk_fma_f32 v[18:19], v[242:243], v[116:117], v[18:19] op_sel_hi:[1,0,1] neg_lo:[0,1,0] neg_hi:[0,1,0]
	v_pk_fma_f32 v[10:11], v[242:243], v[118:119], v[10:11] op_sel_hi:[1,0,1] neg_lo:[0,1,0] neg_hi:[0,1,0]
	v_pk_fma_f32 v[4:5], v[244:245], v[116:117], v[4:5] op_sel_hi:[1,0,1] neg_lo:[0,1,0] neg_hi:[0,1,0]
	v_pk_fma_f32 v[0:1], v[244:245], v[118:119], v[0:1] op_sel_hi:[1,0,1] neg_lo:[0,1,0] neg_hi:[0,1,0]
	v_pk_fma_f32 v[6:7], v[246:247], v[116:117], v[6:7] op_sel_hi:[1,0,1] neg_lo:[0,1,0] neg_hi:[0,1,0]
	v_pk_fma_f32 v[2:3], v[246:247], v[118:119], v[2:3] op_sel_hi:[1,0,1] neg_lo:[0,1,0] neg_hi:[0,1,0]
	ds_read_b128 v[224:227], v33 offset:3584
	ds_read_b128 v[228:231], v33 offset:3600
	ds_read_b128 v[232:235], v33 offset:7680
	ds_read_b128 v[236:239], v33 offset:7696
	ds_read_b128 v[240:243], v33 offset:11776
	ds_read_b128 v[244:247], v33 offset:11792
	ds_read_b128 v[166:169], v33 offset:15872
	ds_read_b128 v[170:173], v33 offset:15888
	ds_read2_b32 v[248:249], v151 offset0:128 offset1:136
	s_waitcnt lgkmcnt(9)
; #define LAS __attribute__((address_space(3)))
; template <int CTRL> __device__ __forceinline__ float dpp_f(float x) { return __builtin_bit_cast(float, __builtin_amdgcn_mov_dpp(__builtin_bit_cast(int, x), CTRL, 0xf, 0xf, true)); }
; __device__ __forceinline__ float red8(float d) { d += dpp_f<0xB1>(d); d += dpp_f<0x4E>(d); d += dpp_f<0x141>(d); return d; }
; __device__ __forceinline__ void upd8(V8& S, const V8& w, const V8& b, const V8& k, float sa, float vv) {
;     const f32x2 sa2 = {sa, sa}, vv2 = {vv, vv};
; #pragma unroll
;     for (int i = 0; i < 4; ++i) { f32x2 t = vv2 * k.p[i]; t = sa2 * b.p[i] + t; S.p[i] = S.p[i] * w.p[i] + t; }
; }
; __device__ __forceinline__ void updp8(V8& S, const V8& w, const V8& b, float sa) {
;     const f32x2 sa2 = {sa, sa};
; #pragma unroll
;     for (int i = 0; i < 4; ++i) { const f32x2 t = sa2 * b.p[i]; S.p[i] = S.p[i] * w.p[i] + t; }
; }
; template <int MODE>
; __device__ __forceinline__ void scan_pair(LAS unsigned char* lds, CArgsP a, const ScanUnit u, int nch) {
;     ...
;             const LAS float* p = cb + t * 64 + 8 * ks;
;             const V8 w = ld8(p), kk = ld8(p + 1024), bb = ld8(p + 2048), kv = ld8(p + 3072);
;             const float va = cb[(5 * 16 + t) * 64 + vr0], vb = cb[(5 * 16 + t) * 64 + vr1];
;             float da = dot8(Sa, kk), db = dot8(Sb, kk);
;             da = red8(da); db = red8(db);
;             upd8(Sa, w, bb, kv, -da, va); upd8(Sb, w, bb, kv, -db, vb);
;             if (MODE == 1) {
;                 float pa = dot8(Pa, kk), pb = dot8(Pb, kk);
;                 pa = red8(pa); pb = red8(pb);
;                 updp8(Pa, w, bb, -pa); updp8(Pb, w, bb, -pb);
	v_pk_mul_f32 v[112:113], v[28:29], v[182:183]
	v_pk_mul_f32 v[114:115], v[24:25], v[182:183]
	v_pk_mul_f32 v[116:117], v[16:17], v[182:183]
	v_pk_mul_f32 v[118:119], v[8:9], v[182:183]
	v_pk_fma_f32 v[112:113], v[30:31], v[184:185], v[112:113]
	v_pk_fma_f32 v[114:115], v[26:27], v[184:185], v[114:115]
	v_pk_fma_f32 v[116:117], v[18:19], v[184:185], v[116:117]
	v_pk_fma_f32 v[118:119], v[10:11], v[184:185], v[118:119]
	v_pk_fma_f32 v[112:113], v[20:21], v[186:187], v[112:113]
	v_pk_fma_f32 v[114:115], v[12:13], v[186:187], v[114:115]
	v_pk_fma_f32 v[116:117], v[4:5], v[186:187], v[116:117]
	v_pk_fma_f32 v[118:119], v[0:1], v[186:187], v[118:119]
	v_pk_fma_f32 v[112:113], v[22:23], v[188:189], v[112:113]
	v_pk_fma_f32 v[114:115], v[14:15], v[188:189], v[114:115]
	v_pk_fma_f32 v[116:117], v[6:7], v[188:189], v[116:117]
	v_pk_fma_f32 v[118:119], v[2:3], v[188:189], v[118:119]
	v_add_f32_e32 v112, v112, v113
	v_add_f32_e32 v114, v114, v115
	v_add_f32_e32 v116, v116, v117
	v_add_f32_e32 v118, v118, v119
	v_pk_mul_f32 v[252:253], v[134:135], v[142:143] op_sel_hi:[1,0]
	v_pk_mul_f32 v[254:255], v[134:135], v[142:143] op_sel:[0,1] op_sel_hi:[1,1]
	v_pk_mul_f32 v[194:195], v[136:137], v[142:143] op_sel_hi:[1,0]
	v_pk_mul_f32 v[162:163], v[136:137], v[142:143] op_sel:[0,1] op_sel_hi:[1,1]
	v_add_f32_dpp v112, v112, v112 quad_perm:[1,0,3,2] row_mask:0xf bank_mask:0xf bound_ctrl:1
	v_add_f32_dpp v114, v114, v114 quad_perm:[1,0,3,2] row_mask:0xf bank_mask:0xf bound_ctrl:1
	v_add_f32_dpp v116, v116, v116 quad_perm:[1,0,3,2] row_mask:0xf bank_mask:0xf bound_ctrl:1
	v_add_f32_dpp v118, v118, v118 quad_perm:[1,0,3,2] row_mask:0xf bank_mask:0xf bound_ctrl:1
	v_pk_fma_f32 v[28:29], v[28:29], v[174:175], v[252:253]
	v_pk_fma_f32 v[24:25], v[24:25], v[174:175], v[254:255]
	v_pk_fma_f32 v[30:31], v[30:31], v[176:177], v[194:195]
	v_pk_fma_f32 v[26:27], v[26:27], v[176:177], v[162:163]
	v_add_f32_dpp v112, v112, v112 quad_perm:[2,3,0,1] row_mask:0xf bank_mask:0xf bound_ctrl:1
	v_add_f32_dpp v114, v114, v114 quad_perm:[2,3,0,1] row_mask:0xf bank_mask:0xf bound_ctrl:1
	v_add_f32_dpp v116, v116, v116 quad_perm:[2,3,0,1] row_mask:0xf bank_mask:0xf bound_ctrl:1
	v_add_f32_dpp v118, v118, v118 quad_perm:[2,3,0,1] row_mask:0xf bank_mask:0xf bound_ctrl:1
	v_pk_mul_f32 v[252:253], v[138:139], v[142:143] op_sel_hi:[1,0]
	v_pk_mul_f32 v[254:255], v[138:139], v[142:143] op_sel:[0,1] op_sel_hi:[1,1]
	v_pk_mul_f32 v[194:195], v[140:141], v[142:143] op_sel_hi:[1,0]
	v_pk_mul_f32 v[162:163], v[140:141], v[142:143] op_sel:[0,1] op_sel_hi:[1,1]
	v_add_f32_dpp v112, v112, v112 row_half_mirror row_mask:0xf bank_mask:0xf bound_ctrl:1
	v_add_f32_dpp v114, v114, v114 row_half_mirror row_mask:0xf bank_mask:0xf bound_ctrl:1
	v_add_f32_dpp v116, v116, v116 row_half_mirror row_mask:0xf bank_mask:0xf bound_ctrl:1
	v_add_f32_dpp v118, v118, v118 row_half_mirror row_mask:0xf bank_mask:0xf bound_ctrl:1
	v_pk_fma_f32 v[20:21], v[20:21], v[178:179], v[252:253]
	v_pk_fma_f32 v[12:13], v[12:13], v[178:179], v[254:255]
	v_pk_fma_f32 v[22:23], v[22:23], v[180:181], v[194:195]
	v_pk_fma_f32 v[14:15], v[14:15], v[180:181], v[162:163]
	v_pk_mul_f32 v[16:17], v[16:17], v[174:175]
	v_pk_mul_f32 v[8:9], v[8:9], v[174:175]
	v_pk_mul_f32 v[18:19], v[18:19], v[176:177]
	v_pk_mul_f32 v[10:11], v[10:11], v[176:177]
	v_pk_mul_f32 v[4:5], v[4:5], v[178:179]
	v_pk_mul_f32 v[0:1], v[0:1], v[178:179]
	v_pk_mul_f32 v[6:7], v[6:7], v[180:181]
	v_pk_mul_f32 v[2:3], v[2:3], v[180:181]
	v_pk_fma_f32 v[28:29], v[190:191], v[112:113], v[28:29] op_sel_hi:[1,0,1] neg_lo:[0,1,0] neg_hi:[0,1,0]
	v_pk_fma_f32 v[24:25], v[190:191], v[114:115], v[24:25] op_sel_hi:[1,0,1] neg_lo:[0,1,0] neg_hi:[0,1,0]
	v_pk_fma_f32 v[30:31], v[192:193], v[112:113], v[30:31] op_sel_hi:[1,0,1] neg_lo:[0,1,0] neg_hi:[0,1,0]
	v_pk_fma_f32 v[26:27], v[192:193], v[114:115], v[26:27] op_sel_hi:[1,0,1] neg_lo:[0,1,0] neg_hi:[0,1,0]
	v_pk_fma_f32 v[20:21], v[130:131], v[112:113], v[20:21] op_sel_hi:[1,0,1] neg_lo:[0,1,0] neg_hi:[0,1,0]
	v_pk_fma_f32 v[12:13], v[130:131], v[114:115], v[12:13] op_sel_hi:[1,0,1] neg_lo:[0,1,0] neg_hi:[0,1,0]
	v_pk_fma_f32 v[22:23], v[132:133], v[112:113], v[22:23] op_sel_hi:[1,0,1] neg_lo:[0,1,0] neg_hi:[0,1,0]
	v_pk_fma_f32 v[14:15], v[132:133], v[114:115], v[14:15] op_sel_hi:[1,0,1] neg_lo:[0,1,0] neg_hi:[0,1,0]
	v_pk_fma_f32 v[16:17], v[190:191], v[116:117], v[16:17] op_sel_hi:[1,0,1] neg_lo:[0,1,0] neg_hi:[0,1,0]
	v_pk_fma_f32 v[8:9], v[190:191], v[118:119], v[8:9] op_sel_hi:[1,0,1] neg_lo:[0,1,0] neg_hi:[0,1,0]
	v_pk_fma_f32 v[18:19], v[192:193], v[116:117], v[18:19] op_sel_hi:[1,0,1] neg_lo:[0,1,0] neg_hi:[0,1,0]
	v_pk_fma_f32 v[10:11], v[192:193], v[118:119], v[10:11] op_sel_hi:[1,0,1] neg_lo:[0,1,0] neg_hi:[0,1,0]
	v_pk_fma_f32 v[4:5], v[130:131], v[116:117], v[4:5] op_sel_hi:[1,0,1] neg_lo:[0,1,0] neg_hi:[0,1,0]
	v_pk_fma_f32 v[0:1], v[130:131], v[118:119], v[0:1] op_sel_hi:[1,0,1] neg_lo:[0,1,0] neg_hi:[0,1,0]
	v_pk_fma_f32 v[6:7], v[132:133], v[116:117], v[6:7] op_sel_hi:[1,0,1] neg_lo:[0,1,0] neg_hi:[0,1,0]
	v_pk_fma_f32 v[2:3], v[132:133], v[118:119], v[2:3] op_sel_hi:[1,0,1] neg_lo:[0,1,0] neg_hi:[0,1,0]
	ds_read_b128 v[174:177], v33 offset:3840
	ds_read_b128 v[178:181], v33 offset:3856
	ds_read_b128 v[182:185], v33 offset:7936
	ds_read_b128 v[186:189], v33 offset:7952
	ds_read_b128 v[190:193], v33 offset:12032
	ds_read_b128 v[130:133], v33 offset:12048
	ds_read_b128 v[134:137], v33 offset:16128
	ds_read_b128 v[138:141], v33 offset:16144
	ds_read2_b32 v[142:143], v151 offset0:192 offset1:200
	s_waitcnt lgkmcnt(9)
; #define LAS __attribute__((address_space(3)))
; template <int CTRL> __device__ __forceinline__ float dpp_f(float x) { return __builtin_bit_cast(float, __builtin_amdgcn_mov_dpp(__builtin_bit_cast(int, x), CTRL, 0xf, 0xf, true)); }
; __device__ __forceinline__ float red8(float d) { d += dpp_f<0xB1>(d); d += dpp_f<0x4E>(d); d += dpp_f<0x141>(d); return d; }
; __device__ __forceinline__ void upd8(V8& S, const V8& w, const V8& b, const V8& k, float sa, float vv) {
;     const f32x2 sa2 = {sa, sa}, vv2 = {vv, vv};
; #pragma unroll
;     for (int i = 0; i < 4; ++i) { f32x2 t = vv2 * k.p[i]; t = sa2 * b.p[i] + t; S.p[i] = S.p[i] * w.p[i] + t; }
; }
; __device__ __forceinline__ void updp8(V8& S, const V8& w, const V8& b, float sa) {
;     const f32x2 sa2 = {sa, sa};
; #pragma unroll
;     for (int i = 0; i < 4; ++i) { const f32x2 t = sa2 * b.p[i]; S.p[i] = S.p[i] * w.p[i] + t; }
; }
; template <int MODE>
; __device__ __forceinline__ void scan_pair(LAS unsigned char* lds, CArgsP a, const ScanUnit u, int nch) {
;     ...
;             const LAS float* p = cb + t * 64 + 8 * ks;
;             const V8 w = ld8(p), kk = ld8(p + 1024), bb = ld8(p + 2048), kv = ld8(p + 3072);
;             const float va = cb[(5 * 16 + t) * 64 + vr0], vb = cb[(5 * 16 + t) * 64 + vr1];
;             float da = dot8(Sa, kk), db = dot8(Sb, kk);
;             da = red8(da); db = red8(db);
;             upd8(Sa, w, bb, kv, -da, va); upd8(Sb, w, bb, kv, -db, vb);
;             if (MODE == 1) {
;                 float pa = dot8(Pa, kk), pb = dot8(Pb, kk);
;                 pa = red8(pa); pb = red8(pb);
;                 updp8(Pa, w, bb, -pa); updp8(Pb, w, bb, -pb);
	v_pk_mul_f32 v[112:113], v[28:29], v[232:233]
	v_pk_mul_f32 v[114:115], v[24:25], v[232:233]
	v_pk_mul_f32 v[116:117], v[16:17], v[232:233]
	v_pk_mul_f32 v[118:119], v[8:9], v[232:233]
	v_pk_fma_f32 v[112:113], v[30:31], v[234:235], v[112:113]
	v_pk_fma_f32 v[114:115], v[26:27], v[234:235], v[114:115]
	v_pk_fma_f32 v[116:117], v[18:19], v[234:235], v[116:117]
	v_pk_fma_f32 v[118:119], v[10:11], v[234:235], v[118:119]
	v_pk_fma_f32 v[112:113], v[20:21], v[236:237], v[112:113]
	v_pk_fma_f32 v[114:115], v[12:13], v[236:237], v[114:115]
	v_pk_fma_f32 v[116:117], v[4:5], v[236:237], v[116:117]
	v_pk_fma_f32 v[118:119], v[0:1], v[236:237], v[118:119]
	v_pk_fma_f32 v[112:113], v[22:23], v[238:239], v[112:113]
	v_pk_fma_f32 v[114:115], v[14:15], v[238:239], v[114:115]
	v_pk_fma_f32 v[116:117], v[6:7], v[238:239], v[116:117]
	v_pk_fma_f32 v[118:119], v[2:3], v[238:239], v[118:119]
	v_add_f32_e32 v112, v112, v113
	v_add_f32_e32 v114, v114, v115
	v_add_f32_e32 v116, v116, v117
	v_add_f32_e32 v118, v118, v119
	v_pk_mul_f32 v[252:253], v[166:167], v[248:249] op_sel_hi:[1,0]
	v_pk_mul_f32 v[254:255], v[166:167], v[248:249] op_sel:[0,1] op_sel_hi:[1,1]
	v_pk_mul_f32 v[194:195], v[168:169], v[248:249] op_sel_hi:[1,0]
	v_pk_mul_f32 v[162:163], v[168:169], v[248:249] op_sel:[0,1] op_sel_hi:[1,1]
	v_add_f32_dpp v112, v112, v112 quad_perm:[1,0,3,2] row_mask:0xf bank_mask:0xf bound_ctrl:1
	v_add_f32_dpp v114, v114, v114 quad_perm:[1,0,3,2] row_mask:0xf bank_mask:0xf bound_ctrl:1
	v_add_f32_dpp v116, v116, v116 quad_perm:[1,0,3,2] row_mask:0xf bank_mask:0xf bound_ctrl:1
	v_add_f32_dpp v118, v118, v118 quad_perm:[1,0,3,2] row_mask:0xf bank_mask:0xf bound_ctrl:1
	v_pk_fma_f32 v[28:29], v[28:29], v[224:225], v[252:253]
	v_pk_fma_f32 v[24:25], v[24:25], v[224:225], v[254:255]
	v_pk_fma_f32 v[30:31], v[30:31], v[226:227], v[194:195]
	v_pk_fma_f32 v[26:27], v[26:27], v[226:227], v[162:163]
	v_add_f32_dpp v112, v112, v112 quad_perm:[2,3,0,1] row_mask:0xf bank_mask:0xf bound_ctrl:1
	v_add_f32_dpp v114, v114, v114 quad_perm:[2,3,0,1] row_mask:0xf bank_mask:0xf bound_ctrl:1
	v_add_f32_dpp v116, v116, v116 quad_perm:[2,3,0,1] row_mask:0xf bank_mask:0xf bound_ctrl:1
	v_add_f32_dpp v118, v118, v118 quad_perm:[2,3,0,1] row_mask:0xf bank_mask:0xf bound_ctrl:1
	v_pk_mul_f32 v[252:253], v[170:171], v[248:249] op_sel_hi:[1,0]
	v_pk_mul_f32 v[254:255], v[170:171], v[248:249] op_sel:[0,1] op_sel_hi:[1,1]
	v_pk_mul_f32 v[194:195], v[172:173], v[248:249] op_sel_hi:[1,0]
	v_pk_mul_f32 v[162:163], v[172:173], v[248:249] op_sel:[0,1] op_sel_hi:[1,1]
	v_add_f32_dpp v112, v112, v112 row_half_mirror row_mask:0xf bank_mask:0xf bound_ctrl:1
	v_add_f32_dpp v114, v114, v114 row_half_mirror row_mask:0xf bank_mask:0xf bound_ctrl:1
	v_add_f32_dpp v116, v116, v116 row_half_mirror row_mask:0xf bank_mask:0xf bound_ctrl:1
	v_add_f32_dpp v118, v118, v118 row_half_mirror row_mask:0xf bank_mask:0xf bound_ctrl:1
	v_pk_fma_f32 v[20:21], v[20:21], v[228:229], v[252:253]
	v_pk_fma_f32 v[12:13], v[12:13], v[228:229], v[254:255]
	v_pk_fma_f32 v[22:23], v[22:23], v[230:231], v[194:195]
	v_pk_fma_f32 v[14:15], v[14:15], v[230:231], v[162:163]
	v_pk_mul_f32 v[16:17], v[16:17], v[224:225]
	v_pk_mul_f32 v[8:9], v[8:9], v[224:225]
	v_pk_mul_f32 v[18:19], v[18:19], v[226:227]
	v_pk_mul_f32 v[10:11], v[10:11], v[226:227]
	v_pk_mul_f32 v[4:5], v[4:5], v[228:229]
	v_pk_mul_f32 v[0:1], v[0:1], v[228:229]
	v_pk_mul_f32 v[6:7], v[6:7], v[230:231]
	v_pk_mul_f32 v[2:3], v[2:3], v[230:231]
	v_pk_fma_f32 v[28:29], v[240:241], v[112:113], v[28:29] op_sel_hi:[1,0,1] neg_lo:[0,1,0] neg_hi:[0,1,0]
	v_pk_fma_f32 v[24:25], v[240:241], v[114:115], v[24:25] op_sel_hi:[1,0,1] neg_lo:[0,1,0] neg_hi:[0,1,0]
	v_pk_fma_f32 v[30:31], v[242:243], v[112:113], v[30:31] op_sel_hi:[1,0,1] neg_lo:[0,1,0] neg_hi:[0,1,0]
	v_pk_fma_f32 v[26:27], v[242:243], v[114:115], v[26:27] op_sel_hi:[1,0,1] neg_lo:[0,1,0] neg_hi:[0,1,0]
	v_pk_fma_f32 v[20:21], v[244:245], v[112:113], v[20:21] op_sel_hi:[1,0,1] neg_lo:[0,1,0] neg_hi:[0,1,0]
	v_pk_fma_f32 v[12:13], v[244:245], v[114:115], v[12:13] op_sel_hi:[1,0,1] neg_lo:[0,1,0] neg_hi:[0,1,0]
	v_pk_fma_f32 v[22:23], v[246:247], v[112:113], v[22:23] op_sel_hi:[1,0,1] neg_lo:[0,1,0] neg_hi:[0,1,0]
	v_pk_fma_f32 v[14:15], v[246:247], v[114:115], v[14:15] op_sel_hi:[1,0,1] neg_lo:[0,1,0] neg_hi:[0,1,0]
	v_pk_fma_f32 v[16:17], v[240:241], v[116:117], v[16:17] op_sel_hi:[1,0,1] neg_lo:[0,1,0] neg_hi:[0,1,0]
	v_pk_fma_f32 v[8:9], v[240:241], v[118:119], v[8:9] op_sel_hi:[1,0,1] neg_lo:[0,1,0] neg_hi:[0,1,0]
	v_pk_fma_f32 v[18:19], v[242:243], v[116:117], v[18:19] op_sel_hi:[1,0,1] neg_lo:[0,1,0] neg_hi:[0,1,0]
	v_pk_fma_f32 v[10:11], v[242:243], v[118:119], v[10:11] op_sel_hi:[1,0,1] neg_lo:[0,1,0] neg_hi:[0,1,0]
	v_pk_fma_f32 v[4:5], v[244:245], v[116:117], v[4:5] op_sel_hi:[1,0,1] neg_lo:[0,1,0] neg_hi:[0,1,0]
	v_pk_fma_f32 v[0:1], v[244:245], v[118:119], v[0:1] op_sel_hi:[1,0,1] neg_lo:[0,1,0] neg_hi:[0,1,0]
	v_pk_fma_f32 v[6:7], v[246:247], v[116:117], v[6:7] op_sel_hi:[1,0,1] neg_lo:[0,1,0] neg_hi:[0,1,0]
	v_pk_fma_f32 v[2:3], v[246:247], v[118:119], v[2:3] op_sel_hi:[1,0,1] neg_lo:[0,1,0] neg_hi:[0,1,0]
	s_waitcnt lgkmcnt(0)
; #define LAS __attribute__((address_space(3)))
; template <int CTRL> __device__ __forceinline__ float dpp_f(float x) { return __builtin_bit_cast(float, __builtin_amdgcn_mov_dpp(__builtin_bit_cast(int, x), CTRL, 0xf, 0xf, true)); }
; __device__ __forceinline__ float red8(float d) { d += dpp_f<0xB1>(d); d += dpp_f<0x4E>(d); d += dpp_f<0x141>(d); return d; }
; __device__ __forceinline__ void upd8(V8& S, const V8& w, const V8& b, const V8& k, float sa, float vv) {
;     const f32x2 sa2 = {sa, sa}, vv2 = {vv, vv};
; #pragma unroll
;     for (int i = 0; i < 4; ++i) { f32x2 t = vv2 * k.p[i]; t = sa2 * b.p[i] + t; S.p[i] = S.p[i] * w.p[i] + t; }
; }
; __device__ __forceinline__ void updp8(V8& S, const V8& w, const V8& b, float sa) {
;     const f32x2 sa2 = {sa, sa};
; #pragma unroll
;     for (int i = 0; i < 4; ++i) { const f32x2 t = sa2 * b.p[i]; S.p[i] = S.p[i] * w.p[i] + t; }
; }
; template <int MODE>
; __device__ __forceinline__ void scan_pair(LAS unsigned char* lds, CArgsP a, const ScanUnit u, int nch) {
;     ...
;             const LAS float* p = cb + t * 64 + 8 * ks;
;             const V8 w = ld8(p), kk = ld8(p + 1024), bb = ld8(p + 2048), kv = ld8(p + 3072);
;             const float va = cb[(5 * 16 + t) * 64 + vr0], vb = cb[(5 * 16 + t) * 64 + vr1];
;             float da = dot8(Sa, kk), db = dot8(Sb, kk);
;             da = red8(da); db = red8(db);
;             upd8(Sa, w, bb, kv, -da, va); upd8(Sb, w, bb, kv, -db, vb);
;             if (MODE == 1) {
;                 float pa = dot8(Pa, kk), pb = dot8(Pb, kk);
;                 pa = red8(pa); pb = red8(pb);
;                 updp8(Pa, w, bb, -pa); updp8(Pb, w, bb, -pb);
;             } else {
;                 const V8 rr = ld8(p + 4096);
;                 float ya = dot8(Sa, rr), yb = dot8(Sb, rr);
;                 ya = red8(ya); yb = red8(yb);
;                 if (ks == 0) { Y[t * 64 + vr0] = ya; Y[t * 64 + vr1] = yb; }
;             }
;         }
;         __syncthreads();
	v_pk_mul_f32 v[112:113], v[28:29], v[182:183]
	v_pk_mul_f32 v[114:115], v[24:25], v[182:183]
	v_pk_mul_f32 v[116:117], v[16:17], v[182:183]
	v_pk_mul_f32 v[118:119], v[8:9], v[182:183]
	v_pk_fma_f32 v[112:113], v[30:31], v[184:185], v[112:113]
	v_pk_fma_f32 v[114:115], v[26:27], v[184:185], v[114:115]
	v_pk_fma_f32 v[116:117], v[18:19], v[184:185], v[116:117]
	v_pk_fma_f32 v[118:119], v[10:11], v[184:185], v[118:119]
	v_pk_fma_f32 v[112:113], v[20:21], v[186:187], v[112:113]
	v_pk_fma_f32 v[114:115], v[12:13], v[186:187], v[114:115]
	v_pk_fma_f32 v[116:117], v[4:5], v[186:187], v[116:117]
	v_pk_fma_f32 v[118:119], v[0:1], v[186:187], v[118:119]
	v_pk_fma_f32 v[112:113], v[22:23], v[188:189], v[112:113]
	v_pk_fma_f32 v[114:115], v[14:15], v[188:189], v[114:115]
	v_pk_fma_f32 v[116:117], v[6:7], v[188:189], v[116:117]
	v_pk_fma_f32 v[118:119], v[2:3], v[188:189], v[118:119]
	v_add_f32_e32 v112, v112, v113
	v_add_f32_e32 v114, v114, v115
	v_add_f32_e32 v116, v116, v117
	v_add_f32_e32 v118, v118, v119
	v_pk_mul_f32 v[252:253], v[134:135], v[142:143] op_sel_hi:[1,0]
	v_pk_mul_f32 v[254:255], v[134:135], v[142:143] op_sel:[0,1] op_sel_hi:[1,1]
	v_pk_mul_f32 v[194:195], v[136:137], v[142:143] op_sel_hi:[1,0]
	v_pk_mul_f32 v[162:163], v[136:137], v[142:143] op_sel:[0,1] op_sel_hi:[1,1]
	v_add_f32_dpp v112, v112, v112 quad_perm:[1,0,3,2] row_mask:0xf bank_mask:0xf bound_ctrl:1
	v_add_f32_dpp v114, v114, v114 quad_perm:[1,0,3,2] row_mask:0xf bank_mask:0xf bound_ctrl:1
	v_add_f32_dpp v116, v116, v116 quad_perm:[1,0,3,2] row_mask:0xf bank_mask:0xf bound_ctrl:1
	v_add_f32_dpp v118, v118, v118 quad_perm:[1,0,3,2] row_mask:0xf bank_mask:0xf bound_ctrl:1
	v_pk_fma_f32 v[28:29], v[28:29], v[174:175], v[252:253]
	v_pk_fma_f32 v[24:25], v[24:25], v[174:175], v[254:255]
	v_pk_fma_f32 v[30:31], v[30:31], v[176:177], v[194:195]
	v_pk_fma_f32 v[26:27], v[26:27], v[176:177], v[162:163]
	v_add_f32_dpp v112, v112, v112 quad_perm:[2,3,0,1] row_mask:0xf bank_mask:0xf bound_ctrl:1
	v_add_f32_dpp v114, v114, v114 quad_perm:[2,3,0,1] row_mask:0xf bank_mask:0xf bound_ctrl:1
	v_add_f32_dpp v116, v116, v116 quad_perm:[2,3,0,1] row_mask:0xf bank_mask:0xf bound_ctrl:1
	v_add_f32_dpp v118, v118, v118 quad_perm:[2,3,0,1] row_mask:0xf bank_mask:0xf bound_ctrl:1
	v_pk_mul_f32 v[252:253], v[138:139], v[142:143] op_sel_hi:[1,0]
	v_pk_mul_f32 v[254:255], v[138:139], v[142:143] op_sel:[0,1] op_sel_hi:[1,1]
	v_pk_mul_f32 v[194:195], v[140:141], v[142:143] op_sel_hi:[1,0]
	v_pk_mul_f32 v[162:163], v[140:141], v[142:143] op_sel:[0,1] op_sel_hi:[1,1]
	v_add_f32_dpp v112, v112, v112 row_half_mirror row_mask:0xf bank_mask:0xf bound_ctrl:1
	v_add_f32_dpp v114, v114, v114 row_half_mirror row_mask:0xf bank_mask:0xf bound_ctrl:1
	v_add_f32_dpp v116, v116, v116 row_half_mirror row_mask:0xf bank_mask:0xf bound_ctrl:1
	v_add_f32_dpp v118, v118, v118 row_half_mirror row_mask:0xf bank_mask:0xf bound_ctrl:1
	v_pk_fma_f32 v[20:21], v[20:21], v[178:179], v[252:253]
	v_pk_fma_f32 v[12:13], v[12:13], v[178:179], v[254:255]
	v_pk_fma_f32 v[22:23], v[22:23], v[180:181], v[194:195]
	v_pk_fma_f32 v[14:15], v[14:15], v[180:181], v[162:163]
	v_pk_mul_f32 v[16:17], v[16:17], v[174:175]
	v_pk_mul_f32 v[8:9], v[8:9], v[174:175]
	v_pk_mul_f32 v[18:19], v[18:19], v[176:177]
	v_pk_mul_f32 v[10:11], v[10:11], v[176:177]
	v_pk_mul_f32 v[4:5], v[4:5], v[178:179]
	v_pk_mul_f32 v[0:1], v[0:1], v[178:179]
	v_pk_mul_f32 v[6:7], v[6:7], v[180:181]
	v_pk_mul_f32 v[2:3], v[2:3], v[180:181]
	v_pk_fma_f32 v[28:29], v[190:191], v[112:113], v[28:29] op_sel_hi:[1,0,1] neg_lo:[0,1,0] neg_hi:[0,1,0]
	v_pk_fma_f32 v[24:25], v[190:191], v[114:115], v[24:25] op_sel_hi:[1,0,1] neg_lo:[0,1,0] neg_hi:[0,1,0]
	v_pk_fma_f32 v[30:31], v[192:193], v[112:113], v[30:31] op_sel_hi:[1,0,1] neg_lo:[0,1,0] neg_hi:[0,1,0]
	v_pk_fma_f32 v[26:27], v[192:193], v[114:115], v[26:27] op_sel_hi:[1,0,1] neg_lo:[0,1,0] neg_hi:[0,1,0]
	v_pk_fma_f32 v[20:21], v[130:131], v[112:113], v[20:21] op_sel_hi:[1,0,1] neg_lo:[0,1,0] neg_hi:[0,1,0]
	v_pk_fma_f32 v[12:13], v[130:131], v[114:115], v[12:13] op_sel_hi:[1,0,1] neg_lo:[0,1,0] neg_hi:[0,1,0]
	v_pk_fma_f32 v[22:23], v[132:133], v[112:113], v[22:23] op_sel_hi:[1,0,1] neg_lo:[0,1,0] neg_hi:[0,1,0]
	v_pk_fma_f32 v[14:15], v[132:133], v[114:115], v[14:15] op_sel_hi:[1,0,1] neg_lo:[0,1,0] neg_hi:[0,1,0]
	v_pk_fma_f32 v[16:17], v[190:191], v[116:117], v[16:17] op_sel_hi:[1,0,1] neg_lo:[0,1,0] neg_hi:[0,1,0]
	v_pk_fma_f32 v[8:9], v[190:191], v[118:119], v[8:9] op_sel_hi:[1,0,1] neg_lo:[0,1,0] neg_hi:[0,1,0]
	v_pk_fma_f32 v[18:19], v[192:193], v[116:117], v[18:19] op_sel_hi:[1,0,1] neg_lo:[0,1,0] neg_hi:[0,1,0]
	v_pk_fma_f32 v[10:11], v[192:193], v[118:119], v[10:11] op_sel_hi:[1,0,1] neg_lo:[0,1,0] neg_hi:[0,1,0]
	v_pk_fma_f32 v[4:5], v[130:131], v[116:117], v[4:5] op_sel_hi:[1,0,1] neg_lo:[0,1,0] neg_hi:[0,1,0]
	v_pk_fma_f32 v[0:1], v[130:131], v[118:119], v[0:1] op_sel_hi:[1,0,1] neg_lo:[0,1,0] neg_hi:[0,1,0]
	v_pk_fma_f32 v[6:7], v[132:133], v[116:117], v[6:7] op_sel_hi:[1,0,1] neg_lo:[0,1,0] neg_hi:[0,1,0]
	v_pk_fma_f32 v[2:3], v[132:133], v[118:119], v[2:3] op_sel_hi:[1,0,1] neg_lo:[0,1,0] neg_hi:[0,1,0]
	s_and_b64 vcc, exec, s[28:29]
	s_barrier
	s_cbranch_vccz .LBB0_818
; #define LAS __attribute__((address_space(3)))
; template <int MODE>
; __device__ __forceinline__ void scan_pair(LAS unsigned char* lds, CArgsP a, const ScanUnit u, int nch) {
;     ...
;     auto prep = [&](int c, int b) {
;         LAS float* cb = (LAS float*)(hl + b * SC_CHB);
; #pragma unroll
;         for (int tt = 0; tt < 4; ++tt) {
;             const int t = 4 * hw + tt, tl = 16 * c + t;
;             const float pr = bf2f(R.prk[tt] & 0xffffu), pk = bf2f(R.prk[tt] >> 16), pv = bf2f(R.pvq[tt] & 0xffffu);
;             float qr = bf2f(R.pvq[tt] >> 16), qk = bf2f(R.qkv[tt] & 0xffffu), qv = bf2f(R.qkv[tt] >> 16);
;             if (tl == 0) { qr = sh0[0]; qk = sh0[1]; qv = sh0[2]; }
;             const float xr = pr + (qr - pr) * mu_r, xk = pk + (qk - pk) * mu_k, xv = pv + (qv - pv) * mu_v;
;             const float wp = w0c + bf2f(R.lwa[tt] & 0xffffu);
;             const float w = __expf(-0.6065306597126334f * __builtin_amdgcn_rcpf(1.f + __expf(-wp)));
;             const float av = __builtin_amdgcn_rcpf(1.f + __expf(-(a0c + bf2f(R.lwa[tt] >> 16))));
;             float kk = xk * kkc;
;             const float n2 = wave_sum_fast(kk * kk);
;             kk = kk * rsqrtf(fmaxf(n2, 1e-24f));
;             const float kp = xk * (1.f + (av - 1.f) * kac);
;             cb[(0 * 16 + t) * 64 + lane] = w; cb[(1 * 16 + t) * 64 + lane] = kk; cb[(2 * 16 + t) * 64 + lane] = kk * av; cb[(3 * 16 + t) * 64 + lane] = kp;
;             cb[(4 * 16 + t) * 64 + lane] = xr; cb[(5 * 16 + t) * 64 + lane] = xv; cb[(6 * 16 + t) * 64 + lane] = bf2f(R.lg[tt]);
;         }
;     };
	s_waitcnt vmcnt(0)
	v_mov_b32_e32 v118, v200
	v_mov_b32_e32 v119, v201
	v_mov_b32_e32 v120, v202
	v_mov_b32_e32 v121, v203
	v_mov_b32_e32 v123, v204
	v_mov_b32_e32 v124, v205
	v_mov_b32_e32 v125, v206
	v_mov_b32_e32 v126, v207
	v_mov_b32_e32 v127, v208
	v_mov_b32_e32 v128, v209
	v_mov_b32_e32 v130, v210
	v_mov_b32_e32 v131, v211
	v_mov_b32_e32 v132, v212
	v_mov_b32_e32 v133, v213
	v_mov_b32_e32 v134, v214
	v_mov_b32_e32 v135, v215
	v_mov_b32_e32 v136, v216
	v_mov_b32_e32 v137, v217
	v_mov_b32_e32 v138, v218
	v_mov_b32_e32 v139, v219
	v_mov_b32_e32 v140, v220
	v_mov_b32_e32 v33, v221
	v_mov_b32_e32 v141, v222
	v_lshl_or_b32 v112, v119, 16, v118
	v_lshl_or_b32 v116, v120, 16, v119
	v_lshl_or_b32 v113, v121, 16, v120
	v_lshl_or_b32 v115, v125, 16, v124
	v_lshl_or_b32 v114, v126, 16, v123
	v_lshl_or_b32 v117, v128, 16, v127
	v_lshl_or_b32 v118, v118, 16, v130
	v_lshl_or_b32 v120, v130, 16, v128
	v_lshl_or_b32 v119, v132, 16, v131
	v_lshl_or_b32 v121, v134, 16, v133
	v_lshl_or_b32 v123, v127, 16, v135
	v_lshl_or_b32 v124, v137, 16, v136
	v_lshl_or_b32 v125, v135, 16, v134
	v_lshl_or_b32 v127, v133, 16, v139
	v_lshl_or_b32 v126, v140, 16, v138
	v_lshl_or_b32 v128, v141, 16, v33
	v_lshlrev_b32_e32 v135, 16, v115
	v_add_f32_e32 v135, v107, v135
	v_and_b32_e32 v33, 0xffff0000, v113
	v_lshlrev_b32_e32 v134, 16, v112
	v_mul_f32_e32 v135, 0xbfb8aa3b, v135
	v_lshlrev_b32_e32 v130, 16, v114
	v_and_b32_e32 v133, 0xffff0000, v112
	v_sub_f32_e32 v33, v33, v134
	v_exp_f32_e32 v135, v135
	v_lshlrev_b32_e32 v143, 16, v119
	v_and_b32_e32 v131, 0xffff0000, v114
	v_lshlrev_b32_e32 v132, 16, v113
	v_fmac_f32_e32 v134, v99, v33
	v_sub_f32_e32 v33, v130, v133
	v_add_f32_e32 v143, v107, v143
	v_fmac_f32_e32 v133, v101, v33
	v_sub_f32_e32 v131, v131, v132
	v_mul_f32_e32 v143, 0xbfb8aa3b, v143
	v_fmac_f32_e32 v132, v108, v131
	v_mul_f32_e32 v131, v105, v133
	v_and_b32_e32 v139, 0xffff0000, v118
	v_lshlrev_b32_e32 v142, 16, v117
	v_exp_f32_e32 v143, v143
	v_add_f32_e32 v33, 1.0, v135
	v_mul_f32_e32 v135, v131, v131
	v_sub_f32_e32 v139, v139, v142
	v_lshlrev_b32_e32 v138, 16, v116
	v_mov_b32_dpp v135, v135 quad_perm:[1,0,3,2] row_mask:0xf bank_mask:0xf bound_ctrl:1
	v_and_b32_e32 v141, 0xffff0000, v117
	v_fmac_f32_e32 v142, v99, v139
	v_and_b32_e32 v139, 0xffff0000, v119
	v_fmac_f32_e32 v135, v131, v131
	v_sub_f32_e32 v138, v138, v141
	v_add_f32_e32 v139, v104, v139
	v_add_f32_dpp v135, v135, v135 quad_perm:[2,3,0,1] row_mask:0xf bank_mask:0xf bound_ctrl:1
	v_fmac_f32_e32 v141, v101, v138
	v_add_f32_e32 v138, 1.0, v143
	v_mul_f32_e32 v139, 0xbfb8aa3b, v139
	v_add_f32_dpp v135, v135, v135 row_half_mirror row_mask:0xf bank_mask:0xf bound_ctrl:1
	v_rcp_f32_e32 v138, v138
	v_exp_f32_e32 v139, v139
	v_and_b32_e32 v130, 0xffff0000, v115
	v_add_f32_dpp v135, v135, v135 row_mirror row_mask:0xf bank_mask:0xf bound_ctrl:1
	v_mov_b32_e32 v136, 0
	v_add_f32_e32 v130, v104, v130
	v_and_b32_e32 v137, 0xffff0000, v116
	v_mov_b32_dpp v136, v135 row_bcast:15 row_mask:0xa bank_mask:0xf
	v_lshlrev_b32_e32 v140, 16, v118
	v_mul_f32_e32 v130, 0xbfb8aa3b, v130
	v_add_f32_e32 v135, v135, v136
	v_mov_b32_e32 v136, 0
	v_sub_f32_e32 v137, v137, v140
	v_exp_f32_e32 v130, v130
	v_mov_b32_dpp v136, v135 row_bcast:31 row_mask:0xc bank_mask:0xf
	v_fmac_f32_e32 v140, v108, v137
	v_mul_f32_e32 v137, 0xbf1b4598, v138
	v_add_f32_e32 v138, 1.0, v139
	v_mul_f32_e32 v139, v105, v141
	v_add_f32_e32 v135, v135, v136
	v_mul_f32_e32 v143, v139, v139
	v_readlane_b32 s29, v135, 63
	v_add_f32_e32 v130, 1.0, v130
	v_mov_b32_dpp v143, v143 quad_perm:[1,0,3,2] row_mask:0xf bank_mask:0xf bound_ctrl:1
	v_max_f32_e64 v135, s29, s29
	v_fmac_f32_e32 v143, v139, v139
	v_max_f32_e32 v135, 0x179abe15, v135
	v_rsq_f32_e32 v135, v135
	v_add_f32_dpp v143, v143, v143 quad_perm:[2,3,0,1] row_mask:0xf bank_mask:0xf bound_ctrl:1
	v_rcp_f32_e32 v130, v130
	v_mov_b32_e32 v151, 0
	v_add_f32_dpp v143, v143, v143 row_half_mirror row_mask:0xf bank_mask:0xf bound_ctrl:1
	s_andn2_b32 s28, 1, s31
	v_rcp_f32_e32 v33, v33
	v_add_f32_dpp v143, v143, v143 row_mirror row_mask:0xf bank_mask:0xf bound_ctrl:1
	v_mul_f32_e32 v131, v131, v135
	v_add_f32_e32 v135, -1.0, v130
	v_mov_b32_dpp v151, v143 row_bcast:15 row_mask:0xa bank_mask:0xf
	v_add_f32_e32 v143, v143, v151
	v_mov_b32_e32 v151, 0
	s_mulk_i32 s28, 0x7000
	v_fma_f32 v135, v106, v135, 1.0
	v_mov_b32_dpp v151, v143 row_bcast:31 row_mask:0xc bank_mask:0xf
	v_add_f32_e32 v143, v143, v151
	v_mul_f32_e32 v133, v133, v135
	v_add_u32_e32 v135, s28, v86
	v_readlane_b32 s28, v143, 63
	v_mul_f32_e32 v33, 0xbf1b4598, v33
	v_mul_f32_e32 v33, 0x3fb8aa3b, v33
	v_max_f32_e64 v143, s28, s28
	v_max_f32_e32 v143, 0x179abe15, v143
	v_rsq_f32_e32 v143, v143
	v_rcp_f32_e32 v138, v138
	v_mul_f32_e32 v137, 0x3fb8aa3b, v137
	v_exp_f32_e32 v33, v33
	v_exp_f32_e32 v137, v137
	v_mul_f32_e32 v139, v139, v143
; #define LAS __attribute__((address_space(3)))
; template <int MODE>
; __device__ __forceinline__ void scan_pair(LAS unsigned char* lds, CArgsP a, const ScanUnit u, int nch) {
;     ...
;     auto prep = [&](int c, int b) {
;         LAS float* cb = (LAS float*)(hl + b * SC_CHB);
; #pragma unroll
;         for (int tt = 0; tt < 4; ++tt) {
;             const int t = 4 * hw + tt, tl = 16 * c + t;
;             const float pr = bf2f(R.prk[tt] & 0xffffu), pk = bf2f(R.prk[tt] >> 16), pv = bf2f(R.pvq[tt] & 0xffffu);
;             float qr = bf2f(R.pvq[tt] >> 16), qk = bf2f(R.qkv[tt] & 0xffffu), qv = bf2f(R.qkv[tt] >> 16);
;             if (tl == 0) { qr = sh0[0]; qk = sh0[1]; qv = sh0[2]; }
;             const float xr = pr + (qr - pr) * mu_r, xk = pk + (qk - pk) * mu_k, xv = pv + (qv - pv) * mu_v;
;             const float wp = w0c + bf2f(R.lwa[tt] & 0xffffu);
;             const float w = __expf(-0.6065306597126334f * __builtin_amdgcn_rcpf(1.f + __expf(-wp)));
;             const float av = __builtin_amdgcn_rcpf(1.f + __expf(-(a0c + bf2f(R.lwa[tt] >> 16))));
;             float kk = xk * kkc;
;             const float n2 = wave_sum_fast(kk * kk);
;             kk = kk * rsqrtf(fmaxf(n2, 1e-24f));
;             const float kp = xk * (1.f + (av - 1.f) * kac);
;             cb[(0 * 16 + t) * 64 + lane] = w; cb[(1 * 16 + t) * 64 + lane] = kk; cb[(2 * 16 + t) * 64 + lane] = kk * av; cb[(3 * 16 + t) * 64 + lane] = kp;
;             cb[(4 * 16 + t) * 64 + lane] = xr; cb[(5 * 16 + t) * 64 + lane] = xv; cb[(6 * 16 + t) * 64 + lane] = bf2f(R.lg[tt]);
;         }
;     };
;     ...
;         if (ci + 1 < nch) prep(c + 1, b ^ 1);
;         __syncthreads();
	v_add_f32_e32 v143, -1.0, v138
	v_mul_f32_e32 v130, v130, v131
	v_fma_f32 v143, v106, v143, 1.0
	ds_write2st64_b32 v135, v33, v137 offset1:1
	ds_write2st64_b32 v135, v131, v139 offset0:16 offset1:17
	v_mul_f32_e32 v33, v138, v139
	v_lshlrev_b32_e32 v136, 16, v109
	v_mul_f32_e32 v141, v141, v143
	ds_write2st64_b32 v135, v130, v33 offset0:32 offset1:33
	ds_write2st64_b32 v135, v133, v141 offset0:48 offset1:49
	ds_write2st64_b32 v135, v134, v142 offset0:64 offset1:65
	ds_write2st64_b32 v135, v132, v140 offset0:80 offset1:81
	v_lshlrev_b32_e32 v33, 16, v110
	ds_write2st64_b32 v135, v136, v33 offset0:96 offset1:97
	v_lshlrev_b32_e32 v136, 16, v124
	v_add_f32_e32 v136, v107, v136
	v_mul_f32_e32 v136, 0xbfb8aa3b, v136
	v_and_b32_e32 v131, 0xffff0000, v123
	v_lshlrev_b32_e32 v134, 16, v121
	v_exp_f32_e32 v136, v136
	v_sub_f32_e32 v131, v131, v134
	v_lshlrev_b32_e32 v130, 16, v120
	v_and_b32_e32 v133, 0xffff0000, v121
	v_fmac_f32_e32 v134, v99, v131
	v_and_b32_e32 v131, 0xffff0000, v124
	v_sub_f32_e32 v130, v130, v133
	v_add_f32_e32 v131, v104, v131
	v_fmac_f32_e32 v133, v101, v130
	v_add_f32_e32 v130, 1.0, v136
	v_mul_f32_e32 v131, 0xbfb8aa3b, v131
	v_rcp_f32_e32 v130, v130
	v_exp_f32_e32 v131, v131
	v_and_b32_e32 v33, 0xffff0000, v120
	v_lshlrev_b32_e32 v132, 16, v123
	v_sub_f32_e32 v33, v33, v132
	v_fmac_f32_e32 v132, v108, v33
	v_mul_f32_e32 v33, 0xbf1b4598, v130
	v_add_f32_e32 v130, 1.0, v131
	v_mul_f32_e32 v131, v105, v133
	v_lshlrev_b32_e32 v143, 16, v128
	v_mul_f32_e32 v136, v131, v131
	v_add_f32_e32 v143, v107, v143
	v_mul_f32_e32 v143, 0xbfb8aa3b, v143
	v_mov_b32_dpp v136, v136 quad_perm:[1,0,3,2] row_mask:0xf bank_mask:0xf bound_ctrl:1
	v_fmac_f32_e32 v136, v131, v131
	v_and_b32_e32 v139, 0xffff0000, v127
	v_lshlrev_b32_e32 v142, 16, v126
	v_exp_f32_e32 v143, v143
	v_add_f32_dpp v136, v136, v136 quad_perm:[2,3,0,1] row_mask:0xf bank_mask:0xf bound_ctrl:1
	v_sub_f32_e32 v139, v139, v142
	v_lshlrev_b32_e32 v138, 16, v125
	v_add_f32_dpp v136, v136, v136 row_half_mirror row_mask:0xf bank_mask:0xf bound_ctrl:1
	v_and_b32_e32 v141, 0xffff0000, v126
	v_fmac_f32_e32 v142, v99, v139
	v_and_b32_e32 v139, 0xffff0000, v128
	v_add_f32_dpp v136, v136, v136 row_mirror row_mask:0xf bank_mask:0xf bound_ctrl:1
	v_mov_b32_e32 v137, 0
	v_sub_f32_e32 v138, v138, v141
	v_add_f32_e32 v139, v104, v139
	v_mov_b32_dpp v137, v136 row_bcast:15 row_mask:0xa bank_mask:0xf
	v_fmac_f32_e32 v141, v101, v138
	v_add_f32_e32 v138, 1.0, v143
	v_mul_f32_e32 v139, 0xbfb8aa3b, v139
	v_add_f32_e32 v136, v136, v137
	v_mov_b32_e32 v137, 0
	v_rcp_f32_e32 v138, v138
	v_exp_f32_e32 v139, v139
	v_mov_b32_dpp v137, v136 row_bcast:31 row_mask:0xc bank_mask:0xf
	v_add_f32_e32 v136, v136, v137
	v_and_b32_e32 v137, 0xffff0000, v125
	v_lshlrev_b32_e32 v140, 16, v127
	v_sub_f32_e32 v137, v137, v140
	v_fmac_f32_e32 v140, v108, v137
	v_mul_f32_e32 v137, 0xbf1b4598, v138
	v_add_f32_e32 v138, 1.0, v139
	v_mul_f32_e32 v139, v105, v141
	v_mul_f32_e32 v143, v139, v139
	v_mov_b32_e32 v151, 0
	v_readlane_b32 s28, v136, 63
	v_mov_b32_dpp v143, v143 quad_perm:[1,0,3,2] row_mask:0xf bank_mask:0xf bound_ctrl:1
	v_fmac_f32_e32 v143, v139, v139
	v_max_f32_e64 v136, s28, s28
	v_max_f32_e32 v136, 0x179abe15, v136
	v_add_f32_dpp v143, v143, v143 quad_perm:[2,3,0,1] row_mask:0xf bank_mask:0xf bound_ctrl:1
	v_rsq_f32_e32 v136, v136
	v_rcp_f32_e32 v130, v130
	v_add_f32_dpp v143, v143, v143 row_half_mirror row_mask:0xf bank_mask:0xf bound_ctrl:1
	v_mul_f32_e32 v33, 0x3fb8aa3b, v33
	v_rcp_f32_e32 v138, v138
	v_add_f32_dpp v143, v143, v143 row_mirror row_mask:0xf bank_mask:0xf bound_ctrl:1
	v_mul_f32_e32 v137, 0x3fb8aa3b, v137
	v_exp_f32_e32 v33, v33
	v_mov_b32_dpp v151, v143 row_bcast:15 row_mask:0xa bank_mask:0xf
	v_add_f32_e32 v143, v143, v151
	v_mov_b32_e32 v151, 0
	v_exp_f32_e32 v137, v137
	v_mul_f32_e32 v131, v131, v136
	v_mov_b32_dpp v151, v143 row_bcast:31 row_mask:0xc bank_mask:0xf
	v_add_f32_e32 v143, v143, v151
	v_add_f32_e32 v136, -1.0, v130
	v_readlane_b32 s28, v143, 63
	v_fma_f32 v136, v106, v136, 1.0
	v_mul_f32_e32 v130, v130, v131
	v_max_f32_e64 v143, s28, s28
	v_max_f32_e32 v143, 0x179abe15, v143
	v_rsq_f32_e32 v143, v143
	v_mul_f32_e32 v133, v133, v136
	v_lshlrev_b32_e32 v136, 16, v111
	v_mul_f32_e32 v139, v139, v143
	v_add_f32_e32 v143, -1.0, v138
	v_fma_f32 v143, v106, v143, 1.0
	ds_write2st64_b32 v135, v33, v137 offset0:2 offset1:3
	ds_write2st64_b32 v135, v131, v139 offset0:18 offset1:19
	v_mul_f32_e32 v33, v138, v139
	v_mul_f32_e32 v141, v141, v143
	ds_write2st64_b32 v135, v130, v33 offset0:34 offset1:35
	ds_write2st64_b32 v135, v133, v141 offset0:50 offset1:51
	ds_write2st64_b32 v135, v134, v142 offset0:66 offset1:67
	ds_write2st64_b32 v135, v132, v140 offset0:82 offset1:83
	s_waitcnt vmcnt(0)
	v_lshlrev_b32_e32 v33, 16, v122
	ds_write2st64_b32 v135, v136, v33 offset0:98 offset1:99
	s_branch .LBB0_818

; __global__ void __launch_bounds__(512, 2) mega_fwd(Args a_unused) {
	.amdhsa_kernel _Z8mega_fwd4Args
		.amdhsa_group_segment_fixed_size 0
		.amdhsa_private_segment_fixed_size 0
		.amdhsa_kernarg_size 512
		.amdhsa_user_sgpr_count 2
		.amdhsa_user_sgpr_dispatch_ptr 0
		.amdhsa_user_sgpr_queue_ptr 0
		.amdhsa_user_sgpr_kernarg_segment_ptr 1
		.amdhsa_user_sgpr_dispatch_id 0
		.amdhsa_user_sgpr_kernarg_preload_length 0
		.amdhsa_user_sgpr_kernarg_preload_offset 0
		.amdhsa_user_sgpr_private_segment_size 0
		.amdhsa_uses_dynamic_stack 0
		.amdhsa_enable_private_segment 0
		.amdhsa_system_sgpr_workgroup_id_x 1
		.amdhsa_system_sgpr_workgroup_id_y 0
		.amdhsa_system_sgpr_workgroup_id_z 0
		.amdhsa_system_sgpr_workgroup_info 0
		.amdhsa_system_vgpr_workitem_id 2
		.amdhsa_next_free_vgpr 256
		.amdhsa_next_free_sgpr 98
		.amdhsa_accum_offset 256
		.amdhsa_reserve_vcc 1
		.amdhsa_float_round_mode_32 0
		.amdhsa_float_round_mode_16_64 0
		.amdhsa_float_denorm_mode_32 3
		.amdhsa_float_denorm_mode_16_64 3
		.amdhsa_dx10_clamp 1
		.amdhsa_ieee_mode 1
		.amdhsa_fp16_overflow 0
		.amdhsa_tg_split 0
		.amdhsa_exception_fp_ieee_invalid_op 0
		.amdhsa_exception_fp_denorm_src 0
		.amdhsa_exception_fp_ieee_div_zero 0
		.amdhsa_exception_fp_ieee_overflow 0
		.amdhsa_exception_fp_ieee_underflow 0
		.amdhsa_exception_fp_ieee_inexact 0
		.amdhsa_exception_int_div_zero 0
	.end_amdhsa_kernel

; __global__ void __launch_bounds__(512, 2) mega_fwd(Args a_unused) {
amdhsa.kernels:
  - .agpr_count:     0
    .args:
      - .offset:         0
        .size:           256
        .value_kind:     by_value
      - .offset:         256
        .size:           4
        .value_kind:     hidden_block_count_x
      - .offset:         260
        .size:           4
        .value_kind:     hidden_block_count_y
      - .offset:         264
        .size:           4
        .value_kind:     hidden_block_count_z
      - .offset:         268
        .size:           2
        .value_kind:     hidden_group_size_x
      - .offset:         270
        .size:           2
        .value_kind:     hidden_group_size_y
      - .offset:         272
        .size:           2
        .value_kind:     hidden_group_size_z
      - .offset:         274
        .size:           2
        .value_kind:     hidden_remainder_x
      - .offset:         276
        .size:           2
        .value_kind:     hidden_remainder_y
      - .offset:         278
        .size:           2
        .value_kind:     hidden_remainder_z
      - .offset:         296
        .size:           8
        .value_kind:     hidden_global_offset_x
      - .offset:         304
        .size:           8
        .value_kind:     hidden_global_offset_y
      - .offset:         312
        .size:           8
        .value_kind:     hidden_global_offset_z
      - .offset:         320
        .size:           2
        .value_kind:     hidden_grid_dims
      - .offset:         344
        .size:           8
        .value_kind:     hidden_multigrid_sync_arg
      - .offset:         376
        .size:           4
        .value_kind:     hidden_dynamic_lds_size
    .group_segment_fixed_size: 0
    .kernarg_segment_align: 8
    .kernarg_segment_size: 512
    .language:       OpenCL C
    .language_version:
      - 2
      - 0
    .max_flat_workgroup_size: 512
    .name:           _Z8mega_fwd4Args
    .private_segment_fixed_size: 0
    .sgpr_count:     104
    .sgpr_spill_count: 31
    .symbol:         _Z8mega_fwd4Args.kd
    .uniform_work_group_size: 1
    .uses_dynamic_stack: false
    .vgpr_count:     256
    .vgpr_spill_count: 0
    .wavefront_size: 64
